# diff-attn: skip cross-lane max reduction when no lane exceeds running max; GEMM epilogue stores write-through (sc1)
# baseline (speedup 1.0000x reference)
; __device__ __forceinline__ unsigned pk2(float lo, float hi) { f32x2 v = {lo, hi}; bf16x2_t b = __builtin_convertvector(v, bf16x2_t); return __builtin_bit_cast(unsigned, b); }
; __device__ __forceinline__ float bflo(unsigned w) { return __uint_as_float(w << 16); }
; __device__ __forceinline__ float bfhi(unsigned w) { return __uint_as_float(w & 0xffff0000u); }
;     __device__ __forceinline__ void operator()(const f32x4 (&acc)[2][2][4][2], const Unit& u, int wr, int wc, int fr, int fq) const {
;         const int row0 = u.pm * BM + wr * 64 + fr, col0 = u.pn * BM + wc * 32 + 8 * fq;
;         const float* const Rf = this->Rf; bf16_t* const X = this->X; const float scale = this->half_ ? 0.5f : 1.0f; unsigned* const RS = this->RS;
;         f32x4 rv[2][2], rn[2][2];
;         float ssv[8];
;     ...
;         EPIRES_LOAD(rv, (size_t)row0 * 1024 + col0);
; #pragma unroll
;         for (int b = 0; b < 8; ++b) {
;             const int ai = b >> 2, m = b & 3;
;             const size_t off = (size_t)(row0 + ai * HALF + m * 16) * 1024 + col0;
;             if (b < 7) EPIRES_LOAD(rn, (size_t)(row0 + ((b + 1) >> 2) * HALF + ((b + 1) & 3) * 16) * 1024 + col0);
;             float ss = 0.f;
; #pragma unroll
;             for (int bj = 0; bj < 2; ++bj) {
;                 const f32x4 o0 = rv[bj][0] + acc[ai][bj][m][0] * scale, o1 = rv[bj][1] + acc[ai][bj][m][1] * scale;
;                 u32x4 w; w.x = ::pk2(o0[0], o0[1]); w.y = ::pk2(o0[2], o0[3]); w.z = ::pk2(o1[0], o1[1]); w.w = ::pk2(o1[2], o1[3]);
;                 *(u32x4*)(X + off + bj * HALF) = w;
;                 const float q0 = ::bflo(w.x), q1 = ::bfhi(w.x), q2 = ::bflo(w.y), q3 = ::bfhi(w.y), q4 = ::bflo(w.z), q5 = ::bfhi(w.z), q6 = ::bflo(w.w), q7 = ::bfhi(w.w);
;                 ss += ((q0 * q0 + q1 * q1) + (q2 * q2 + q3 * q3)) + ((q4 * q4 + q5 * q5) + (q6 * q6 + q7 * q7));
.LBB0_52:
	v_lshl_add_u32 v146, s14, 8, v3
	v_lshl_or_b32 v148, s15, 8, v189
	v_ashrrev_i32_e32 v147, 31, v146
	v_ashrrev_i32_e32 v149, 31, v148
	v_lshlrev_b64 v[152:153], 11, v[146:147]
	v_lshl_add_u64 v[154:155], s[38:39], 0, v[152:153]
	v_lshlrev_b64 v[150:151], 1, v[148:149]
	v_lshl_add_u64 v[148:149], v[154:155], 0, v[150:151]
	global_load_dwordx4 v[154:157], v[148:149], off
	s_mov_b64 s[14:15], 0x40000
	s_waitcnt vmcnt(0)
	v_lshlrev_b32_e32 v192, 16, v154
	v_and_b32_e32 v193, 0xffff0000, v154
	v_lshlrev_b32_e32 v194, 16, v155
	v_and_b32_e32 v195, 0xffff0000, v155
	v_lshlrev_b32_e32 v196, 16, v156
	v_and_b32_e32 v197, 0xffff0000, v156
	v_lshlrev_b32_e32 v198, 16, v157
	v_and_b32_e32 v199, 0xffff0000, v157
	global_load_dwordx4 v[154:157], v[148:149], off offset:256
	v_lshl_add_u64 v[148:149], s[38:39], 0, v[150:151]
	v_pk_fma_f32 v[130:131], v[130:131], 0.5, v[194:195] op_sel_hi:[1,0,1]
	v_pk_fma_f32 v[128:129], v[128:129], 0.5, v[192:193] op_sel_hi:[1,0,1]
	v_pk_fma_f32 v[192:193], v[126:127], 0.5, v[198:199] op_sel_hi:[1,0,1]
	v_pk_fma_f32 v[126:127], v[124:125], 0.5, v[196:197] op_sel_hi:[1,0,1]
	v_lshl_add_u64 v[206:207], v[148:149], 0, v[152:153]
	v_cvt_pk_bf16_f32 v124, v128, v129
	v_cvt_pk_bf16_f32 v125, v130, v131
	v_cvt_pk_bf16_f32 v126, v126, v127
	v_cvt_pk_bf16_f32 v127, v192, v193
	global_store_dwordx4 v[206:207], v[124:127], off sc1
	v_lshlrev_b32_e32 v128, 16, v124
	v_lshlrev_b32_e32 v129, 16, v125
	v_and_b32_e32 v124, 0xffff0000, v124
	v_and_b32_e32 v125, 0xffff0000, v125
	v_lshlrev_b32_e32 v130, 16, v126
	v_and_b32_e32 v126, 0xffff0000, v126
	v_lshlrev_b32_e32 v131, 16, v127
	v_and_b32_e32 v127, 0xffff0000, v127
	v_mul_f32_e32 v140, v124, v124
	v_mul_f32_e32 v141, v125, v125
	v_mul_f32_e32 v124, v126, v126
	v_mul_f32_e32 v125, v127, v127
	v_fmac_f32_e32 v124, v130, v130
	v_fmac_f32_e32 v125, v131, v131
	v_add_f32_e32 v126, v124, v125
	v_fmac_f32_e32 v141, v129, v129
	v_fmac_f32_e32 v140, v128, v128
	s_waitcnt vmcnt(1)
	v_lshlrev_b32_e32 v202, 16, v156
	v_and_b32_e32 v203, 0xffff0000, v156
	v_or_b32_e32 v156, 16, v146
	v_lshlrev_b32_e32 v204, 16, v157
	v_and_b32_e32 v205, 0xffff0000, v157
	v_ashrrev_i32_e32 v157, 31, v156
	v_lshlrev_b64 v[156:157], 11, v[156:157]
	v_lshl_add_u64 v[158:159], s[38:39], 0, v[156:157]
	v_lshl_add_u64 v[166:167], v[158:159], 0, v[150:151]
	global_load_dwordx4 v[162:165], v[166:167], off
	global_load_dwordx4 v[170:173], v[166:167], off offset:256
	v_lshlrev_b32_e32 v200, 16, v154
	v_and_b32_e32 v201, 0xffff0000, v154
	v_lshlrev_b32_e32 v154, 16, v155
	v_and_b32_e32 v155, 0xffff0000, v155
	v_pk_fma_f32 v[122:123], v[122:123], 0.5, v[154:155] op_sel_hi:[1,0,1]
	v_pk_fma_f32 v[120:121], v[120:121], 0.5, v[200:201] op_sel_hi:[1,0,1]
	v_pk_fma_f32 v[124:125], v[118:119], 0.5, v[204:205] op_sel_hi:[1,0,1]
	v_pk_fma_f32 v[118:119], v[116:117], 0.5, v[202:203] op_sel_hi:[1,0,1]
	v_cvt_pk_bf16_f32 v116, v120, v121
	v_cvt_pk_bf16_f32 v117, v122, v123
	v_cvt_pk_bf16_f32 v118, v118, v119
	v_cvt_pk_bf16_f32 v119, v124, v125
	global_store_dwordx4 v[206:207], v[116:119], off offset:256 sc1
	v_lshlrev_b32_e32 v120, 16, v116
	v_lshlrev_b32_e32 v121, 16, v117
	v_and_b32_e32 v116, 0xffff0000, v116
	v_and_b32_e32 v117, 0xffff0000, v117
	v_mul_f32_e32 v116, v116, v116
	v_mul_f32_e32 v117, v117, v117
	v_lshlrev_b32_e32 v122, 16, v118
	v_and_b32_e32 v118, 0xffff0000, v118
	v_lshlrev_b32_e32 v123, 16, v119
	v_and_b32_e32 v119, 0xffff0000, v119
	v_fmac_f32_e32 v116, v120, v120
	v_fmac_f32_e32 v117, v121, v121
	v_add_f32_e32 v116, v116, v117
	v_mul_f32_e32 v117, v118, v118
	v_mul_f32_e32 v118, v119, v119
	v_fmac_f32_e32 v117, v122, v122
	v_fmac_f32_e32 v118, v123, v123
	v_add_f32_e32 v117, v117, v118
	v_add_f32_e32 v116, v117, v116
	v_add_f32_e32 v117, v140, v141
	v_add_f32_e32 v117, v126, v117
	v_add_f32_e32 v191, v117, v116
	v_or_b32_e32 v116, 32, v146
	v_ashrrev_i32_e32 v117, 31, v116
	v_lshlrev_b64 v[116:117], 11, v[116:117]
	v_lshl_add_u64 v[118:119], s[38:39], 0, v[116:117]
	v_lshl_add_u64 v[156:157], v[148:149], 0, v[156:157]
	v_lshl_add_u64 v[126:127], v[118:119], 0, v[150:151]
	global_load_dwordx4 v[122:125], v[126:127], off
	global_load_dwordx4 v[192:195], v[126:127], off offset:256
	v_lshl_add_u64 v[116:117], v[148:149], 0, v[116:117]
	s_waitcnt vmcnt(4)
	v_lshlrev_b32_e32 v158, 16, v162
	v_and_b32_e32 v159, 0xffff0000, v162
	v_lshlrev_b32_e32 v162, 16, v163
	v_and_b32_e32 v163, 0xffff0000, v163
	v_lshlrev_b32_e32 v160, 16, v164
	v_and_b32_e32 v161, 0xffff0000, v164
	v_lshlrev_b32_e32 v164, 16, v165
	v_and_b32_e32 v165, 0xffff0000, v165
	v_pk_fma_f32 v[114:115], v[114:115], 0.5, v[162:163] op_sel_hi:[1,0,1]
	v_pk_fma_f32 v[112:113], v[112:113], 0.5, v[158:159] op_sel_hi:[1,0,1]
	v_pk_fma_f32 v[158:159], v[110:111], 0.5, v[164:165] op_sel_hi:[1,0,1]
	v_pk_fma_f32 v[110:111], v[108:109], 0.5, v[160:161] op_sel_hi:[1,0,1]
	v_cvt_pk_bf16_f32 v108, v112, v113
	v_cvt_pk_bf16_f32 v109, v114, v115
	v_cvt_pk_bf16_f32 v110, v110, v111
	v_cvt_pk_bf16_f32 v111, v158, v159
	global_store_dwordx4 v[156:157], v[108:111], off sc1
	v_lshlrev_b32_e32 v112, 16, v108
	v_lshlrev_b32_e32 v113, 16, v109
	v_and_b32_e32 v108, 0xffff0000, v108
	v_and_b32_e32 v109, 0xffff0000, v109
	v_lshlrev_b32_e32 v114, 16, v110
	v_and_b32_e32 v110, 0xffff0000, v110
	v_lshlrev_b32_e32 v115, 16, v111
	v_and_b32_e32 v111, 0xffff0000, v111
	v_mul_f32_e32 v140, v108, v108
	v_mul_f32_e32 v141, v109, v109
	v_mul_f32_e32 v108, v110, v110
	v_mul_f32_e32 v109, v111, v111
	s_waitcnt vmcnt(4)
; __device__ __forceinline__ unsigned pk2(float lo, float hi) { f32x2 v = {lo, hi}; bf16x2_t b = __builtin_convertvector(v, bf16x2_t); return __builtin_bit_cast(unsigned, b); }
; __device__ __forceinline__ float bflo(unsigned w) { return __uint_as_float(w << 16); }
; __device__ __forceinline__ float bfhi(unsigned w) { return __uint_as_float(w & 0xffff0000u); }
;     __device__ __forceinline__ void operator()(const f32x4 (&acc)[2][2][4][2], const Unit& u, int wr, int wc, int fr, int fq) const {
;     ...
;         for (int b = 0; b < 8; ++b) {
;             const int ai = b >> 2, m = b & 3;
;             const size_t off = (size_t)(row0 + ai * HALF + m * 16) * 1024 + col0;
;             if (b < 7) EPIRES_LOAD(rn, (size_t)(row0 + ((b + 1) >> 2) * HALF + ((b + 1) & 3) * 16) * 1024 + col0);
;             float ss = 0.f;
; #pragma unroll
;             for (int bj = 0; bj < 2; ++bj) {
;                 const f32x4 o0 = rv[bj][0] + acc[ai][bj][m][0] * scale, o1 = rv[bj][1] + acc[ai][bj][m][1] * scale;
;                 u32x4 w; w.x = ::pk2(o0[0], o0[1]); w.y = ::pk2(o0[2], o0[3]); w.z = ::pk2(o1[0], o1[1]); w.w = ::pk2(o1[2], o1[3]);
;                 *(u32x4*)(X + off + bj * HALF) = w;
;                 const float q0 = ::bflo(w.x), q1 = ::bfhi(w.x), q2 = ::bflo(w.y), q3 = ::bfhi(w.y), q4 = ::bflo(w.z), q5 = ::bfhi(w.z), q6 = ::bflo(w.w), q7 = ::bfhi(w.w);
;                 ss += ((q0 * q0 + q1 * q1) + (q2 * q2 + q3 * q3)) + ((q4 * q4 + q5 * q5) + (q6 * q6 + q7 * q7));
;             }
;             ssv[b] = ss;
	v_lshlrev_b32_e32 v166, 16, v170
	v_and_b32_e32 v167, 0xffff0000, v170
	v_lshlrev_b32_e32 v170, 16, v171
	v_and_b32_e32 v171, 0xffff0000, v171
	v_lshlrev_b32_e32 v168, 16, v172
	v_and_b32_e32 v169, 0xffff0000, v172
	v_lshlrev_b32_e32 v172, 16, v173
	v_and_b32_e32 v173, 0xffff0000, v173
	v_fmac_f32_e32 v108, v114, v114
	v_fmac_f32_e32 v109, v115, v115
	v_add_f32_e32 v110, v108, v109
	v_pk_fma_f32 v[106:107], v[106:107], 0.5, v[170:171] op_sel_hi:[1,0,1]
	v_pk_fma_f32 v[104:105], v[104:105], 0.5, v[166:167] op_sel_hi:[1,0,1]
	v_pk_fma_f32 v[108:109], v[102:103], 0.5, v[172:173] op_sel_hi:[1,0,1]
	v_pk_fma_f32 v[102:103], v[100:101], 0.5, v[168:169] op_sel_hi:[1,0,1]
	v_cvt_pk_bf16_f32 v100, v104, v105
	v_cvt_pk_bf16_f32 v101, v106, v107
	v_cvt_pk_bf16_f32 v102, v102, v103
	v_cvt_pk_bf16_f32 v103, v108, v109
	global_store_dwordx4 v[156:157], v[100:103], off offset:256 sc1
	v_lshlrev_b32_e32 v104, 16, v100
	v_lshlrev_b32_e32 v105, 16, v101
	v_and_b32_e32 v100, 0xffff0000, v100
	v_and_b32_e32 v101, 0xffff0000, v101
	v_mul_f32_e32 v100, v100, v100
	v_mul_f32_e32 v101, v101, v101
	v_lshlrev_b32_e32 v106, 16, v102
	v_and_b32_e32 v102, 0xffff0000, v102
	v_lshlrev_b32_e32 v107, 16, v103
	v_and_b32_e32 v103, 0xffff0000, v103
	v_fmac_f32_e32 v100, v104, v104
	v_fmac_f32_e32 v101, v105, v105
	v_add_f32_e32 v100, v100, v101
	v_mul_f32_e32 v101, v102, v102
	v_mul_f32_e32 v102, v103, v103
	v_fmac_f32_e32 v101, v106, v106
	v_fmac_f32_e32 v102, v107, v107
	v_fmac_f32_e32 v141, v113, v113
	v_add_f32_e32 v101, v101, v102
	v_fmac_f32_e32 v140, v112, v112
	v_add_f32_e32 v100, v101, v100
	v_add_f32_e32 v101, v140, v141
	v_add_f32_e32 v101, v110, v101
	v_add_f32_e32 v158, v101, v100
	v_or_b32_e32 v100, 48, v146
	v_ashrrev_i32_e32 v101, 31, v100
	v_lshlrev_b64 v[100:101], 11, v[100:101]
	v_lshl_add_u64 v[102:103], s[38:39], 0, v[100:101]
	v_lshl_add_u64 v[110:111], v[102:103], 0, v[150:151]
	global_load_dwordx4 v[106:109], v[110:111], off
	global_load_dwordx4 v[160:163], v[110:111], off offset:256
	s_waitcnt vmcnt(5)
	v_lshlrev_b32_e32 v118, 16, v122
	v_and_b32_e32 v119, 0xffff0000, v122
	v_lshlrev_b32_e32 v122, 16, v123
	v_and_b32_e32 v123, 0xffff0000, v123
	v_lshlrev_b32_e32 v120, 16, v124
	v_and_b32_e32 v121, 0xffff0000, v124
	v_lshlrev_b32_e32 v124, 16, v125
	v_and_b32_e32 v125, 0xffff0000, v125
	v_pk_fma_f32 v[98:99], v[98:99], 0.5, v[122:123] op_sel_hi:[1,0,1]
	v_pk_fma_f32 v[96:97], v[96:97], 0.5, v[118:119] op_sel_hi:[1,0,1]
	v_pk_fma_f32 v[118:119], v[94:95], 0.5, v[124:125] op_sel_hi:[1,0,1]
	v_pk_fma_f32 v[94:95], v[92:93], 0.5, v[120:121] op_sel_hi:[1,0,1]
	v_cvt_pk_bf16_f32 v92, v96, v97
	v_cvt_pk_bf16_f32 v93, v98, v99
	v_cvt_pk_bf16_f32 v94, v94, v95
	v_cvt_pk_bf16_f32 v95, v118, v119
	global_store_dwordx4 v[116:117], v[92:95], off sc1
	v_lshlrev_b32_e32 v96, 16, v92
	v_lshlrev_b32_e32 v97, 16, v93
	v_and_b32_e32 v92, 0xffff0000, v92
	v_and_b32_e32 v93, 0xffff0000, v93
	v_lshlrev_b32_e32 v98, 16, v94
	v_and_b32_e32 v94, 0xffff0000, v94
	v_lshlrev_b32_e32 v99, 16, v95
	v_and_b32_e32 v95, 0xffff0000, v95
	v_mul_f32_e32 v118, v92, v92
	v_mul_f32_e32 v119, v93, v93
	v_mul_f32_e32 v92, v94, v94
	v_mul_f32_e32 v93, v95, v95
	s_waitcnt vmcnt(5)
	v_lshlrev_b32_e32 v126, 16, v192
	v_and_b32_e32 v127, 0xffff0000, v192
	v_lshlrev_b32_e32 v130, 16, v193
	v_and_b32_e32 v131, 0xffff0000, v193
	v_lshlrev_b32_e32 v128, 16, v194
	v_and_b32_e32 v129, 0xffff0000, v194
	v_lshlrev_b32_e32 v154, 16, v195
	v_and_b32_e32 v155, 0xffff0000, v195
	v_fmac_f32_e32 v92, v98, v98
	v_fmac_f32_e32 v93, v99, v99
	v_add_f32_e32 v94, v92, v93
	v_pk_fma_f32 v[90:91], v[90:91], 0.5, v[130:131] op_sel_hi:[1,0,1]
	v_pk_fma_f32 v[88:89], v[88:89], 0.5, v[126:127] op_sel_hi:[1,0,1]
	v_pk_fma_f32 v[92:93], v[86:87], 0.5, v[154:155] op_sel_hi:[1,0,1]
	v_pk_fma_f32 v[86:87], v[84:85], 0.5, v[128:129] op_sel_hi:[1,0,1]
	v_cvt_pk_bf16_f32 v84, v88, v89
	v_cvt_pk_bf16_f32 v85, v90, v91
	v_cvt_pk_bf16_f32 v86, v86, v87
	v_cvt_pk_bf16_f32 v87, v92, v93
	global_store_dwordx4 v[116:117], v[84:87], off offset:256 sc1
	v_lshlrev_b32_e32 v88, 16, v84
	v_lshlrev_b32_e32 v89, 16, v85
	v_and_b32_e32 v84, 0xffff0000, v84
	v_and_b32_e32 v85, 0xffff0000, v85
	v_mul_f32_e32 v84, v84, v84
	v_mul_f32_e32 v85, v85, v85
	v_lshlrev_b32_e32 v90, 16, v86
	v_and_b32_e32 v86, 0xffff0000, v86
	v_lshlrev_b32_e32 v91, 16, v87
	v_and_b32_e32 v87, 0xffff0000, v87
	v_fmac_f32_e32 v84, v88, v88
	v_fmac_f32_e32 v85, v89, v89
	v_add_f32_e32 v84, v84, v85
	v_mul_f32_e32 v85, v86, v86
	v_mul_f32_e32 v86, v87, v87
	v_fmac_f32_e32 v85, v90, v90
	v_fmac_f32_e32 v86, v91, v91
	v_fmac_f32_e32 v119, v97, v97
	v_add_f32_e32 v85, v85, v86
	v_fmac_f32_e32 v118, v96, v96
	v_add_f32_e32 v84, v85, v84
	v_add_f32_e32 v85, v118, v119
	v_add_f32_e32 v85, v94, v85
	v_add_f32_e32 v122, v85, v84
	v_lshl_add_u64 v[84:85], v[152:153], 0, s[14:15]
	v_lshl_add_u64 v[86:87], s[38:39], 0, v[84:85]
	v_lshl_add_u64 v[94:95], v[86:87], 0, v[150:151]
	global_load_dwordx4 v[90:93], v[94:95], off
	global_load_dwordx4 v[118:121], v[94:95], off offset:256
	s_waitcnt vmcnt(5)
; __device__ __forceinline__ unsigned pk2(float lo, float hi) { f32x2 v = {lo, hi}; bf16x2_t b = __builtin_convertvector(v, bf16x2_t); return __builtin_bit_cast(unsigned, b); }
; __device__ __forceinline__ float bflo(unsigned w) { return __uint_as_float(w << 16); }
; __device__ __forceinline__ float bfhi(unsigned w) { return __uint_as_float(w & 0xffff0000u); }
;     __device__ __forceinline__ void operator()(const f32x4 (&acc)[2][2][4][2], const Unit& u, int wr, int wc, int fr, int fq) const {
;     ...
;         for (int b = 0; b < 8; ++b) {
;             const int ai = b >> 2, m = b & 3;
;             const size_t off = (size_t)(row0 + ai * HALF + m * 16) * 1024 + col0;
;             if (b < 7) EPIRES_LOAD(rn, (size_t)(row0 + ((b + 1) >> 2) * HALF + ((b + 1) & 3) * 16) * 1024 + col0);
;             float ss = 0.f;
; #pragma unroll
;             for (int bj = 0; bj < 2; ++bj) {
;                 const f32x4 o0 = rv[bj][0] + acc[ai][bj][m][0] * scale, o1 = rv[bj][1] + acc[ai][bj][m][1] * scale;
;                 u32x4 w; w.x = ::pk2(o0[0], o0[1]); w.y = ::pk2(o0[2], o0[3]); w.z = ::pk2(o1[0], o1[1]); w.w = ::pk2(o1[2], o1[3]);
;                 *(u32x4*)(X + off + bj * HALF) = w;
;                 const float q0 = ::bflo(w.x), q1 = ::bfhi(w.x), q2 = ::bflo(w.y), q3 = ::bfhi(w.y), q4 = ::bflo(w.z), q5 = ::bfhi(w.z), q6 = ::bflo(w.w), q7 = ::bfhi(w.w);
;                 ss += ((q0 * q0 + q1 * q1) + (q2 * q2 + q3 * q3)) + ((q4 * q4 + q5 * q5) + (q6 * q6 + q7 * q7));
;             }
;             ssv[b] = ss;
	v_lshlrev_b32_e32 v102, 16, v106
	v_and_b32_e32 v103, 0xffff0000, v106
	v_lshlrev_b32_e32 v106, 16, v107
	v_and_b32_e32 v107, 0xffff0000, v107
	v_lshlrev_b32_e32 v104, 16, v108
	v_and_b32_e32 v105, 0xffff0000, v108
	v_lshlrev_b32_e32 v108, 16, v109
	v_and_b32_e32 v109, 0xffff0000, v109
	v_pk_fma_f32 v[82:83], v[82:83], 0.5, v[106:107] op_sel_hi:[1,0,1]
	v_pk_fma_f32 v[80:81], v[80:81], 0.5, v[102:103] op_sel_hi:[1,0,1]
	v_pk_fma_f32 v[98:99], v[78:79], 0.5, v[108:109] op_sel_hi:[1,0,1]
	v_pk_fma_f32 v[78:79], v[76:77], 0.5, v[104:105] op_sel_hi:[1,0,1]
	v_lshl_add_u64 v[94:95], v[148:149], 0, v[100:101]
	v_cvt_pk_bf16_f32 v76, v80, v81
	v_cvt_pk_bf16_f32 v77, v82, v83
	v_cvt_pk_bf16_f32 v78, v78, v79
	v_cvt_pk_bf16_f32 v79, v98, v99
	global_store_dwordx4 v[94:95], v[76:79], off sc1
	v_lshlrev_b32_e32 v80, 16, v76
	v_lshlrev_b32_e32 v81, 16, v77
	v_and_b32_e32 v76, 0xffff0000, v76
	v_and_b32_e32 v77, 0xffff0000, v77
	v_lshlrev_b32_e32 v82, 16, v78
	v_and_b32_e32 v78, 0xffff0000, v78
	v_lshlrev_b32_e32 v83, 16, v79
	v_and_b32_e32 v79, 0xffff0000, v79
	v_mul_f32_e32 v98, v76, v76
	v_mul_f32_e32 v99, v77, v77
	v_mul_f32_e32 v76, v78, v78
	v_mul_f32_e32 v77, v79, v79
	s_waitcnt vmcnt(5)
	v_lshlrev_b32_e32 v110, 16, v160
	v_and_b32_e32 v111, 0xffff0000, v160
	v_lshlrev_b32_e32 v114, 16, v161
	v_and_b32_e32 v115, 0xffff0000, v161
	v_lshlrev_b32_e32 v112, 16, v162
	v_and_b32_e32 v113, 0xffff0000, v162
	v_lshlrev_b32_e32 v156, 16, v163
	v_and_b32_e32 v157, 0xffff0000, v163
	v_fmac_f32_e32 v76, v82, v82
	v_fmac_f32_e32 v77, v83, v83
	v_add_f32_e32 v78, v76, v77
	v_pk_fma_f32 v[74:75], v[74:75], 0.5, v[114:115] op_sel_hi:[1,0,1]
	v_pk_fma_f32 v[72:73], v[72:73], 0.5, v[110:111] op_sel_hi:[1,0,1]
	v_pk_fma_f32 v[76:77], v[70:71], 0.5, v[156:157] op_sel_hi:[1,0,1]
	v_pk_fma_f32 v[70:71], v[68:69], 0.5, v[112:113] op_sel_hi:[1,0,1]
	v_cvt_pk_bf16_f32 v68, v72, v73
	v_cvt_pk_bf16_f32 v69, v74, v75
	v_cvt_pk_bf16_f32 v70, v70, v71
	v_cvt_pk_bf16_f32 v71, v76, v77
	global_store_dwordx4 v[94:95], v[68:71], off offset:256 sc1
	v_lshlrev_b32_e32 v72, 16, v68
	v_lshlrev_b32_e32 v73, 16, v69
	v_and_b32_e32 v68, 0xffff0000, v68
	v_and_b32_e32 v69, 0xffff0000, v69
	v_mul_f32_e32 v68, v68, v68
	v_mul_f32_e32 v69, v69, v69
	v_lshlrev_b32_e32 v74, 16, v70
	v_and_b32_e32 v70, 0xffff0000, v70
	v_lshlrev_b32_e32 v75, 16, v71
	v_and_b32_e32 v71, 0xffff0000, v71
	v_fmac_f32_e32 v68, v72, v72
	v_fmac_f32_e32 v69, v73, v73
	v_add_f32_e32 v68, v68, v69
	v_mul_f32_e32 v69, v70, v70
	v_mul_f32_e32 v70, v71, v71
	v_fmac_f32_e32 v69, v74, v74
	v_fmac_f32_e32 v70, v75, v75
	v_fmac_f32_e32 v99, v81, v81
	v_add_f32_e32 v69, v69, v70
	v_fmac_f32_e32 v98, v80, v80
	v_add_f32_e32 v68, v69, v68
	v_add_f32_e32 v69, v98, v99
	v_add_f32_e32 v69, v78, v69
	v_add_f32_e32 v100, v69, v68
	v_add_u32_e32 v68, 0x90, v146
	v_ashrrev_i32_e32 v69, 31, v68
	v_lshlrev_b64 v[70:71], 11, v[68:69]
	v_lshl_add_u64 v[68:69], s[38:39], 0, v[70:71]
	v_lshl_add_u64 v[68:69], v[68:69], 0, v[150:151]
	global_load_dwordx4 v[76:79], v[68:69], off
	global_load_dwordx4 v[102:105], v[68:69], off offset:256
	v_lshl_add_u64 v[70:71], v[148:149], 0, v[70:71]
	s_waitcnt vmcnt(5)
	v_lshlrev_b32_e32 v86, 16, v90
	v_and_b32_e32 v87, 0xffff0000, v90
	v_lshlrev_b32_e32 v90, 16, v91
	v_and_b32_e32 v91, 0xffff0000, v91
	v_lshlrev_b32_e32 v88, 16, v92
	v_and_b32_e32 v89, 0xffff0000, v92
	v_lshlrev_b32_e32 v92, 16, v93
	v_and_b32_e32 v93, 0xffff0000, v93
	v_lshl_add_u64 v[68:69], v[148:149], 0, v[84:85]
	v_pk_fma_f32 v[66:67], v[66:67], 0.5, v[90:91] op_sel_hi:[1,0,1]
	v_pk_fma_f32 v[64:65], v[64:65], 0.5, v[86:87] op_sel_hi:[1,0,1]
	v_pk_fma_f32 v[84:85], v[62:63], 0.5, v[92:93] op_sel_hi:[1,0,1]
	v_pk_fma_f32 v[62:63], v[60:61], 0.5, v[88:89] op_sel_hi:[1,0,1]
	v_cvt_pk_bf16_f32 v60, v64, v65
	v_cvt_pk_bf16_f32 v61, v66, v67
	v_cvt_pk_bf16_f32 v62, v62, v63
	v_cvt_pk_bf16_f32 v63, v84, v85
	global_store_dwordx4 v[68:69], v[60:63], off sc1
	v_lshlrev_b32_e32 v64, 16, v60
	v_lshlrev_b32_e32 v65, 16, v61
	v_and_b32_e32 v60, 0xffff0000, v60
	v_and_b32_e32 v61, 0xffff0000, v61
	v_lshlrev_b32_e32 v66, 16, v62
	v_and_b32_e32 v62, 0xffff0000, v62
	v_lshlrev_b32_e32 v67, 16, v63
	v_and_b32_e32 v63, 0xffff0000, v63
	v_mul_f32_e32 v84, v60, v60
	v_mul_f32_e32 v85, v61, v61
	v_mul_f32_e32 v60, v62, v62
	v_mul_f32_e32 v61, v63, v63
	s_waitcnt vmcnt(5)
	v_lshlrev_b32_e32 v96, 16, v118
	v_and_b32_e32 v97, 0xffff0000, v118
	v_lshlrev_b32_e32 v118, 16, v119
	v_and_b32_e32 v119, 0xffff0000, v119
	v_lshlrev_b32_e32 v116, 16, v120
	v_and_b32_e32 v117, 0xffff0000, v120
	v_lshlrev_b32_e32 v120, 16, v121
	v_and_b32_e32 v121, 0xffff0000, v121
	v_fmac_f32_e32 v60, v66, v66
	v_fmac_f32_e32 v61, v67, v67
	v_add_f32_e32 v62, v60, v61
	v_pk_fma_f32 v[58:59], v[58:59], 0.5, v[118:119] op_sel_hi:[1,0,1]
	v_pk_fma_f32 v[56:57], v[56:57], 0.5, v[96:97] op_sel_hi:[1,0,1]
	v_pk_fma_f32 v[60:61], v[54:55], 0.5, v[120:121] op_sel_hi:[1,0,1]
	v_pk_fma_f32 v[54:55], v[52:53], 0.5, v[116:117] op_sel_hi:[1,0,1]
	v_cvt_pk_bf16_f32 v52, v56, v57
	v_cvt_pk_bf16_f32 v53, v58, v59
	v_cvt_pk_bf16_f32 v54, v54, v55
	v_cvt_pk_bf16_f32 v55, v60, v61
	global_store_dwordx4 v[68:69], v[52:55], off offset:256 sc1
	v_lshlrev_b32_e32 v56, 16, v52
	v_lshlrev_b32_e32 v57, 16, v53
	v_and_b32_e32 v52, 0xffff0000, v52
	v_and_b32_e32 v53, 0xffff0000, v53
	v_mul_f32_e32 v52, v52, v52
	v_mul_f32_e32 v53, v53, v53
	v_lshlrev_b32_e32 v58, 16, v54
	v_and_b32_e32 v54, 0xffff0000, v54
	v_lshlrev_b32_e32 v59, 16, v55
	v_and_b32_e32 v55, 0xffff0000, v55
	v_fmac_f32_e32 v52, v56, v56
	v_fmac_f32_e32 v53, v57, v57
	v_add_f32_e32 v52, v52, v53
	v_mul_f32_e32 v53, v54, v54
	v_mul_f32_e32 v54, v55, v55
	v_fmac_f32_e32 v53, v58, v58
	v_fmac_f32_e32 v54, v59, v59
	v_fmac_f32_e32 v85, v65, v65
	v_add_f32_e32 v53, v53, v54
	v_fmac_f32_e32 v84, v64, v64
	v_add_f32_e32 v52, v53, v52
	v_add_f32_e32 v53, v84, v85
	v_add_f32_e32 v53, v62, v53
	v_add_f32_e32 v84, v53, v52
	v_add_u32_e32 v52, 0xa0, v146
	v_ashrrev_i32_e32 v53, 31, v52
	v_lshlrev_b64 v[58:59], 11, v[52:53]
	s_waitcnt vmcnt(3)
; __device__ __forceinline__ unsigned pk2(float lo, float hi) { f32x2 v = {lo, hi}; bf16x2_t b = __builtin_convertvector(v, bf16x2_t); return __builtin_bit_cast(unsigned, b); }
; __device__ __forceinline__ float bflo(unsigned w) { return __uint_as_float(w << 16); }
; __device__ __forceinline__ float bfhi(unsigned w) { return __uint_as_float(w & 0xffff0000u); }
;     __device__ __forceinline__ void operator()(const f32x4 (&acc)[2][2][4][2], const Unit& u, int wr, int wc, int fr, int fq) const {
;     ...
;         for (int b = 0; b < 8; ++b) {
;             const int ai = b >> 2, m = b & 3;
;             const size_t off = (size_t)(row0 + ai * HALF + m * 16) * 1024 + col0;
;             if (b < 7) EPIRES_LOAD(rn, (size_t)(row0 + ((b + 1) >> 2) * HALF + ((b + 1) & 3) * 16) * 1024 + col0);
;             float ss = 0.f;
; #pragma unroll
;             for (int bj = 0; bj < 2; ++bj) {
;                 const f32x4 o0 = rv[bj][0] + acc[ai][bj][m][0] * scale, o1 = rv[bj][1] + acc[ai][bj][m][1] * scale;
;                 u32x4 w; w.x = ::pk2(o0[0], o0[1]); w.y = ::pk2(o0[2], o0[3]); w.z = ::pk2(o1[0], o1[1]); w.w = ::pk2(o1[2], o1[3]);
;                 *(u32x4*)(X + off + bj * HALF) = w;
;                 const float q0 = ::bflo(w.x), q1 = ::bfhi(w.x), q2 = ::bflo(w.y), q3 = ::bfhi(w.y), q4 = ::bflo(w.z), q5 = ::bfhi(w.z), q6 = ::bflo(w.w), q7 = ::bfhi(w.w);
;                 ss += ((q0 * q0 + q1 * q1) + (q2 * q2 + q3 * q3)) + ((q4 * q4 + q5 * q5) + (q6 * q6 + q7 * q7));
;             }
;             ssv[b] = ss;
	v_lshlrev_b32_e32 v72, 16, v76
	v_and_b32_e32 v73, 0xffff0000, v76
	v_lshlrev_b32_e32 v76, 16, v77
	v_and_b32_e32 v77, 0xffff0000, v77
	v_lshlrev_b32_e32 v74, 16, v78
	v_and_b32_e32 v75, 0xffff0000, v78
	v_lshlrev_b32_e32 v78, 16, v79
	v_and_b32_e32 v79, 0xffff0000, v79
	v_pk_fma_f32 v[50:51], v[50:51], 0.5, v[76:77] op_sel_hi:[1,0,1]
	v_pk_fma_f32 v[48:49], v[48:49], 0.5, v[72:73] op_sel_hi:[1,0,1]
	v_pk_fma_f32 v[72:73], v[46:47], 0.5, v[78:79] op_sel_hi:[1,0,1]
	v_pk_fma_f32 v[46:47], v[44:45], 0.5, v[74:75] op_sel_hi:[1,0,1]
	v_cvt_pk_bf16_f32 v44, v48, v49
	v_cvt_pk_bf16_f32 v45, v50, v51
	v_cvt_pk_bf16_f32 v46, v46, v47
	v_cvt_pk_bf16_f32 v47, v72, v73
	global_store_dwordx4 v[70:71], v[44:47], off sc1
	v_lshlrev_b32_e32 v48, 16, v44
	v_lshlrev_b32_e32 v49, 16, v45
	v_and_b32_e32 v44, 0xffff0000, v44
	v_and_b32_e32 v45, 0xffff0000, v45
	v_lshlrev_b32_e32 v50, 16, v46
	v_and_b32_e32 v46, 0xffff0000, v46
	v_lshlrev_b32_e32 v51, 16, v47
	v_and_b32_e32 v47, 0xffff0000, v47
	v_mul_f32_e32 v72, v44, v44
	v_mul_f32_e32 v73, v45, v45
	v_mul_f32_e32 v44, v46, v46
	v_mul_f32_e32 v45, v47, v47
	s_waitcnt vmcnt(3)
	v_lshlrev_b32_e32 v80, 16, v102
	v_and_b32_e32 v81, 0xffff0000, v102
	v_lshlrev_b32_e32 v94, 16, v103
	v_and_b32_e32 v95, 0xffff0000, v103
	v_lshlrev_b32_e32 v82, 16, v104
	v_and_b32_e32 v83, 0xffff0000, v104
	v_lshlrev_b32_e32 v98, 16, v105
	v_and_b32_e32 v99, 0xffff0000, v105
	v_fmac_f32_e32 v44, v50, v50
	v_fmac_f32_e32 v45, v51, v51
	v_add_f32_e32 v46, v44, v45
	v_pk_fma_f32 v[42:43], v[42:43], 0.5, v[94:95] op_sel_hi:[1,0,1]
	v_pk_fma_f32 v[40:41], v[40:41], 0.5, v[80:81] op_sel_hi:[1,0,1]
	v_pk_fma_f32 v[44:45], v[38:39], 0.5, v[98:99] op_sel_hi:[1,0,1]
	v_pk_fma_f32 v[38:39], v[36:37], 0.5, v[82:83] op_sel_hi:[1,0,1]
	v_cvt_pk_bf16_f32 v36, v40, v41
	v_cvt_pk_bf16_f32 v37, v42, v43
	v_cvt_pk_bf16_f32 v38, v38, v39
	v_cvt_pk_bf16_f32 v39, v44, v45
	global_store_dwordx4 v[70:71], v[36:39], off offset:256 sc1
	v_lshlrev_b32_e32 v40, 16, v36
	v_lshlrev_b32_e32 v41, 16, v37
	v_and_b32_e32 v36, 0xffff0000, v36
	v_and_b32_e32 v37, 0xffff0000, v37
	v_mul_f32_e32 v36, v36, v36
	v_mul_f32_e32 v37, v37, v37
	v_lshlrev_b32_e32 v42, 16, v38
	v_and_b32_e32 v38, 0xffff0000, v38
	v_lshlrev_b32_e32 v43, 16, v39
	v_and_b32_e32 v39, 0xffff0000, v39
	v_fmac_f32_e32 v36, v40, v40
	v_fmac_f32_e32 v37, v41, v41
	v_add_f32_e32 v36, v36, v37
	v_mul_f32_e32 v37, v38, v38
	v_mul_f32_e32 v38, v39, v39
	v_fmac_f32_e32 v37, v42, v42
	v_fmac_f32_e32 v38, v43, v43
	v_fmac_f32_e32 v73, v49, v49
	v_add_f32_e32 v37, v37, v38
	v_fmac_f32_e32 v72, v48, v48
	v_add_f32_e32 v36, v37, v36
	v_add_f32_e32 v37, v72, v73
	v_add_f32_e32 v37, v46, v37
	v_add_f32_e32 v50, v37, v36
	v_add_u32_e32 v36, 0xb0, v146
	v_ashrrev_i32_e32 v37, 31, v36
	v_lshlrev_b64 v[46:47], 11, v[36:37]
	v_lshl_add_u64 v[36:37], s[38:39], 0, v[46:47]
	v_lshl_add_u64 v[70:71], v[36:37], 0, v[150:151]
	global_load_dwordx4 v[36:39], v[70:71], off
	v_lshl_add_u64 v[52:53], s[38:39], 0, v[58:59]
	v_lshl_add_u64 v[64:65], v[52:53], 0, v[150:151]
	global_load_dwordx4 v[60:63], v[64:65], off
	global_load_dwordx4 v[86:89], v[64:65], off offset:256
	v_lshl_add_u64 v[58:59], v[148:149], 0, v[58:59]
	s_waitcnt vmcnt(2)
	v_lshlrev_b32_e32 v42, 16, v36
	v_and_b32_e32 v43, 0xffff0000, v36
	v_lshlrev_b32_e32 v48, 16, v37
	v_and_b32_e32 v49, 0xffff0000, v37
	v_lshlrev_b32_e32 v40, 16, v38
	v_and_b32_e32 v41, 0xffff0000, v38
	v_lshlrev_b32_e32 v44, 16, v39
	v_and_b32_e32 v45, 0xffff0000, v39
	global_load_dwordx4 v[36:39], v[70:71], off offset:256
	s_waitcnt vmcnt(2)
	v_lshlrev_b32_e32 v54, 16, v60
	v_and_b32_e32 v55, 0xffff0000, v60
	v_lshlrev_b32_e32 v60, 16, v61
	v_and_b32_e32 v61, 0xffff0000, v61
	v_lshlrev_b32_e32 v52, 16, v62
	v_and_b32_e32 v53, 0xffff0000, v62
	v_lshlrev_b32_e32 v56, 16, v63
	v_and_b32_e32 v57, 0xffff0000, v63
	s_waitcnt vmcnt(1)
	v_lshlrev_b32_e32 v64, 16, v86
	v_and_b32_e32 v65, 0xffff0000, v86
	v_pk_fma_f32 v[32:33], v[32:33], 0.5, v[54:55] op_sel_hi:[1,0,1]
	v_lshlrev_b32_e32 v68, 16, v87
	v_and_b32_e32 v69, 0xffff0000, v87
	v_lshlrev_b32_e32 v62, 16, v88
	v_and_b32_e32 v63, 0xffff0000, v88
	v_lshlrev_b32_e32 v66, 16, v89
	v_and_b32_e32 v67, 0xffff0000, v89
	v_pk_fma_f32 v[34:35], v[34:35], 0.5, v[60:61] op_sel_hi:[1,0,1]
	v_pk_fma_f32 v[54:55], v[30:31], 0.5, v[56:57] op_sel_hi:[1,0,1]
	v_pk_fma_f32 v[30:31], v[28:29], 0.5, v[52:53] op_sel_hi:[1,0,1]
	v_cvt_pk_bf16_f32 v28, v32, v33
	v_pk_fma_f32 v[24:25], v[24:25], 0.5, v[64:65] op_sel_hi:[1,0,1]
	v_cvt_pk_bf16_f32 v29, v34, v35
	v_pk_fma_f32 v[26:27], v[26:27], 0.5, v[68:69] op_sel_hi:[1,0,1]
	v_pk_fma_f32 v[32:33], v[22:23], 0.5, v[66:67] op_sel_hi:[1,0,1]
	v_pk_fma_f32 v[22:23], v[20:21], 0.5, v[62:63] op_sel_hi:[1,0,1]
	v_cvt_pk_bf16_f32 v20, v24, v25
	v_and_b32_e32 v25, 0xffff0000, v28
	v_cvt_pk_bf16_f32 v21, v26, v27
	v_lshlrev_b32_e32 v24, 16, v28
	v_mul_f32_e32 v25, v25, v25
	v_and_b32_e32 v26, 0xffff0000, v29
	v_fmac_f32_e32 v25, v24, v24
	v_lshlrev_b32_e32 v24, 16, v29
	v_mul_f32_e32 v26, v26, v26
	v_cvt_pk_bf16_f32 v30, v30, v31
	v_fmac_f32_e32 v26, v24, v24
	v_cvt_pk_bf16_f32 v31, v54, v55
	v_add_f32_e32 v24, v25, v26
	v_and_b32_e32 v26, 0xffff0000, v30
	v_lshlrev_b32_e32 v25, 16, v30
	v_mul_f32_e32 v26, v26, v26
	v_and_b32_e32 v27, 0xffff0000, v31
	v_fmac_f32_e32 v26, v25, v25
	v_lshlrev_b32_e32 v25, 16, v31
	v_mul_f32_e32 v27, v27, v27
	v_fmac_f32_e32 v27, v25, v25
	v_cvt_pk_bf16_f32 v22, v22, v23
	v_cvt_pk_bf16_f32 v23, v32, v33
	v_add_f32_e32 v25, v26, v27
; __device__ __forceinline__ unsigned pk2(float lo, float hi) { f32x2 v = {lo, hi}; bf16x2_t b = __builtin_convertvector(v, bf16x2_t); return __builtin_bit_cast(unsigned, b); }
; __device__ __forceinline__ float bflo(unsigned w) { return __uint_as_float(w << 16); }
; __device__ __forceinline__ float bfhi(unsigned w) { return __uint_as_float(w & 0xffff0000u); }
; __device__ __forceinline__ float xsum16(float x) { auto r = __builtin_amdgcn_permlane16_swap(__float_as_uint(x), __float_as_uint(x), false, false); return __uint_as_float(r[0]) + __uint_as_float(r[1]); }
; __device__ __forceinline__ float xsum32(float x) { auto r = __builtin_amdgcn_permlane32_swap(__float_as_uint(x), __float_as_uint(x), false, false); return __uint_as_float(r[0]) + __uint_as_float(r[1]); }
;     __device__ __forceinline__ void operator()(const f32x4 (&acc)[2][2][4][2], const Unit& u, int wr, int wc, int fr, int fq) const {
;     ...
;             for (int bj = 0; bj < 2; ++bj) {
;                 const f32x4 o0 = rv[bj][0] + acc[ai][bj][m][0] * scale, o1 = rv[bj][1] + acc[ai][bj][m][1] * scale;
;                 u32x4 w; w.x = ::pk2(o0[0], o0[1]); w.y = ::pk2(o0[2], o0[3]); w.z = ::pk2(o1[0], o1[1]); w.w = ::pk2(o1[2], o1[3]);
;                 *(u32x4*)(X + off + bj * HALF) = w;
;                 const float q0 = ::bflo(w.x), q1 = ::bfhi(w.x), q2 = ::bflo(w.y), q3 = ::bfhi(w.y), q4 = ::bflo(w.z), q5 = ::bfhi(w.z), q6 = ::bflo(w.w), q7 = ::bfhi(w.w);
;                 ss += ((q0 * q0 + q1 * q1) + (q2 * q2 + q3 * q3)) + ((q4 * q4 + q5 * q5) + (q6 * q6 + q7 * q7));
;             }
;             ssv[b] = ss;
; #pragma unroll
;             for (int bj = 0; bj < 2; ++bj)
; #pragma unroll
;                 for (int n = 0; n < 2; ++n) rv[bj][n] = rn[bj][n];
;         }
; #pragma unroll
;         for (int b = 0; b < 8; ++b) ssv[b] = ::xsum16(ssv[b]);
; #pragma unroll
;         for (int b = 0; b < 8; ++b) ssv[b] = ::xsum32(ssv[b]);
;         if (fq == 0) {
; #pragma unroll
;             for (int b = 0; b < 8; ++b) atomicAdd(RS + row0 + (b >> 2) * HALF + (b & 3) * 16, (unsigned)(ssv[b] * 1024.f + 0.5f));
;         }
	global_store_dwordx4 v[58:59], v[20:23], off offset:256 sc1
	v_add_f32_e32 v24, v25, v24
	v_lshlrev_b32_e32 v25, 16, v20
	v_and_b32_e32 v20, 0xffff0000, v20
	v_mul_f32_e32 v20, v20, v20
	v_fmac_f32_e32 v20, v25, v25
	v_lshlrev_b32_e32 v25, 16, v21
	v_and_b32_e32 v21, 0xffff0000, v21
	v_mul_f32_e32 v21, v21, v21
	v_fmac_f32_e32 v21, v25, v25
	v_add_f32_e32 v20, v20, v21
	v_lshlrev_b32_e32 v21, 16, v22
	v_and_b32_e32 v22, 0xffff0000, v22
	v_mul_f32_e32 v22, v22, v22
	v_fmac_f32_e32 v22, v21, v21
	v_lshlrev_b32_e32 v21, 16, v23
	v_and_b32_e32 v23, 0xffff0000, v23
	v_mul_f32_e32 v23, v23, v23
	v_fmac_f32_e32 v23, v21, v21
	v_add_f32_e32 v21, v22, v23
	v_add_f32_e32 v20, v21, v20
	v_pk_fma_f32 v[18:19], v[18:19], 0.5, v[48:49] op_sel_hi:[1,0,1]
	v_pk_fma_f32 v[16:17], v[16:17], 0.5, v[42:43] op_sel_hi:[1,0,1]
	v_pk_fma_f32 v[22:23], v[14:15], 0.5, v[44:45] op_sel_hi:[1,0,1]
	v_pk_fma_f32 v[14:15], v[12:13], 0.5, v[40:41] op_sel_hi:[1,0,1]
	v_add_f32_e32 v24, v24, v20
	v_lshl_add_u64 v[20:21], v[148:149], 0, v[46:47]
	v_cvt_pk_bf16_f32 v12, v16, v17
	v_cvt_pk_bf16_f32 v13, v18, v19
	v_cvt_pk_bf16_f32 v14, v14, v15
	v_cvt_pk_bf16_f32 v15, v22, v23
	global_store_dwordx4 v[20:21], v[12:15], off sc1
	v_lshlrev_b32_e32 v16, 16, v12
	v_lshlrev_b32_e32 v17, 16, v13
	v_and_b32_e32 v12, 0xffff0000, v12
	v_and_b32_e32 v13, 0xffff0000, v13
	v_lshlrev_b32_e32 v18, 16, v14
	v_and_b32_e32 v14, 0xffff0000, v14
	v_lshlrev_b32_e32 v19, 16, v15
	v_and_b32_e32 v15, 0xffff0000, v15
	v_mul_f32_e32 v22, v12, v12
	v_mul_f32_e32 v23, v13, v13
	v_mul_f32_e32 v12, v14, v14
	v_mul_f32_e32 v13, v15, v15
	s_waitcnt vmcnt(2)
	v_lshlrev_b32_e32 v70, 16, v36
	v_and_b32_e32 v71, 0xffff0000, v36
	v_lshlrev_b32_e32 v36, 16, v37
	v_and_b32_e32 v37, 0xffff0000, v37
	v_lshlrev_b32_e32 v72, 16, v38
	v_and_b32_e32 v73, 0xffff0000, v38
	v_lshlrev_b32_e32 v38, 16, v39
	v_and_b32_e32 v39, 0xffff0000, v39
	v_fmac_f32_e32 v12, v18, v18
	v_fmac_f32_e32 v13, v19, v19
	v_add_f32_e32 v14, v12, v13
	v_pk_fma_f32 v[10:11], v[10:11], 0.5, v[36:37] op_sel_hi:[1,0,1]
	v_pk_fma_f32 v[8:9], v[8:9], 0.5, v[70:71] op_sel_hi:[1,0,1]
	v_pk_fma_f32 v[12:13], v[6:7], 0.5, v[38:39] op_sel_hi:[1,0,1]
	v_pk_fma_f32 v[6:7], v[4:5], 0.5, v[72:73] op_sel_hi:[1,0,1]
	v_cvt_pk_bf16_f32 v4, v8, v9
	v_cvt_pk_bf16_f32 v5, v10, v11
	v_cvt_pk_bf16_f32 v6, v6, v7
	v_cvt_pk_bf16_f32 v7, v12, v13
	global_store_dwordx4 v[20:21], v[4:7], off offset:256 sc1
	v_lshlrev_b32_e32 v8, 16, v4
	v_lshlrev_b32_e32 v9, 16, v5
	v_and_b32_e32 v4, 0xffff0000, v4
	v_and_b32_e32 v5, 0xffff0000, v5
	v_mul_f32_e32 v4, v4, v4
	v_mul_f32_e32 v5, v5, v5
	v_lshlrev_b32_e32 v10, 16, v6
	v_and_b32_e32 v6, 0xffff0000, v6
	v_lshlrev_b32_e32 v11, 16, v7
	v_and_b32_e32 v7, 0xffff0000, v7
	v_fmac_f32_e32 v4, v8, v8
	v_fmac_f32_e32 v5, v9, v9
	v_add_f32_e32 v4, v4, v5
	v_mul_f32_e32 v5, v6, v6
	v_mul_f32_e32 v6, v7, v7
	v_fmac_f32_e32 v5, v10, v10
	v_fmac_f32_e32 v6, v11, v11
	v_fmac_f32_e32 v23, v17, v17
	v_add_f32_e32 v5, v5, v6
	v_fmac_f32_e32 v22, v16, v16
	v_add_f32_e32 v4, v5, v4
	v_add_f32_e32 v5, v22, v23
	v_add_f32_e32 v5, v14, v5
	v_add_f32_e32 v10, v5, v4
	v_mov_b32_e32 v4, v191
	v_mov_b32_e32 v5, v158
	v_mov_b32_e32 v6, v122
	v_mov_b32_e32 v7, v100
	v_mov_b32_e32 v8, v84
	v_mov_b32_e32 v9, v50
	v_mov_b32_e32 v11, v24
	v_mov_b32_e32 v12, v10
	v_permlane16_swap_b32_e32 v191, v4
	v_permlane16_swap_b32_e32 v158, v5
	v_permlane16_swap_b32_e32 v122, v6
	v_permlane16_swap_b32_e32 v100, v7
	v_permlane16_swap_b32_e32 v84, v8
	v_permlane16_swap_b32_e32 v50, v9
	v_permlane16_swap_b32_e32 v24, v11
	v_permlane16_swap_b32_e32 v10, v12
	v_add_f32_e32 v4, v191, v4
	v_add_f32_e32 v5, v158, v5
	v_add_f32_e32 v6, v122, v6
	v_add_f32_e32 v7, v100, v7
	v_add_f32_e32 v8, v84, v8
	v_add_f32_e32 v9, v50, v9
	v_add_f32_e32 v11, v24, v11
	v_add_f32_e32 v13, v10, v12
	v_mov_b32_e32 v10, v4
	v_mov_b32_e32 v12, v5
	v_mov_b32_e32 v14, v6
	v_mov_b32_e32 v15, v7
	v_mov_b32_e32 v16, v8
	v_mov_b32_e32 v17, v9
	v_mov_b32_e32 v18, v11
	v_mov_b32_e32 v19, v13
	v_permlane32_swap_b32_e32 v4, v10
	v_permlane32_swap_b32_e32 v5, v12
	v_permlane32_swap_b32_e32 v6, v14
	v_permlane32_swap_b32_e32 v7, v15
	v_permlane32_swap_b32_e32 v8, v16
	v_permlane32_swap_b32_e32 v9, v17
	v_permlane32_swap_b32_e32 v11, v18
	v_permlane32_swap_b32_e32 v13, v19
	global_store_dwordx4 v[58:59], v[28:31], off sc1
	s_and_saveexec_b64 s[58:59], s[40:41]
	s_cbranch_execz .LBB0_54
	v_add_f32_e32 v10, v4, v10
	v_add_f32_e32 v12, v5, v12
	v_fma_f32 v10, v10, s3, 0.5
	v_add_f32_e32 v6, v6, v14
	v_cvt_u32_f32_e32 v10, v10
	v_fma_f32 v12, v12, s3, 0.5
	v_add_f32_e32 v7, v7, v15
	v_cvt_u32_f32_e32 v12, v12
	v_fma_f32 v6, v6, s3, 0.5
	v_cvt_u32_f32_e32 v6, v6
	v_fma_f32 v7, v7, s3, 0.5
	v_add_f32_e32 v8, v8, v16
	v_lshl_add_u64 v[4:5], v[146:147], 2, s[52:53]
	v_cvt_u32_f32_e32 v7, v7
	v_add_f32_e32 v9, v9, v17
	global_atomic_add v[4:5], v10, off
	global_atomic_add v[4:5], v12, off offset:64
	global_atomic_add v[4:5], v6, off offset:128
	global_atomic_add v[4:5], v7, off offset:192
	v_fma_f32 v6, v8, s3, 0.5
	v_add_f32_e32 v11, v11, v18
	v_cvt_u32_f32_e32 v6, v6
	v_fma_f32 v7, v9, s3, 0.5
	v_add_f32_e32 v13, v13, v19
	v_cvt_u32_f32_e32 v7, v7
	v_fma_f32 v8, v11, s3, 0.5
	v_cvt_u32_f32_e32 v8, v8
	v_fma_f32 v9, v13, s3, 0.5
	v_cvt_u32_f32_e32 v9, v9
	global_atomic_add v[4:5], v6, off offset:512
	global_atomic_add v[4:5], v7, off offset:576
	global_atomic_add v[4:5], v8, off offset:640
	global_atomic_add v[4:5], v9, off offset:704

; __device__ __forceinline__ float fexp2(float x) { return __builtin_amdgcn_exp2f(x); }
; __device__ __forceinline__ float frcp(float x) { return __builtin_amdgcn_rcpf(x); }
;     __device__ __forceinline__ void operator()(const f32x4 (&acc)[2][2][4][2], const Unit& u, int wr, int wc, int fr, int fq) const {
;         const int row0 = u.pm * BM + wr * 64 + fr, col0 = u.pn * 128 + wc * 32 + 8 * fq;
;         float rsv[2][4];
; #pragma unroll
;         for (int ai = 0; ai < 2; ++ai)
; #pragma unroll
;             for (int m = 0; m < 4; ++m) rsv[ai][m] = (float)RS[row0 + ai * HALF + m * 16] * (1.f / 1024.f);
; #pragma unroll
;         for (int ai = 0; ai < 2; ++ai)
; #pragma unroll
;             for (int mp = 0; mp < 2; ++mp) {
;                 float g[16], uu[16], e[16];
; #pragma unroll
;                 for (int h = 0; h < 2; ++h) {
;                     const int m = 2 * mp + h;
;                     const float rs = __builtin_amdgcn_rsqf(rsv[ai][m] * (1.f / 1024.f) + 1e-6f);
; #pragma unroll
;                     for (int j = 0; j < 4; ++j) { g[8 * h + j] = acc[ai][0][m][0][j] * rs; g[8 * h + 4 + j] = acc[ai][0][m][1][j] * rs; uu[8 * h + j] = acc[ai][1][m][0][j] * rs; uu[8 * h + 4 + j] = acc[ai][1][m][1][j] * rs; }
;                 }
;                 __builtin_amdgcn_sched_barrier(0);
; #pragma unroll
;                 for (int i = 0; i < 16; ++i) e[i] = ::fexp2(-LOG2E * g[i]);
;                 __builtin_amdgcn_sched_barrier(0);
; #pragma unroll
;                 for (int i = 0; i < 16; ++i) e[i] = ::frcp(1.f + e[i]);
;                 __builtin_amdgcn_sched_barrier(0);
; #pragma unroll
;                 for (int i = 0; i < 16; ++i) g[i] = g[i] * e[i] * uu[i];
.LBB0_72:
	v_lshl_add_u32 v146, s72, 8, v3
	v_ashrrev_i32_e32 v147, 31, v146
	v_lshl_add_u64 v[148:149], v[146:147], 2, s[44:45]
	global_load_dword v140, v[148:149], off
	global_load_dword v141, v[148:149], off offset:64
	global_load_dword v150, v[148:149], off offset:128
	global_load_dword v154, v[148:149], off offset:192
	global_load_dword v156, v[148:149], off offset:512
	global_load_dword v158, v[148:149], off offset:576
	global_load_dword v159, v[148:149], off offset:640
	s_nop 0
	global_load_dword v148, v[148:149], off offset:704
	v_or_b32_e32 v161, 16, v146
	v_or_b32_e32 v160, 32, v146
	v_add_u32_e32 v157, 0x80, v146
	v_add_u32_e32 v155, 0x90, v146
	v_add_u32_e32 v147, 0xa0, v146
	s_waitcnt vmcnt(0)
	v_cvt_f32_u32_e32 v140, v140
	v_cvt_f32_u32_e32 v141, v141
	v_cvt_f32_u32_e32 v149, v150
	v_cvt_f32_u32_e32 v150, v154
	v_cvt_f32_u32_e32 v154, v156
	v_cvt_f32_u32_e32 v156, v158
	v_cvt_f32_u32_e32 v162, v159
	v_cvt_f32_u32_e32 v148, v148
	v_mul_f32_e32 v140, 0x3a800000, v140
	v_mul_f32_e32 v141, 0x3a800000, v141
	v_mul_f32_e32 v158, 0x3a800000, v156
	v_fmamk_f32 v140, v140, 0x3a800000, v175
	v_fmamk_f32 v141, v141, 0x3a800000, v175
	v_mul_f32_e32 v156, 0x3a800000, v148
	v_lshl_or_b32 v148, s64, 7, v152
	v_mul_f32_e32 v163, 0x3a800000, v149
	v_mul_f32_e32 v166, 0x3a800000, v150
	v_mul_f32_e32 v159, 0x3a800000, v154
	v_mul_f32_e32 v154, 0x3a800000, v162
	v_rsq_f32_e32 v162, v140
	v_rsq_f32_e32 v150, v141
	v_ashrrev_i32_e32 v149, 31, v148
	v_pk_mul_f32 v[128:129], v[128:129], v[162:163] op_sel_hi:[1,0]
	v_pk_mul_f32 v[124:125], v[124:125], v[162:163] op_sel_hi:[1,0]
	v_mul_f32_e32 v140, 0xbfb8aa3b, v128
	v_exp_f32_e32 v140, v140
	v_mul_f32_e32 v141, 0xbfb8aa3b, v129
	v_exp_f32_e32 v141, v141
	v_pk_mul_f32 v[126:127], v[126:127], v[162:163] op_sel_hi:[1,0]
	v_add_f32_e32 v140, 1.0, v140
	v_rcp_f32_e32 v164, v140
	v_add_f32_e32 v140, 1.0, v141
	v_rcp_f32_e32 v165, v140
	v_pk_mul_f32 v[120:121], v[120:121], v[162:163] op_sel_hi:[1,0]
	v_pk_mul_f32 v[116:117], v[116:117], v[162:163] op_sel_hi:[1,0]
	v_pk_mul_f32 v[118:119], v[118:119], v[162:163] op_sel_hi:[1,0]
	v_pk_mul_f32 v[128:129], v[128:129], v[164:165]
	v_pk_mul_f32 v[112:113], v[112:113], v[150:151] op_sel_hi:[1,0]
	v_pk_mul_f32 v[124:125], v[124:125], v[128:129]
	v_pk_mul_f32 v[128:129], v[130:131], v[162:163] op_sel_hi:[1,0]
	v_pk_mul_f32 v[108:109], v[108:109], v[150:151] op_sel_hi:[1,0]
	v_mul_f32_e32 v130, 0xbfb8aa3b, v128
	v_mul_f32_e32 v131, 0xbfb8aa3b, v129
	v_exp_f32_e32 v130, v130
	v_exp_f32_e32 v131, v131
	v_pk_mul_f32 v[110:111], v[110:111], v[150:151] op_sel_hi:[1,0]
	v_pk_mul_f32 v[104:105], v[104:105], v[150:151] op_sel_hi:[1,0]
	v_add_f32_e32 v130, 1.0, v130
	v_add_f32_e32 v131, 1.0, v131
	v_rcp_f32_e32 v130, v130
	v_rcp_f32_e32 v131, v131
	v_pk_mul_f32 v[100:101], v[100:101], v[150:151] op_sel_hi:[1,0]
	v_pk_mul_f32 v[102:103], v[102:103], v[150:151] op_sel_hi:[1,0]
	v_pk_mul_f32 v[128:129], v[128:129], v[130:131]
	s_nop 0
	v_pk_mul_f32 v[126:127], v[126:127], v[128:129]
	v_mul_f32_e32 v128, 0xbfb8aa3b, v120
	v_mul_f32_e32 v129, 0xbfb8aa3b, v121
	v_exp_f32_e32 v128, v128
	v_exp_f32_e32 v129, v129
	v_add_f32_e32 v128, 1.0, v128
	v_add_f32_e32 v129, 1.0, v129
	v_rcp_f32_e32 v128, v128
	v_rcp_f32_e32 v129, v129
	s_nop 0
	v_pk_mul_f32 v[120:121], v[120:121], v[128:129]
	s_nop 0
	v_pk_mul_f32 v[116:117], v[116:117], v[120:121]
	v_pk_mul_f32 v[120:121], v[122:123], v[162:163] op_sel_hi:[1,0]
	s_nop 0
	v_mul_f32_e32 v122, 0xbfb8aa3b, v120
	v_mul_f32_e32 v123, 0xbfb8aa3b, v121
	v_exp_f32_e32 v122, v122
	v_exp_f32_e32 v123, v123
	v_add_f32_e32 v122, 1.0, v122
	v_add_f32_e32 v123, 1.0, v123
	v_rcp_f32_e32 v122, v122
	v_rcp_f32_e32 v123, v123
	s_nop 0
	v_pk_mul_f32 v[120:121], v[120:121], v[122:123]
	s_nop 0
	v_pk_mul_f32 v[118:119], v[118:119], v[120:121]
	v_mul_f32_e32 v120, 0xbfb8aa3b, v112
	v_mul_f32_e32 v121, 0xbfb8aa3b, v113
	v_exp_f32_e32 v120, v120
	v_exp_f32_e32 v121, v121
	v_add_f32_e32 v120, 1.0, v120
	v_add_f32_e32 v121, 1.0, v121
	v_rcp_f32_e32 v120, v120
	v_rcp_f32_e32 v121, v121
	s_nop 0
	v_pk_mul_f32 v[112:113], v[112:113], v[120:121]
	s_nop 0
	v_pk_mul_f32 v[108:109], v[108:109], v[112:113]
	v_pk_mul_f32 v[112:113], v[114:115], v[150:151] op_sel_hi:[1,0]
	s_nop 0
	v_mul_f32_e32 v114, 0xbfb8aa3b, v112
	v_mul_f32_e32 v115, 0xbfb8aa3b, v113
	v_exp_f32_e32 v114, v114
	v_exp_f32_e32 v115, v115
	v_add_f32_e32 v114, 1.0, v114
	v_add_f32_e32 v115, 1.0, v115
	v_rcp_f32_e32 v114, v114
	v_rcp_f32_e32 v115, v115
	s_nop 0
	v_pk_mul_f32 v[112:113], v[112:113], v[114:115]
	s_nop 0
	v_pk_mul_f32 v[110:111], v[110:111], v[112:113]
	v_mul_f32_e32 v112, 0xbfb8aa3b, v104
	v_mul_f32_e32 v113, 0xbfb8aa3b, v105
	v_exp_f32_e32 v112, v112
	v_exp_f32_e32 v113, v113
	v_add_f32_e32 v112, 1.0, v112
	v_add_f32_e32 v113, 1.0, v113
	v_rcp_f32_e32 v112, v112
	v_rcp_f32_e32 v113, v113
	s_nop 0
	v_pk_mul_f32 v[104:105], v[104:105], v[112:113]
	s_nop 0
	v_pk_mul_f32 v[112:113], v[100:101], v[104:105]
	v_pk_mul_f32 v[100:101], v[106:107], v[150:151] op_sel_hi:[1,0]
	v_cvt_pk_bf16_f32 v106, v116, v117
	v_mul_f32_e32 v104, 0xbfb8aa3b, v100
	v_mul_f32_e32 v105, 0xbfb8aa3b, v101
	v_exp_f32_e32 v104, v104
	v_exp_f32_e32 v105, v105
	v_cvt_pk_bf16_f32 v107, v118, v119
	v_add_f32_e32 v104, 1.0, v104
	v_add_f32_e32 v105, 1.0, v105
	v_rcp_f32_e32 v104, v104
	v_rcp_f32_e32 v105, v105
	s_nop 0
	v_pk_mul_f32 v[100:101], v[100:101], v[104:105]
	s_nop 0
	v_pk_mul_f32 v[114:115], v[102:103], v[100:101]
	v_mov_b64_e32 v[100:101], s[70:71]
	v_mad_i64_i32 v[104:105], s[64:65], v146, s97, v[100:101]
	v_lshlrev_b64 v[102:103], 1, v[148:149]
	v_lshl_add_u64 v[120:121], v[104:105], 0, v[102:103]
	v_cvt_pk_bf16_f32 v104, v124, v125
; __device__ __forceinline__ unsigned pk2(float lo, float hi) { f32x2 v = {lo, hi}; bf16x2_t b = __builtin_convertvector(v, bf16x2_t); return __builtin_bit_cast(unsigned, b); }
; __device__ __forceinline__ float fexp2(float x) { return __builtin_amdgcn_exp2f(x); }
; __device__ __forceinline__ float frcp(float x) { return __builtin_amdgcn_rcpf(x); }
;     __device__ __forceinline__ void operator()(const f32x4 (&acc)[2][2][4][2], const Unit& u, int wr, int wc, int fr, int fq) const {
;     ...
;             for (int m = 0; m < 4; ++m) rsv[ai][m] = (float)RS[row0 + ai * HALF + m * 16] * (1.f / 1024.f);
; #pragma unroll
;         for (int ai = 0; ai < 2; ++ai)
; #pragma unroll
;             for (int mp = 0; mp < 2; ++mp) {
;                 float g[16], uu[16], e[16];
; #pragma unroll
;                 for (int h = 0; h < 2; ++h) {
;                     const int m = 2 * mp + h;
;                     const float rs = __builtin_amdgcn_rsqf(rsv[ai][m] * (1.f / 1024.f) + 1e-6f);
; #pragma unroll
;                     for (int j = 0; j < 4; ++j) { g[8 * h + j] = acc[ai][0][m][0][j] * rs; g[8 * h + 4 + j] = acc[ai][0][m][1][j] * rs; uu[8 * h + j] = acc[ai][1][m][0][j] * rs; uu[8 * h + 4 + j] = acc[ai][1][m][1][j] * rs; }
;                 }
;                 __builtin_amdgcn_sched_barrier(0);
; #pragma unroll
;                 for (int i = 0; i < 16; ++i) e[i] = ::fexp2(-LOG2E * g[i]);
;                 __builtin_amdgcn_sched_barrier(0);
; #pragma unroll
;                 for (int i = 0; i < 16; ++i) e[i] = ::frcp(1.f + e[i]);
;                 __builtin_amdgcn_sched_barrier(0);
; #pragma unroll
;                 for (int i = 0; i < 16; ++i) g[i] = g[i] * e[i] * uu[i];
; #pragma unroll
;                 for (int h = 0; h < 2; ++h) {
;                     bf16_t* rowp = O + (size_t)(row0 + ai * HALF + (2 * mp + h) * 16) * ldo + col0;
;                     u32x4 w; w.x = ::pk2(g[8 * h + 0], g[8 * h + 1]); w.y = ::pk2(g[8 * h + 2], g[8 * h + 3]); w.z = ::pk2(g[8 * h + 4], g[8 * h + 5]); w.w = ::pk2(g[8 * h + 6], g[8 * h + 7]);
;                     *(u32x4*)rowp = w;
;                 }
	v_cvt_pk_bf16_f32 v105, v126, v127
	global_store_dwordx4 v[120:121], v[104:107], off sc1
	s_nop 1
	v_mad_i64_i32 v[104:105], s[64:65], v161, s97, v[100:101]
	v_lshl_add_u64 v[116:117], v[104:105], 0, v[102:103]
	v_cvt_pk_bf16_f32 v104, v108, v109
	v_cvt_pk_bf16_f32 v105, v110, v111
	v_cvt_pk_bf16_f32 v106, v112, v113
	v_cvt_pk_bf16_f32 v107, v114, v115
	global_store_dwordx4 v[116:117], v[104:107], off sc1
	s_nop 1
	v_fmamk_f32 v104, v163, 0x3a800000, v175
	v_rsq_f32_e32 v106, v104
	v_fmamk_f32 v104, v166, 0x3a800000, v175
	v_rsq_f32_e32 v104, v104
	v_pk_mul_f32 v[96:97], v[96:97], v[106:107] op_sel_hi:[1,0]
	v_pk_mul_f32 v[92:93], v[92:93], v[106:107] op_sel_hi:[1,0]
	v_mul_f32_e32 v105, 0xbfb8aa3b, v96
	v_exp_f32_e32 v105, v105
	v_mul_f32_e32 v107, 0xbfb8aa3b, v97
	v_exp_f32_e32 v107, v107
	v_add_f32_e32 v105, 1.0, v105
	v_rcp_f32_e32 v108, v105
	v_add_f32_e32 v105, 1.0, v107
	v_rcp_f32_e32 v109, v105
	v_pk_mul_f32 v[94:95], v[94:95], v[106:107] op_sel_hi:[1,0]
	v_pk_mul_f32 v[88:89], v[88:89], v[106:107] op_sel_hi:[1,0]
	v_pk_mul_f32 v[84:85], v[84:85], v[106:107] op_sel_hi:[1,0]
	v_pk_mul_f32 v[96:97], v[96:97], v[108:109]
	v_pk_mul_f32 v[86:87], v[86:87], v[106:107] op_sel_hi:[1,0]
	v_pk_mul_f32 v[92:93], v[92:93], v[96:97]
	v_pk_mul_f32 v[96:97], v[98:99], v[106:107] op_sel_hi:[1,0]
	v_pk_mul_f32 v[80:81], v[80:81], v[104:105] op_sel_hi:[1,0]
	v_mul_f32_e32 v98, 0xbfb8aa3b, v96
	v_mul_f32_e32 v99, 0xbfb8aa3b, v97
	v_exp_f32_e32 v98, v98
	v_exp_f32_e32 v99, v99
	v_pk_mul_f32 v[76:77], v[76:77], v[104:105] op_sel_hi:[1,0]
	v_pk_mul_f32 v[78:79], v[78:79], v[104:105] op_sel_hi:[1,0]
	v_add_f32_e32 v98, 1.0, v98
	v_add_f32_e32 v99, 1.0, v99
	v_rcp_f32_e32 v98, v98
	v_rcp_f32_e32 v99, v99
	v_pk_mul_f32 v[72:73], v[72:73], v[104:105] op_sel_hi:[1,0]
	v_pk_mul_f32 v[68:69], v[68:69], v[104:105] op_sel_hi:[1,0]
	v_pk_mul_f32 v[70:71], v[70:71], v[104:105] op_sel_hi:[1,0]
	v_pk_mul_f32 v[96:97], v[96:97], v[98:99]
	s_nop 0
	v_pk_mul_f32 v[94:95], v[94:95], v[96:97]
	v_mul_f32_e32 v96, 0xbfb8aa3b, v88
	v_mul_f32_e32 v97, 0xbfb8aa3b, v89
	v_exp_f32_e32 v96, v96
	v_exp_f32_e32 v97, v97
	v_add_f32_e32 v96, 1.0, v96
	v_add_f32_e32 v97, 1.0, v97
	v_rcp_f32_e32 v96, v96
	v_rcp_f32_e32 v97, v97
	s_nop 0
	v_pk_mul_f32 v[88:89], v[88:89], v[96:97]
	s_nop 0
	v_pk_mul_f32 v[84:85], v[84:85], v[88:89]
	v_pk_mul_f32 v[88:89], v[90:91], v[106:107] op_sel_hi:[1,0]
	s_nop 0
	v_mul_f32_e32 v90, 0xbfb8aa3b, v88
	v_mul_f32_e32 v91, 0xbfb8aa3b, v89
	v_exp_f32_e32 v90, v90
	v_exp_f32_e32 v91, v91
	v_add_f32_e32 v90, 1.0, v90
	v_add_f32_e32 v91, 1.0, v91
	v_rcp_f32_e32 v90, v90
	v_rcp_f32_e32 v91, v91
	s_nop 0
	v_pk_mul_f32 v[88:89], v[88:89], v[90:91]
	s_nop 0
	v_pk_mul_f32 v[86:87], v[86:87], v[88:89]
	v_mul_f32_e32 v88, 0xbfb8aa3b, v80
	v_mul_f32_e32 v89, 0xbfb8aa3b, v81
	v_exp_f32_e32 v88, v88
	v_exp_f32_e32 v89, v89
	v_add_f32_e32 v88, 1.0, v88
	v_add_f32_e32 v89, 1.0, v89
	v_rcp_f32_e32 v88, v88
	v_rcp_f32_e32 v89, v89
	s_nop 0
	v_pk_mul_f32 v[80:81], v[80:81], v[88:89]
	s_nop 0
	v_pk_mul_f32 v[76:77], v[76:77], v[80:81]
	v_pk_mul_f32 v[80:81], v[82:83], v[104:105] op_sel_hi:[1,0]
	s_nop 0
	v_mul_f32_e32 v82, 0xbfb8aa3b, v80
	v_mul_f32_e32 v83, 0xbfb8aa3b, v81
	v_exp_f32_e32 v82, v82
	v_exp_f32_e32 v83, v83
	v_add_f32_e32 v82, 1.0, v82
	v_add_f32_e32 v83, 1.0, v83
	v_rcp_f32_e32 v82, v82
	v_rcp_f32_e32 v83, v83
	s_nop 0
	v_pk_mul_f32 v[80:81], v[80:81], v[82:83]
	s_nop 0
	v_pk_mul_f32 v[78:79], v[78:79], v[80:81]
	v_mul_f32_e32 v80, 0xbfb8aa3b, v72
	v_mul_f32_e32 v81, 0xbfb8aa3b, v73
	v_exp_f32_e32 v80, v80
	v_exp_f32_e32 v81, v81
	v_add_f32_e32 v80, 1.0, v80
	v_add_f32_e32 v81, 1.0, v81
	v_rcp_f32_e32 v80, v80
	v_rcp_f32_e32 v81, v81
	s_nop 0
	v_pk_mul_f32 v[72:73], v[72:73], v[80:81]
	s_nop 0
	v_pk_mul_f32 v[72:73], v[68:69], v[72:73]
	v_pk_mul_f32 v[68:69], v[74:75], v[104:105] op_sel_hi:[1,0]
	s_nop 0
	v_mul_f32_e32 v74, 0xbfb8aa3b, v68
	v_mul_f32_e32 v75, 0xbfb8aa3b, v69
	v_exp_f32_e32 v74, v74
	v_exp_f32_e32 v75, v75
	v_add_f32_e32 v74, 1.0, v74
	v_add_f32_e32 v75, 1.0, v75
	v_rcp_f32_e32 v74, v74
	v_rcp_f32_e32 v75, v75
	s_nop 0
	v_pk_mul_f32 v[68:69], v[68:69], v[74:75]
	s_nop 0
	v_pk_mul_f32 v[74:75], v[70:71], v[68:69]
	v_mad_i64_i32 v[68:69], s[64:65], v160, s97, v[100:101]
	v_lshl_add_u64 v[80:81], v[68:69], 0, v[102:103]
	v_cvt_pk_bf16_f32 v68, v92, v93
	v_cvt_pk_bf16_f32 v69, v94, v95
	v_cvt_pk_bf16_f32 v70, v84, v85
	v_cvt_pk_bf16_f32 v71, v86, v87
	global_store_dwordx4 v[80:81], v[68:71], off sc1
	s_nop 1
	v_or_b32_e32 v68, 48, v146
	v_mad_i64_i32 v[68:69], s[64:65], v68, s97, v[100:101]
	v_lshl_add_u64 v[80:81], v[68:69], 0, v[102:103]
	v_cvt_pk_bf16_f32 v68, v76, v77
	v_cvt_pk_bf16_f32 v69, v78, v79
	v_cvt_pk_bf16_f32 v70, v72, v73
	v_cvt_pk_bf16_f32 v71, v74, v75
	global_store_dwordx4 v[80:81], v[68:71], off sc1
	s_nop 1
	v_fmamk_f32 v68, v159, 0x3a800000, v175
	v_rsq_f32_e32 v70, v68
	v_fmamk_f32 v68, v158, 0x3a800000, v175
	v_rsq_f32_e32 v68, v68
	v_pk_mul_f32 v[64:65], v[64:65], v[70:71] op_sel_hi:[1,0]
	v_pk_mul_f32 v[60:61], v[60:61], v[70:71] op_sel_hi:[1,0]
	v_mul_f32_e32 v69, 0xbfb8aa3b, v64
	v_exp_f32_e32 v69, v69
	v_mul_f32_e32 v71, 0xbfb8aa3b, v65
	v_exp_f32_e32 v71, v71
	v_add_f32_e32 v69, 1.0, v69
	v_rcp_f32_e32 v72, v69
	v_add_f32_e32 v69, 1.0, v71
	v_rcp_f32_e32 v73, v69
	v_pk_mul_f32 v[62:63], v[62:63], v[70:71] op_sel_hi:[1,0]
	v_pk_mul_f32 v[56:57], v[56:57], v[70:71] op_sel_hi:[1,0]
	v_pk_mul_f32 v[52:53], v[52:53], v[70:71] op_sel_hi:[1,0]
	v_pk_mul_f32 v[64:65], v[64:65], v[72:73]
	v_pk_mul_f32 v[54:55], v[54:55], v[70:71] op_sel_hi:[1,0]
	v_pk_mul_f32 v[60:61], v[60:61], v[64:65]
	v_pk_mul_f32 v[64:65], v[66:67], v[70:71] op_sel_hi:[1,0]
; __device__ __forceinline__ unsigned pk2(float lo, float hi) { f32x2 v = {lo, hi}; bf16x2_t b = __builtin_convertvector(v, bf16x2_t); return __builtin_bit_cast(unsigned, b); }
; __device__ __forceinline__ float fexp2(float x) { return __builtin_amdgcn_exp2f(x); }
; __device__ __forceinline__ float frcp(float x) { return __builtin_amdgcn_rcpf(x); }
;     __device__ __forceinline__ void operator()(const f32x4 (&acc)[2][2][4][2], const Unit& u, int wr, int wc, int fr, int fq) const {
;     ...
;                     const float rs = __builtin_amdgcn_rsqf(rsv[ai][m] * (1.f / 1024.f) + 1e-6f);
; #pragma unroll
;                     for (int j = 0; j < 4; ++j) { g[8 * h + j] = acc[ai][0][m][0][j] * rs; g[8 * h + 4 + j] = acc[ai][0][m][1][j] * rs; uu[8 * h + j] = acc[ai][1][m][0][j] * rs; uu[8 * h + 4 + j] = acc[ai][1][m][1][j] * rs; }
;                 }
;                 __builtin_amdgcn_sched_barrier(0);
; #pragma unroll
;                 for (int i = 0; i < 16; ++i) e[i] = ::fexp2(-LOG2E * g[i]);
;                 __builtin_amdgcn_sched_barrier(0);
; #pragma unroll
;                 for (int i = 0; i < 16; ++i) e[i] = ::frcp(1.f + e[i]);
;                 __builtin_amdgcn_sched_barrier(0);
; #pragma unroll
;                 for (int i = 0; i < 16; ++i) g[i] = g[i] * e[i] * uu[i];
; #pragma unroll
;                 for (int h = 0; h < 2; ++h) {
;                     bf16_t* rowp = O + (size_t)(row0 + ai * HALF + (2 * mp + h) * 16) * ldo + col0;
;                     u32x4 w; w.x = ::pk2(g[8 * h + 0], g[8 * h + 1]); w.y = ::pk2(g[8 * h + 2], g[8 * h + 3]); w.z = ::pk2(g[8 * h + 4], g[8 * h + 5]); w.w = ::pk2(g[8 * h + 6], g[8 * h + 7]);
;                     *(u32x4*)rowp = w;
;                 }
	v_pk_mul_f32 v[48:49], v[48:49], v[68:69] op_sel_hi:[1,0]
	v_mul_f32_e32 v66, 0xbfb8aa3b, v64
	v_mul_f32_e32 v67, 0xbfb8aa3b, v65
	v_exp_f32_e32 v66, v66
	v_exp_f32_e32 v67, v67
	v_pk_mul_f32 v[44:45], v[44:45], v[68:69] op_sel_hi:[1,0]
	v_pk_mul_f32 v[46:47], v[46:47], v[68:69] op_sel_hi:[1,0]
	v_add_f32_e32 v66, 1.0, v66
	v_add_f32_e32 v67, 1.0, v67
	v_rcp_f32_e32 v66, v66
	v_rcp_f32_e32 v67, v67
	v_pk_mul_f32 v[40:41], v[40:41], v[68:69] op_sel_hi:[1,0]
	v_pk_mul_f32 v[36:37], v[36:37], v[68:69] op_sel_hi:[1,0]
	v_pk_mul_f32 v[38:39], v[38:39], v[68:69] op_sel_hi:[1,0]
	v_pk_mul_f32 v[64:65], v[64:65], v[66:67]
	s_nop 0
	v_pk_mul_f32 v[62:63], v[62:63], v[64:65]
	v_mul_f32_e32 v64, 0xbfb8aa3b, v56
	v_mul_f32_e32 v65, 0xbfb8aa3b, v57
	v_exp_f32_e32 v64, v64
	v_exp_f32_e32 v65, v65
	v_add_f32_e32 v64, 1.0, v64
	v_add_f32_e32 v65, 1.0, v65
	v_rcp_f32_e32 v64, v64
	v_rcp_f32_e32 v65, v65
	s_nop 0
	v_pk_mul_f32 v[56:57], v[56:57], v[64:65]
	s_nop 0
	v_pk_mul_f32 v[52:53], v[52:53], v[56:57]
	v_pk_mul_f32 v[56:57], v[58:59], v[70:71] op_sel_hi:[1,0]
	s_nop 0
	v_mul_f32_e32 v58, 0xbfb8aa3b, v56
	v_mul_f32_e32 v59, 0xbfb8aa3b, v57
	v_exp_f32_e32 v58, v58
	v_exp_f32_e32 v59, v59
	v_add_f32_e32 v58, 1.0, v58
	v_add_f32_e32 v59, 1.0, v59
	v_rcp_f32_e32 v58, v58
	v_rcp_f32_e32 v59, v59
	s_nop 0
	v_pk_mul_f32 v[56:57], v[56:57], v[58:59]
	s_nop 0
	v_pk_mul_f32 v[54:55], v[54:55], v[56:57]
	v_mul_f32_e32 v56, 0xbfb8aa3b, v48
	v_mul_f32_e32 v57, 0xbfb8aa3b, v49
	v_exp_f32_e32 v56, v56
	v_exp_f32_e32 v57, v57
	v_add_f32_e32 v56, 1.0, v56
	v_add_f32_e32 v57, 1.0, v57
	v_rcp_f32_e32 v56, v56
	v_rcp_f32_e32 v57, v57
	s_nop 0
	v_pk_mul_f32 v[48:49], v[48:49], v[56:57]
	s_nop 0
	v_pk_mul_f32 v[44:45], v[44:45], v[48:49]
	v_pk_mul_f32 v[48:49], v[50:51], v[68:69] op_sel_hi:[1,0]
	s_nop 0
	v_mul_f32_e32 v50, 0xbfb8aa3b, v48
	v_mul_f32_e32 v51, 0xbfb8aa3b, v49
	v_exp_f32_e32 v50, v50
	v_exp_f32_e32 v51, v51
	v_add_f32_e32 v50, 1.0, v50
	v_add_f32_e32 v51, 1.0, v51
	v_rcp_f32_e32 v50, v50
	v_rcp_f32_e32 v51, v51
	s_nop 0
	v_pk_mul_f32 v[48:49], v[48:49], v[50:51]
	s_nop 0
	v_pk_mul_f32 v[46:47], v[46:47], v[48:49]
	v_mul_f32_e32 v48, 0xbfb8aa3b, v40
	v_mul_f32_e32 v49, 0xbfb8aa3b, v41
	v_exp_f32_e32 v48, v48
	v_exp_f32_e32 v49, v49
	v_add_f32_e32 v48, 1.0, v48
	v_add_f32_e32 v49, 1.0, v49
	v_rcp_f32_e32 v48, v48
	v_rcp_f32_e32 v49, v49
	s_nop 0
	v_pk_mul_f32 v[40:41], v[40:41], v[48:49]
	s_nop 0
	v_pk_mul_f32 v[40:41], v[36:37], v[40:41]
	v_pk_mul_f32 v[36:37], v[42:43], v[68:69] op_sel_hi:[1,0]
	s_nop 0
	v_mul_f32_e32 v42, 0xbfb8aa3b, v36
	v_mul_f32_e32 v43, 0xbfb8aa3b, v37
	v_exp_f32_e32 v42, v42
	v_exp_f32_e32 v43, v43
	v_add_f32_e32 v42, 1.0, v42
	v_add_f32_e32 v43, 1.0, v43
	v_rcp_f32_e32 v42, v42
	v_rcp_f32_e32 v43, v43
	s_nop 0
	v_pk_mul_f32 v[36:37], v[36:37], v[42:43]
	s_nop 0
	v_pk_mul_f32 v[42:43], v[38:39], v[36:37]
	v_mad_i64_i32 v[36:37], s[64:65], v157, s97, v[100:101]
	v_lshl_add_u64 v[48:49], v[36:37], 0, v[102:103]
	v_cvt_pk_bf16_f32 v36, v60, v61
	v_cvt_pk_bf16_f32 v37, v62, v63
	v_cvt_pk_bf16_f32 v38, v52, v53
	v_cvt_pk_bf16_f32 v39, v54, v55
	global_store_dwordx4 v[48:49], v[36:39], off sc1
	s_nop 1
	v_mad_i64_i32 v[36:37], s[64:65], v155, s97, v[100:101]
	v_lshl_add_u64 v[48:49], v[36:37], 0, v[102:103]
	v_cvt_pk_bf16_f32 v36, v44, v45
	v_cvt_pk_bf16_f32 v37, v46, v47
	v_cvt_pk_bf16_f32 v38, v40, v41
	v_cvt_pk_bf16_f32 v39, v42, v43
	global_store_dwordx4 v[48:49], v[36:39], off sc1
	s_nop 1
	v_fmamk_f32 v36, v154, 0x3a800000, v175
	v_rsq_f32_e32 v38, v36
	v_fmamk_f32 v36, v156, 0x3a800000, v175
	v_rsq_f32_e32 v36, v36
	v_pk_mul_f32 v[32:33], v[32:33], v[38:39] op_sel_hi:[1,0]
	v_pk_mul_f32 v[28:29], v[28:29], v[38:39] op_sel_hi:[1,0]
	v_mul_f32_e32 v37, 0xbfb8aa3b, v32
	v_exp_f32_e32 v37, v37
	v_mul_f32_e32 v39, 0xbfb8aa3b, v33
	v_exp_f32_e32 v39, v39
	s_mov_b64 s[72:73], -1
	v_add_f32_e32 v37, 1.0, v37
	v_rcp_f32_e32 v40, v37
	v_add_f32_e32 v37, 1.0, v39
	v_rcp_f32_e32 v41, v37
; __device__ __forceinline__ unsigned pk2(float lo, float hi) { f32x2 v = {lo, hi}; bf16x2_t b = __builtin_convertvector(v, bf16x2_t); return __builtin_bit_cast(unsigned, b); }
; __device__ __forceinline__ float fexp2(float x) { return __builtin_amdgcn_exp2f(x); }
; __device__ __forceinline__ float frcp(float x) { return __builtin_amdgcn_rcpf(x); }
;     __device__ __forceinline__ void operator()(const f32x4 (&acc)[2][2][4][2], const Unit& u, int wr, int wc, int fr, int fq) const {
;     ...
;                     const float rs = __builtin_amdgcn_rsqf(rsv[ai][m] * (1.f / 1024.f) + 1e-6f);
; #pragma unroll
;                     for (int j = 0; j < 4; ++j) { g[8 * h + j] = acc[ai][0][m][0][j] * rs; g[8 * h + 4 + j] = acc[ai][0][m][1][j] * rs; uu[8 * h + j] = acc[ai][1][m][0][j] * rs; uu[8 * h + 4 + j] = acc[ai][1][m][1][j] * rs; }
;                 }
;                 __builtin_amdgcn_sched_barrier(0);
; #pragma unroll
;                 for (int i = 0; i < 16; ++i) e[i] = ::fexp2(-LOG2E * g[i]);
;                 __builtin_amdgcn_sched_barrier(0);
; #pragma unroll
;                 for (int i = 0; i < 16; ++i) e[i] = ::frcp(1.f + e[i]);
;                 __builtin_amdgcn_sched_barrier(0);
; #pragma unroll
;                 for (int i = 0; i < 16; ++i) g[i] = g[i] * e[i] * uu[i];
; #pragma unroll
;                 for (int h = 0; h < 2; ++h) {
;                     bf16_t* rowp = O + (size_t)(row0 + ai * HALF + (2 * mp + h) * 16) * ldo + col0;
;                     u32x4 w; w.x = ::pk2(g[8 * h + 0], g[8 * h + 1]); w.y = ::pk2(g[8 * h + 2], g[8 * h + 3]); w.z = ::pk2(g[8 * h + 4], g[8 * h + 5]); w.w = ::pk2(g[8 * h + 6], g[8 * h + 7]);
;                     *(u32x4*)rowp = w;
;                 }
	v_pk_mul_f32 v[30:31], v[30:31], v[38:39] op_sel_hi:[1,0]
	v_pk_mul_f32 v[24:25], v[24:25], v[38:39] op_sel_hi:[1,0]
	v_pk_mul_f32 v[20:21], v[20:21], v[38:39] op_sel_hi:[1,0]
	v_pk_mul_f32 v[32:33], v[32:33], v[40:41]
	v_pk_mul_f32 v[22:23], v[22:23], v[38:39] op_sel_hi:[1,0]
	v_pk_mul_f32 v[28:29], v[28:29], v[32:33]
	v_pk_mul_f32 v[32:33], v[34:35], v[38:39] op_sel_hi:[1,0]
	v_pk_mul_f32 v[16:17], v[16:17], v[36:37] op_sel_hi:[1,0]
	v_mul_f32_e32 v34, 0xbfb8aa3b, v32
	v_mul_f32_e32 v35, 0xbfb8aa3b, v33
	v_exp_f32_e32 v34, v34
	v_exp_f32_e32 v35, v35
	v_pk_mul_f32 v[12:13], v[12:13], v[36:37] op_sel_hi:[1,0]
	v_pk_mul_f32 v[14:15], v[14:15], v[36:37] op_sel_hi:[1,0]
	v_add_f32_e32 v34, 1.0, v34
	v_add_f32_e32 v35, 1.0, v35
	v_rcp_f32_e32 v34, v34
	v_rcp_f32_e32 v35, v35
	v_pk_mul_f32 v[8:9], v[8:9], v[36:37] op_sel_hi:[1,0]
	v_pk_mul_f32 v[4:5], v[4:5], v[36:37] op_sel_hi:[1,0]
	v_pk_mul_f32 v[6:7], v[6:7], v[36:37] op_sel_hi:[1,0]
	v_pk_mul_f32 v[32:33], v[32:33], v[34:35]
	s_andn2_b64 vcc, exec, s[40:41]
	v_pk_mul_f32 v[30:31], v[30:31], v[32:33]
	v_mul_f32_e32 v32, 0xbfb8aa3b, v24
	v_mul_f32_e32 v33, 0xbfb8aa3b, v25
	v_exp_f32_e32 v32, v32
	v_exp_f32_e32 v33, v33
	v_add_f32_e32 v32, 1.0, v32
	v_add_f32_e32 v33, 1.0, v33
	v_rcp_f32_e32 v32, v32
	v_rcp_f32_e32 v33, v33
	s_nop 0
	v_pk_mul_f32 v[24:25], v[24:25], v[32:33]
	s_nop 0
	v_pk_mul_f32 v[20:21], v[20:21], v[24:25]
	v_pk_mul_f32 v[24:25], v[26:27], v[38:39] op_sel_hi:[1,0]
	s_nop 0
	v_mul_f32_e32 v26, 0xbfb8aa3b, v24
	v_mul_f32_e32 v27, 0xbfb8aa3b, v25
	v_exp_f32_e32 v26, v26
	v_exp_f32_e32 v27, v27
	v_add_f32_e32 v26, 1.0, v26
	v_add_f32_e32 v27, 1.0, v27
	v_rcp_f32_e32 v26, v26
	v_rcp_f32_e32 v27, v27
	s_nop 0
	v_pk_mul_f32 v[24:25], v[24:25], v[26:27]
	s_nop 0
	v_pk_mul_f32 v[22:23], v[22:23], v[24:25]
	v_mul_f32_e32 v24, 0xbfb8aa3b, v16
	v_mul_f32_e32 v25, 0xbfb8aa3b, v17
	v_exp_f32_e32 v24, v24
	v_exp_f32_e32 v25, v25
	v_add_f32_e32 v24, 1.0, v24
	v_add_f32_e32 v25, 1.0, v25
	v_rcp_f32_e32 v24, v24
	v_rcp_f32_e32 v25, v25
	s_nop 0
	v_pk_mul_f32 v[16:17], v[16:17], v[24:25]
	s_nop 0
	v_pk_mul_f32 v[12:13], v[12:13], v[16:17]
	v_pk_mul_f32 v[16:17], v[18:19], v[36:37] op_sel_hi:[1,0]
	s_nop 0
	v_mul_f32_e32 v18, 0xbfb8aa3b, v16
	v_mul_f32_e32 v19, 0xbfb8aa3b, v17
	v_exp_f32_e32 v18, v18
	v_exp_f32_e32 v19, v19
	v_add_f32_e32 v18, 1.0, v18
	v_add_f32_e32 v19, 1.0, v19
	v_rcp_f32_e32 v18, v18
	v_rcp_f32_e32 v19, v19
	s_nop 0
	v_pk_mul_f32 v[16:17], v[16:17], v[18:19]
	s_nop 0
	v_pk_mul_f32 v[14:15], v[14:15], v[16:17]
	v_mul_f32_e32 v16, 0xbfb8aa3b, v8
	v_mul_f32_e32 v17, 0xbfb8aa3b, v9
	v_exp_f32_e32 v16, v16
	v_exp_f32_e32 v17, v17
	v_add_f32_e32 v16, 1.0, v16
	v_add_f32_e32 v17, 1.0, v17
	v_rcp_f32_e32 v16, v16
	v_rcp_f32_e32 v17, v17
	s_nop 0
	v_pk_mul_f32 v[8:9], v[8:9], v[16:17]
	s_nop 0
	v_pk_mul_f32 v[8:9], v[4:5], v[8:9]
	v_pk_mul_f32 v[4:5], v[10:11], v[36:37] op_sel_hi:[1,0]
	s_nop 0
	v_mul_f32_e32 v10, 0xbfb8aa3b, v4
	v_mul_f32_e32 v11, 0xbfb8aa3b, v5
	v_exp_f32_e32 v10, v10
	v_exp_f32_e32 v11, v11
	v_add_f32_e32 v10, 1.0, v10
	v_add_f32_e32 v11, 1.0, v11
	v_rcp_f32_e32 v10, v10
	v_rcp_f32_e32 v11, v11
	s_nop 0
	v_pk_mul_f32 v[4:5], v[4:5], v[10:11]
	s_nop 0
	v_pk_mul_f32 v[10:11], v[6:7], v[4:5]
	v_mad_i64_i32 v[4:5], s[64:65], v147, s97, v[100:101]
	v_lshl_add_u64 v[16:17], v[4:5], 0, v[102:103]
	v_cvt_pk_bf16_f32 v4, v28, v29
	v_cvt_pk_bf16_f32 v5, v30, v31
	v_cvt_pk_bf16_f32 v6, v20, v21
	v_cvt_pk_bf16_f32 v7, v22, v23
	global_store_dwordx4 v[16:17], v[4:7], off sc1
	s_nop 1
	v_add_u32_e32 v4, 0xb0, v146
	v_mad_i64_i32 v[4:5], s[64:65], v4, s97, v[100:101]
	v_lshl_add_u64 v[16:17], v[4:5], 0, v[102:103]
	v_cvt_pk_bf16_f32 v4, v12, v13
	v_cvt_pk_bf16_f32 v5, v14, v15
	v_cvt_pk_bf16_f32 v6, v8, v9
	v_cvt_pk_bf16_f32 v7, v10, v11
	global_store_dwordx4 v[16:17], v[4:7], off sc1
	s_cbranch_vccnz .LBB0_65
	s_andn2_b64 vcc, exec, s[42:43]
	s_cbranch_vccnz .LBB0_64
	s_barrier
	s_branch .LBB0_64

; __device__ __forceinline__ unsigned pk2(float lo, float hi) { f32x2 v = {lo, hi}; bf16x2_t b = __builtin_convertvector(v, bf16x2_t); return __builtin_bit_cast(unsigned, b); }
; __device__ __forceinline__ float bflo(unsigned w) { return __uint_as_float(w << 16); }
; __device__ __forceinline__ float bfhi(unsigned w) { return __uint_as_float(w & 0xffff0000u); }
;     __device__ __forceinline__ void operator()(const f32x4 (&acc)[2][2][4][2], const Unit& u, int wr, int wc, int fr, int fq) const {
;         const int row0 = u.pm * BM + wr * 64 + fr, col0 = u.pn * BM + wc * 32 + 8 * fq;
;         const float* const Rf = this->Rf; bf16_t* const X = this->X; const float scale = this->half_ ? 0.5f : 1.0f; unsigned* const RS = this->RS;
;         f32x4 rv[2][2], rn[2][2];
;         float ssv[8];
;     ...
;         EPIRES_LOAD(rv, (size_t)row0 * 1024 + col0);
; #pragma unroll
;         for (int b = 0; b < 8; ++b) {
;             const int ai = b >> 2, m = b & 3;
;             const size_t off = (size_t)(row0 + ai * HALF + m * 16) * 1024 + col0;
;             if (b < 7) EPIRES_LOAD(rn, (size_t)(row0 + ((b + 1) >> 2) * HALF + ((b + 1) & 3) * 16) * 1024 + col0);
;             float ss = 0.f;
; #pragma unroll
;             for (int bj = 0; bj < 2; ++bj) {
;                 const f32x4 o0 = rv[bj][0] + acc[ai][bj][m][0] * scale, o1 = rv[bj][1] + acc[ai][bj][m][1] * scale;
;                 u32x4 w; w.x = ::pk2(o0[0], o0[1]); w.y = ::pk2(o0[2], o0[3]); w.z = ::pk2(o1[0], o1[1]); w.w = ::pk2(o1[2], o1[3]);
;                 *(u32x4*)(X + off + bj * HALF) = w;
;                 const float q0 = ::bflo(w.x), q1 = ::bfhi(w.x), q2 = ::bflo(w.y), q3 = ::bfhi(w.y), q4 = ::bflo(w.z), q5 = ::bfhi(w.z), q6 = ::bflo(w.w), q7 = ::bfhi(w.w);
;                 ss += ((q0 * q0 + q1 * q1) + (q2 * q2 + q3 * q3)) + ((q4 * q4 + q5 * q5) + (q6 * q6 + q7 * q7));
.LBB0_105:
	v_lshl_add_u32 v146, s82, 8, v3
	v_lshl_or_b32 v140, s14, 8, v189
	v_ashrrev_i32_e32 v147, 31, v146
	v_ashrrev_i32_e32 v141, 31, v140
	v_lshlrev_b64 v[152:153], 11, v[146:147]
	v_lshl_add_u64 v[148:149], s[50:51], 0, v[152:153]
	v_lshlrev_b64 v[150:151], 1, v[140:141]
	v_lshl_add_u64 v[140:141], v[148:149], 0, v[150:151]
	global_load_dwordx4 v[154:157], v[140:141], off
	v_lshl_add_u64 v[148:149], s[50:51], 0, v[150:151]
	v_lshl_add_u64 v[202:203], v[148:149], 0, v[152:153]
	s_mov_b64 s[14:15], 0x40000
	s_waitcnt vmcnt(0)
	v_lshlrev_b32_e32 v184, 16, v154
	v_and_b32_e32 v185, 0xffff0000, v154
	v_lshlrev_b32_e32 v192, 16, v155
	v_and_b32_e32 v193, 0xffff0000, v155
	v_lshlrev_b32_e32 v194, 16, v156
	v_and_b32_e32 v195, 0xffff0000, v156
	v_lshlrev_b32_e32 v196, 16, v157
	v_and_b32_e32 v197, 0xffff0000, v157
	global_load_dwordx4 v[154:157], v[140:141], off offset:256
	v_pk_add_f32 v[130:131], v[130:131], v[192:193]
	v_pk_add_f32 v[128:129], v[128:129], v[184:185]
	v_pk_add_f32 v[184:185], v[126:127], v[196:197]
	v_pk_add_f32 v[126:127], v[124:125], v[194:195]
	v_cvt_pk_bf16_f32 v124, v128, v129
	v_cvt_pk_bf16_f32 v125, v130, v131
	v_cvt_pk_bf16_f32 v126, v126, v127
	v_cvt_pk_bf16_f32 v127, v184, v185
	global_store_dwordx4 v[202:203], v[124:127], off sc1
	v_lshlrev_b32_e32 v128, 16, v124
	v_lshlrev_b32_e32 v129, 16, v125
	v_and_b32_e32 v124, 0xffff0000, v124
	v_and_b32_e32 v125, 0xffff0000, v125
	v_lshlrev_b32_e32 v130, 16, v126
	v_and_b32_e32 v126, 0xffff0000, v126
	v_lshlrev_b32_e32 v131, 16, v127
	v_and_b32_e32 v127, 0xffff0000, v127
	v_mul_f32_e32 v184, v124, v124
	v_mul_f32_e32 v185, v125, v125
	v_mul_f32_e32 v124, v126, v126
	v_mul_f32_e32 v125, v127, v127
	v_fmac_f32_e32 v124, v130, v130
	v_fmac_f32_e32 v125, v131, v131
	v_add_f32_e32 v126, v124, v125
	v_fmac_f32_e32 v185, v129, v129
	v_fmac_f32_e32 v184, v128, v128
	s_waitcnt vmcnt(1)
	v_lshlrev_b32_e32 v198, 16, v156
	v_and_b32_e32 v199, 0xffff0000, v156
	v_or_b32_e32 v156, 16, v146
	v_lshlrev_b32_e32 v200, 16, v157
	v_and_b32_e32 v201, 0xffff0000, v157
	v_ashrrev_i32_e32 v157, 31, v156
	v_lshlrev_b64 v[156:157], 11, v[156:157]
	v_lshl_add_u64 v[158:159], s[50:51], 0, v[156:157]
	v_lshl_add_u64 v[166:167], v[158:159], 0, v[150:151]
	global_load_dwordx4 v[162:165], v[166:167], off
	global_load_dwordx4 v[170:173], v[166:167], off offset:256
	v_lshlrev_b32_e32 v140, 16, v154
	v_and_b32_e32 v141, 0xffff0000, v154
	v_lshlrev_b32_e32 v154, 16, v155
	v_and_b32_e32 v155, 0xffff0000, v155
	v_pk_add_f32 v[122:123], v[122:123], v[154:155]
	v_pk_add_f32 v[120:121], v[120:121], v[140:141]
	v_pk_add_f32 v[124:125], v[118:119], v[200:201]
	v_pk_add_f32 v[118:119], v[116:117], v[198:199]
	v_cvt_pk_bf16_f32 v116, v120, v121
	v_cvt_pk_bf16_f32 v117, v122, v123
	v_cvt_pk_bf16_f32 v118, v118, v119
	v_cvt_pk_bf16_f32 v119, v124, v125
	global_store_dwordx4 v[202:203], v[116:119], off offset:256 sc1
	v_lshlrev_b32_e32 v120, 16, v116
	v_lshlrev_b32_e32 v121, 16, v117
	v_and_b32_e32 v116, 0xffff0000, v116
	v_and_b32_e32 v117, 0xffff0000, v117
	v_mul_f32_e32 v116, v116, v116
	v_mul_f32_e32 v117, v117, v117
	v_lshlrev_b32_e32 v122, 16, v118
	v_and_b32_e32 v118, 0xffff0000, v118
	v_lshlrev_b32_e32 v123, 16, v119
	v_and_b32_e32 v119, 0xffff0000, v119
	v_fmac_f32_e32 v116, v120, v120
	v_fmac_f32_e32 v117, v121, v121
	v_add_f32_e32 v116, v116, v117
	v_mul_f32_e32 v117, v118, v118
	v_mul_f32_e32 v118, v119, v119
	v_fmac_f32_e32 v117, v122, v122
	v_fmac_f32_e32 v118, v123, v123
	v_add_f32_e32 v117, v117, v118
	v_add_f32_e32 v116, v117, v116
	v_add_f32_e32 v117, v184, v185
	v_add_f32_e32 v117, v126, v117
	v_add_f32_e32 v191, v117, v116
	v_or_b32_e32 v116, 32, v146
	v_ashrrev_i32_e32 v117, 31, v116
	v_lshlrev_b64 v[116:117], 11, v[116:117]
	v_lshl_add_u64 v[140:141], v[148:149], 0, v[156:157]
	v_lshl_add_u64 v[118:119], s[50:51], 0, v[116:117]
	v_lshl_add_u64 v[126:127], v[118:119], 0, v[150:151]
	global_load_dwordx4 v[122:125], v[126:127], off
	global_load_dwordx4 v[192:195], v[126:127], off offset:256
	v_lshl_add_u64 v[116:117], v[148:149], 0, v[116:117]
	s_waitcnt vmcnt(4)
	v_lshlrev_b32_e32 v158, 16, v162
	v_and_b32_e32 v159, 0xffff0000, v162
	v_lshlrev_b32_e32 v162, 16, v163
	v_and_b32_e32 v163, 0xffff0000, v163
	v_lshlrev_b32_e32 v160, 16, v164
	v_and_b32_e32 v161, 0xffff0000, v164
	v_lshlrev_b32_e32 v164, 16, v165
	v_and_b32_e32 v165, 0xffff0000, v165
	v_pk_add_f32 v[114:115], v[114:115], v[162:163]
	v_pk_add_f32 v[112:113], v[112:113], v[158:159]
	v_pk_add_f32 v[156:157], v[110:111], v[164:165]
	v_pk_add_f32 v[110:111], v[108:109], v[160:161]
	v_cvt_pk_bf16_f32 v108, v112, v113
	v_cvt_pk_bf16_f32 v109, v114, v115
	v_cvt_pk_bf16_f32 v110, v110, v111
	v_cvt_pk_bf16_f32 v111, v156, v157
	global_store_dwordx4 v[140:141], v[108:111], off sc1
	v_lshlrev_b32_e32 v112, 16, v108
	v_lshlrev_b32_e32 v113, 16, v109
	v_and_b32_e32 v108, 0xffff0000, v108
	v_and_b32_e32 v109, 0xffff0000, v109
	v_lshlrev_b32_e32 v114, 16, v110
	v_and_b32_e32 v110, 0xffff0000, v110
	v_lshlrev_b32_e32 v115, 16, v111
	v_and_b32_e32 v111, 0xffff0000, v111
	v_mul_f32_e32 v156, v108, v108
	v_mul_f32_e32 v157, v109, v109
	v_mul_f32_e32 v108, v110, v110
	v_mul_f32_e32 v109, v111, v111
	s_waitcnt vmcnt(4)
; __device__ __forceinline__ unsigned pk2(float lo, float hi) { f32x2 v = {lo, hi}; bf16x2_t b = __builtin_convertvector(v, bf16x2_t); return __builtin_bit_cast(unsigned, b); }
; __device__ __forceinline__ float bflo(unsigned w) { return __uint_as_float(w << 16); }
; __device__ __forceinline__ float bfhi(unsigned w) { return __uint_as_float(w & 0xffff0000u); }
;     __device__ __forceinline__ void operator()(const f32x4 (&acc)[2][2][4][2], const Unit& u, int wr, int wc, int fr, int fq) const {
;     ...
;         EPIRES_LOAD(rv, (size_t)row0 * 1024 + col0);
; #pragma unroll
;         for (int b = 0; b < 8; ++b) {
;             const int ai = b >> 2, m = b & 3;
;             const size_t off = (size_t)(row0 + ai * HALF + m * 16) * 1024 + col0;
;             if (b < 7) EPIRES_LOAD(rn, (size_t)(row0 + ((b + 1) >> 2) * HALF + ((b + 1) & 3) * 16) * 1024 + col0);
;             float ss = 0.f;
; #pragma unroll
;             for (int bj = 0; bj < 2; ++bj) {
;                 const f32x4 o0 = rv[bj][0] + acc[ai][bj][m][0] * scale, o1 = rv[bj][1] + acc[ai][bj][m][1] * scale;
;                 u32x4 w; w.x = ::pk2(o0[0], o0[1]); w.y = ::pk2(o0[2], o0[3]); w.z = ::pk2(o1[0], o1[1]); w.w = ::pk2(o1[2], o1[3]);
;                 *(u32x4*)(X + off + bj * HALF) = w;
;                 const float q0 = ::bflo(w.x), q1 = ::bfhi(w.x), q2 = ::bflo(w.y), q3 = ::bfhi(w.y), q4 = ::bflo(w.z), q5 = ::bfhi(w.z), q6 = ::bflo(w.w), q7 = ::bfhi(w.w);
;                 ss += ((q0 * q0 + q1 * q1) + (q2 * q2 + q3 * q3)) + ((q4 * q4 + q5 * q5) + (q6 * q6 + q7 * q7));
;             }
;             ssv[b] = ss;
	v_lshlrev_b32_e32 v166, 16, v170
	v_and_b32_e32 v167, 0xffff0000, v170
	v_lshlrev_b32_e32 v170, 16, v171
	v_and_b32_e32 v171, 0xffff0000, v171
	v_lshlrev_b32_e32 v168, 16, v172
	v_and_b32_e32 v169, 0xffff0000, v172
	v_lshlrev_b32_e32 v172, 16, v173
	v_and_b32_e32 v173, 0xffff0000, v173
	v_fmac_f32_e32 v108, v114, v114
	v_fmac_f32_e32 v109, v115, v115
	v_add_f32_e32 v110, v108, v109
	v_pk_add_f32 v[106:107], v[106:107], v[170:171]
	v_pk_add_f32 v[104:105], v[104:105], v[166:167]
	v_pk_add_f32 v[108:109], v[102:103], v[172:173]
	v_pk_add_f32 v[102:103], v[100:101], v[168:169]
	v_cvt_pk_bf16_f32 v100, v104, v105
	v_cvt_pk_bf16_f32 v101, v106, v107
	v_cvt_pk_bf16_f32 v102, v102, v103
	v_cvt_pk_bf16_f32 v103, v108, v109
	global_store_dwordx4 v[140:141], v[100:103], off offset:256 sc1
	v_lshlrev_b32_e32 v104, 16, v100
	v_lshlrev_b32_e32 v105, 16, v101
	v_and_b32_e32 v100, 0xffff0000, v100
	v_and_b32_e32 v101, 0xffff0000, v101
	v_mul_f32_e32 v100, v100, v100
	v_mul_f32_e32 v101, v101, v101
	v_lshlrev_b32_e32 v106, 16, v102
	v_and_b32_e32 v102, 0xffff0000, v102
	v_lshlrev_b32_e32 v107, 16, v103
	v_and_b32_e32 v103, 0xffff0000, v103
	v_fmac_f32_e32 v100, v104, v104
	v_fmac_f32_e32 v101, v105, v105
	v_add_f32_e32 v100, v100, v101
	v_mul_f32_e32 v101, v102, v102
	v_mul_f32_e32 v102, v103, v103
	v_fmac_f32_e32 v101, v106, v106
	v_fmac_f32_e32 v102, v107, v107
	v_fmac_f32_e32 v157, v113, v113
	v_add_f32_e32 v101, v101, v102
	v_fmac_f32_e32 v156, v112, v112
	v_add_f32_e32 v100, v101, v100
	v_add_f32_e32 v101, v156, v157
	v_add_f32_e32 v101, v110, v101
	v_add_f32_e32 v158, v101, v100
	v_or_b32_e32 v100, 48, v146
	v_ashrrev_i32_e32 v101, 31, v100
	v_lshlrev_b64 v[100:101], 11, v[100:101]
	v_lshl_add_u64 v[102:103], s[50:51], 0, v[100:101]
	v_lshl_add_u64 v[110:111], v[102:103], 0, v[150:151]
	global_load_dwordx4 v[106:109], v[110:111], off
	global_load_dwordx4 v[160:163], v[110:111], off offset:256
	s_waitcnt vmcnt(5)
	v_lshlrev_b32_e32 v118, 16, v122
	v_and_b32_e32 v119, 0xffff0000, v122
	v_lshlrev_b32_e32 v122, 16, v123
	v_and_b32_e32 v123, 0xffff0000, v123
	v_lshlrev_b32_e32 v120, 16, v124
	v_and_b32_e32 v121, 0xffff0000, v124
	v_lshlrev_b32_e32 v124, 16, v125
	v_and_b32_e32 v125, 0xffff0000, v125
	v_pk_add_f32 v[98:99], v[98:99], v[122:123]
	v_pk_add_f32 v[96:97], v[96:97], v[118:119]
	v_pk_add_f32 v[118:119], v[94:95], v[124:125]
	v_pk_add_f32 v[94:95], v[92:93], v[120:121]
	v_cvt_pk_bf16_f32 v92, v96, v97
	v_cvt_pk_bf16_f32 v93, v98, v99
	v_cvt_pk_bf16_f32 v94, v94, v95
	v_cvt_pk_bf16_f32 v95, v118, v119
	global_store_dwordx4 v[116:117], v[92:95], off sc1
	v_lshlrev_b32_e32 v96, 16, v92
	v_lshlrev_b32_e32 v97, 16, v93
	v_and_b32_e32 v92, 0xffff0000, v92
	v_and_b32_e32 v93, 0xffff0000, v93
	v_lshlrev_b32_e32 v98, 16, v94
	v_and_b32_e32 v94, 0xffff0000, v94
	v_lshlrev_b32_e32 v99, 16, v95
	v_and_b32_e32 v95, 0xffff0000, v95
	v_mul_f32_e32 v118, v92, v92
	v_mul_f32_e32 v119, v93, v93
	v_mul_f32_e32 v92, v94, v94
	v_mul_f32_e32 v93, v95, v95
	s_waitcnt vmcnt(5)
	v_lshlrev_b32_e32 v126, 16, v192
	v_and_b32_e32 v127, 0xffff0000, v192
	v_lshlrev_b32_e32 v130, 16, v193
	v_and_b32_e32 v131, 0xffff0000, v193
	v_lshlrev_b32_e32 v128, 16, v194
	v_and_b32_e32 v129, 0xffff0000, v194
	v_lshlrev_b32_e32 v154, 16, v195
	v_and_b32_e32 v155, 0xffff0000, v195
	v_fmac_f32_e32 v92, v98, v98
	v_fmac_f32_e32 v93, v99, v99
	v_add_f32_e32 v94, v92, v93
	v_pk_add_f32 v[90:91], v[90:91], v[130:131]
	v_pk_add_f32 v[88:89], v[88:89], v[126:127]
	v_pk_add_f32 v[92:93], v[86:87], v[154:155]
	v_pk_add_f32 v[86:87], v[84:85], v[128:129]
	v_cvt_pk_bf16_f32 v84, v88, v89
	v_cvt_pk_bf16_f32 v85, v90, v91
	v_cvt_pk_bf16_f32 v86, v86, v87
	v_cvt_pk_bf16_f32 v87, v92, v93
	global_store_dwordx4 v[116:117], v[84:87], off offset:256 sc1
	v_lshlrev_b32_e32 v88, 16, v84
	v_lshlrev_b32_e32 v89, 16, v85
	v_and_b32_e32 v84, 0xffff0000, v84
	v_and_b32_e32 v85, 0xffff0000, v85
	v_mul_f32_e32 v84, v84, v84
	v_mul_f32_e32 v85, v85, v85
	v_lshlrev_b32_e32 v90, 16, v86
	v_and_b32_e32 v86, 0xffff0000, v86
	v_lshlrev_b32_e32 v91, 16, v87
	v_and_b32_e32 v87, 0xffff0000, v87
	v_fmac_f32_e32 v84, v88, v88
	v_fmac_f32_e32 v85, v89, v89
	v_add_f32_e32 v84, v84, v85
	v_mul_f32_e32 v85, v86, v86
	v_mul_f32_e32 v86, v87, v87
	v_fmac_f32_e32 v85, v90, v90
	v_fmac_f32_e32 v86, v91, v91
	v_fmac_f32_e32 v119, v97, v97
	v_add_f32_e32 v85, v85, v86
	v_fmac_f32_e32 v118, v96, v96
	v_add_f32_e32 v84, v85, v84
	v_add_f32_e32 v85, v118, v119
	v_add_f32_e32 v85, v94, v85
	v_add_f32_e32 v122, v85, v84
	v_lshl_add_u64 v[84:85], v[152:153], 0, s[14:15]
	v_lshl_add_u64 v[86:87], s[50:51], 0, v[84:85]
	v_lshl_add_u64 v[94:95], v[86:87], 0, v[150:151]
	global_load_dwordx4 v[90:93], v[94:95], off
	global_load_dwordx4 v[118:121], v[94:95], off offset:256
	s_waitcnt vmcnt(5)
	v_lshlrev_b32_e32 v102, 16, v106
	v_and_b32_e32 v103, 0xffff0000, v106
	v_lshlrev_b32_e32 v106, 16, v107
	v_and_b32_e32 v107, 0xffff0000, v107
	v_lshlrev_b32_e32 v104, 16, v108
	v_and_b32_e32 v105, 0xffff0000, v108
	v_lshlrev_b32_e32 v108, 16, v109
	v_and_b32_e32 v109, 0xffff0000, v109
	v_pk_add_f32 v[82:83], v[82:83], v[106:107]
	v_pk_add_f32 v[80:81], v[80:81], v[102:103]
	v_pk_add_f32 v[98:99], v[78:79], v[108:109]
	v_pk_add_f32 v[78:79], v[76:77], v[104:105]
	v_lshl_add_u64 v[94:95], v[148:149], 0, v[100:101]
	v_cvt_pk_bf16_f32 v76, v80, v81
	v_cvt_pk_bf16_f32 v77, v82, v83
	v_cvt_pk_bf16_f32 v78, v78, v79
	v_cvt_pk_bf16_f32 v79, v98, v99
	global_store_dwordx4 v[94:95], v[76:79], off sc1
	v_lshlrev_b32_e32 v80, 16, v76
	v_lshlrev_b32_e32 v81, 16, v77
	v_and_b32_e32 v76, 0xffff0000, v76
	v_and_b32_e32 v77, 0xffff0000, v77
	v_lshlrev_b32_e32 v82, 16, v78
	v_and_b32_e32 v78, 0xffff0000, v78
	v_lshlrev_b32_e32 v83, 16, v79
	v_and_b32_e32 v79, 0xffff0000, v79
	v_mul_f32_e32 v98, v76, v76
	v_mul_f32_e32 v99, v77, v77
	v_mul_f32_e32 v76, v78, v78
	v_mul_f32_e32 v77, v79, v79
	s_waitcnt vmcnt(5)
; __device__ __forceinline__ unsigned pk2(float lo, float hi) { f32x2 v = {lo, hi}; bf16x2_t b = __builtin_convertvector(v, bf16x2_t); return __builtin_bit_cast(unsigned, b); }
; __device__ __forceinline__ float bflo(unsigned w) { return __uint_as_float(w << 16); }
; __device__ __forceinline__ float bfhi(unsigned w) { return __uint_as_float(w & 0xffff0000u); }
;     __device__ __forceinline__ void operator()(const f32x4 (&acc)[2][2][4][2], const Unit& u, int wr, int wc, int fr, int fq) const {
;     ...
;         EPIRES_LOAD(rv, (size_t)row0 * 1024 + col0);
; #pragma unroll
;         for (int b = 0; b < 8; ++b) {
;             const int ai = b >> 2, m = b & 3;
;             const size_t off = (size_t)(row0 + ai * HALF + m * 16) * 1024 + col0;
;             if (b < 7) EPIRES_LOAD(rn, (size_t)(row0 + ((b + 1) >> 2) * HALF + ((b + 1) & 3) * 16) * 1024 + col0);
;             float ss = 0.f;
; #pragma unroll
;             for (int bj = 0; bj < 2; ++bj) {
;                 const f32x4 o0 = rv[bj][0] + acc[ai][bj][m][0] * scale, o1 = rv[bj][1] + acc[ai][bj][m][1] * scale;
;                 u32x4 w; w.x = ::pk2(o0[0], o0[1]); w.y = ::pk2(o0[2], o0[3]); w.z = ::pk2(o1[0], o1[1]); w.w = ::pk2(o1[2], o1[3]);
;                 *(u32x4*)(X + off + bj * HALF) = w;
;                 const float q0 = ::bflo(w.x), q1 = ::bfhi(w.x), q2 = ::bflo(w.y), q3 = ::bfhi(w.y), q4 = ::bflo(w.z), q5 = ::bfhi(w.z), q6 = ::bflo(w.w), q7 = ::bfhi(w.w);
;                 ss += ((q0 * q0 + q1 * q1) + (q2 * q2 + q3 * q3)) + ((q4 * q4 + q5 * q5) + (q6 * q6 + q7 * q7));
;             }
;             ssv[b] = ss;
	v_lshlrev_b32_e32 v110, 16, v160
	v_and_b32_e32 v111, 0xffff0000, v160
	v_lshlrev_b32_e32 v114, 16, v161
	v_and_b32_e32 v115, 0xffff0000, v161
	v_lshlrev_b32_e32 v112, 16, v162
	v_and_b32_e32 v113, 0xffff0000, v162
	v_lshlrev_b32_e32 v156, 16, v163
	v_and_b32_e32 v157, 0xffff0000, v163
	v_fmac_f32_e32 v76, v82, v82
	v_fmac_f32_e32 v77, v83, v83
	v_add_f32_e32 v78, v76, v77
	v_pk_add_f32 v[74:75], v[74:75], v[114:115]
	v_pk_add_f32 v[72:73], v[72:73], v[110:111]
	v_pk_add_f32 v[76:77], v[70:71], v[156:157]
	v_pk_add_f32 v[70:71], v[68:69], v[112:113]
	v_cvt_pk_bf16_f32 v68, v72, v73
	v_cvt_pk_bf16_f32 v69, v74, v75
	v_cvt_pk_bf16_f32 v70, v70, v71
	v_cvt_pk_bf16_f32 v71, v76, v77
	global_store_dwordx4 v[94:95], v[68:71], off offset:256 sc1
	v_lshlrev_b32_e32 v72, 16, v68
	v_lshlrev_b32_e32 v73, 16, v69
	v_and_b32_e32 v68, 0xffff0000, v68
	v_and_b32_e32 v69, 0xffff0000, v69
	v_mul_f32_e32 v68, v68, v68
	v_mul_f32_e32 v69, v69, v69
	v_lshlrev_b32_e32 v74, 16, v70
	v_and_b32_e32 v70, 0xffff0000, v70
	v_lshlrev_b32_e32 v75, 16, v71
	v_and_b32_e32 v71, 0xffff0000, v71
	v_fmac_f32_e32 v68, v72, v72
	v_fmac_f32_e32 v69, v73, v73
	v_add_f32_e32 v68, v68, v69
	v_mul_f32_e32 v69, v70, v70
	v_mul_f32_e32 v70, v71, v71
	v_fmac_f32_e32 v69, v74, v74
	v_fmac_f32_e32 v70, v75, v75
	v_fmac_f32_e32 v99, v81, v81
	v_add_f32_e32 v69, v69, v70
	v_fmac_f32_e32 v98, v80, v80
	v_add_f32_e32 v68, v69, v68
	v_add_f32_e32 v69, v98, v99
	v_add_f32_e32 v69, v78, v69
	v_add_f32_e32 v100, v69, v68
	v_add_u32_e32 v68, 0x90, v146
	v_ashrrev_i32_e32 v69, 31, v68
	v_lshlrev_b64 v[70:71], 11, v[68:69]
	v_lshl_add_u64 v[68:69], s[50:51], 0, v[70:71]
	v_lshl_add_u64 v[68:69], v[68:69], 0, v[150:151]
	global_load_dwordx4 v[76:79], v[68:69], off
	global_load_dwordx4 v[102:105], v[68:69], off offset:256
	v_lshl_add_u64 v[70:71], v[148:149], 0, v[70:71]
	s_waitcnt vmcnt(5)
	v_lshlrev_b32_e32 v86, 16, v90
	v_and_b32_e32 v87, 0xffff0000, v90
	v_lshlrev_b32_e32 v90, 16, v91
	v_and_b32_e32 v91, 0xffff0000, v91
	v_lshlrev_b32_e32 v88, 16, v92
	v_and_b32_e32 v89, 0xffff0000, v92
	v_lshlrev_b32_e32 v92, 16, v93
	v_and_b32_e32 v93, 0xffff0000, v93
	v_lshl_add_u64 v[68:69], v[148:149], 0, v[84:85]
	v_pk_add_f32 v[66:67], v[66:67], v[90:91]
	v_pk_add_f32 v[64:65], v[64:65], v[86:87]
	v_pk_add_f32 v[84:85], v[62:63], v[92:93]
	v_pk_add_f32 v[62:63], v[60:61], v[88:89]
	v_cvt_pk_bf16_f32 v60, v64, v65
	v_cvt_pk_bf16_f32 v61, v66, v67
	v_cvt_pk_bf16_f32 v62, v62, v63
	v_cvt_pk_bf16_f32 v63, v84, v85
	global_store_dwordx4 v[68:69], v[60:63], off sc1
	v_lshlrev_b32_e32 v64, 16, v60
	v_lshlrev_b32_e32 v65, 16, v61
	v_and_b32_e32 v60, 0xffff0000, v60
	v_and_b32_e32 v61, 0xffff0000, v61
	v_lshlrev_b32_e32 v66, 16, v62
	v_and_b32_e32 v62, 0xffff0000, v62
	v_lshlrev_b32_e32 v67, 16, v63
	v_and_b32_e32 v63, 0xffff0000, v63
	v_mul_f32_e32 v84, v60, v60
	v_mul_f32_e32 v85, v61, v61
	v_mul_f32_e32 v60, v62, v62
	v_mul_f32_e32 v61, v63, v63
	s_waitcnt vmcnt(5)
	v_lshlrev_b32_e32 v96, 16, v118
	v_and_b32_e32 v97, 0xffff0000, v118
	v_lshlrev_b32_e32 v118, 16, v119
	v_and_b32_e32 v119, 0xffff0000, v119
	v_lshlrev_b32_e32 v116, 16, v120
	v_and_b32_e32 v117, 0xffff0000, v120
	v_lshlrev_b32_e32 v120, 16, v121
	v_and_b32_e32 v121, 0xffff0000, v121
	v_fmac_f32_e32 v60, v66, v66
	v_fmac_f32_e32 v61, v67, v67
	v_add_f32_e32 v62, v60, v61
	v_pk_add_f32 v[58:59], v[58:59], v[118:119]
	v_pk_add_f32 v[56:57], v[56:57], v[96:97]
	v_pk_add_f32 v[60:61], v[54:55], v[120:121]
	v_pk_add_f32 v[54:55], v[52:53], v[116:117]
	v_cvt_pk_bf16_f32 v52, v56, v57
	v_cvt_pk_bf16_f32 v53, v58, v59
	v_cvt_pk_bf16_f32 v54, v54, v55
	v_cvt_pk_bf16_f32 v55, v60, v61
	global_store_dwordx4 v[68:69], v[52:55], off offset:256 sc1
	v_lshlrev_b32_e32 v56, 16, v52
	v_lshlrev_b32_e32 v57, 16, v53
	v_and_b32_e32 v52, 0xffff0000, v52
	v_and_b32_e32 v53, 0xffff0000, v53
	v_mul_f32_e32 v52, v52, v52
	v_mul_f32_e32 v53, v53, v53
	v_lshlrev_b32_e32 v58, 16, v54
	v_and_b32_e32 v54, 0xffff0000, v54
	v_lshlrev_b32_e32 v59, 16, v55
	v_and_b32_e32 v55, 0xffff0000, v55
	v_fmac_f32_e32 v52, v56, v56
	v_fmac_f32_e32 v53, v57, v57
	v_add_f32_e32 v52, v52, v53
	v_mul_f32_e32 v53, v54, v54
	v_mul_f32_e32 v54, v55, v55
	v_fmac_f32_e32 v53, v58, v58
	v_fmac_f32_e32 v54, v59, v59
	v_fmac_f32_e32 v85, v65, v65
	v_add_f32_e32 v53, v53, v54
	v_fmac_f32_e32 v84, v64, v64
	v_add_f32_e32 v52, v53, v52
	v_add_f32_e32 v53, v84, v85
	v_add_f32_e32 v53, v62, v53
	v_add_f32_e32 v84, v53, v52
	v_add_u32_e32 v52, 0xa0, v146
	v_ashrrev_i32_e32 v53, 31, v52
	v_lshlrev_b64 v[58:59], 11, v[52:53]
	s_waitcnt vmcnt(3)
	v_lshlrev_b32_e32 v72, 16, v76
	v_and_b32_e32 v73, 0xffff0000, v76
	v_lshlrev_b32_e32 v76, 16, v77
	v_and_b32_e32 v77, 0xffff0000, v77
	v_lshlrev_b32_e32 v74, 16, v78
	v_and_b32_e32 v75, 0xffff0000, v78
	v_lshlrev_b32_e32 v78, 16, v79
	v_and_b32_e32 v79, 0xffff0000, v79
	v_pk_add_f32 v[50:51], v[50:51], v[76:77]
	v_pk_add_f32 v[48:49], v[48:49], v[72:73]
	v_pk_add_f32 v[72:73], v[46:47], v[78:79]
	v_pk_add_f32 v[46:47], v[44:45], v[74:75]
	v_cvt_pk_bf16_f32 v44, v48, v49
	v_cvt_pk_bf16_f32 v45, v50, v51
	v_cvt_pk_bf16_f32 v46, v46, v47
	v_cvt_pk_bf16_f32 v47, v72, v73
	global_store_dwordx4 v[70:71], v[44:47], off sc1
	v_lshlrev_b32_e32 v48, 16, v44
	v_lshlrev_b32_e32 v49, 16, v45
	v_and_b32_e32 v44, 0xffff0000, v44
	v_and_b32_e32 v45, 0xffff0000, v45
	v_lshlrev_b32_e32 v50, 16, v46
	v_and_b32_e32 v46, 0xffff0000, v46
	v_lshlrev_b32_e32 v51, 16, v47
	v_and_b32_e32 v47, 0xffff0000, v47
	v_mul_f32_e32 v72, v44, v44
	v_mul_f32_e32 v73, v45, v45
	v_mul_f32_e32 v44, v46, v46
	v_mul_f32_e32 v45, v47, v47
	s_waitcnt vmcnt(3)
; __device__ __forceinline__ unsigned pk2(float lo, float hi) { f32x2 v = {lo, hi}; bf16x2_t b = __builtin_convertvector(v, bf16x2_t); return __builtin_bit_cast(unsigned, b); }
; __device__ __forceinline__ float bflo(unsigned w) { return __uint_as_float(w << 16); }
; __device__ __forceinline__ float bfhi(unsigned w) { return __uint_as_float(w & 0xffff0000u); }
;     __device__ __forceinline__ void operator()(const f32x4 (&acc)[2][2][4][2], const Unit& u, int wr, int wc, int fr, int fq) const {
;     ...
;         EPIRES_LOAD(rv, (size_t)row0 * 1024 + col0);
; #pragma unroll
;         for (int b = 0; b < 8; ++b) {
;             const int ai = b >> 2, m = b & 3;
;             const size_t off = (size_t)(row0 + ai * HALF + m * 16) * 1024 + col0;
;             if (b < 7) EPIRES_LOAD(rn, (size_t)(row0 + ((b + 1) >> 2) * HALF + ((b + 1) & 3) * 16) * 1024 + col0);
;             float ss = 0.f;
; #pragma unroll
;             for (int bj = 0; bj < 2; ++bj) {
;                 const f32x4 o0 = rv[bj][0] + acc[ai][bj][m][0] * scale, o1 = rv[bj][1] + acc[ai][bj][m][1] * scale;
;                 u32x4 w; w.x = ::pk2(o0[0], o0[1]); w.y = ::pk2(o0[2], o0[3]); w.z = ::pk2(o1[0], o1[1]); w.w = ::pk2(o1[2], o1[3]);
;                 *(u32x4*)(X + off + bj * HALF) = w;
;                 const float q0 = ::bflo(w.x), q1 = ::bfhi(w.x), q2 = ::bflo(w.y), q3 = ::bfhi(w.y), q4 = ::bflo(w.z), q5 = ::bfhi(w.z), q6 = ::bflo(w.w), q7 = ::bfhi(w.w);
;                 ss += ((q0 * q0 + q1 * q1) + (q2 * q2 + q3 * q3)) + ((q4 * q4 + q5 * q5) + (q6 * q6 + q7 * q7));
;             }
;             ssv[b] = ss;
	v_lshlrev_b32_e32 v80, 16, v102
	v_and_b32_e32 v81, 0xffff0000, v102
	v_lshlrev_b32_e32 v94, 16, v103
	v_and_b32_e32 v95, 0xffff0000, v103
	v_lshlrev_b32_e32 v82, 16, v104
	v_and_b32_e32 v83, 0xffff0000, v104
	v_lshlrev_b32_e32 v98, 16, v105
	v_and_b32_e32 v99, 0xffff0000, v105
	v_fmac_f32_e32 v44, v50, v50
	v_fmac_f32_e32 v45, v51, v51
	v_add_f32_e32 v46, v44, v45
	v_pk_add_f32 v[42:43], v[42:43], v[94:95]
	v_pk_add_f32 v[40:41], v[40:41], v[80:81]
	v_pk_add_f32 v[44:45], v[38:39], v[98:99]
	v_pk_add_f32 v[38:39], v[36:37], v[82:83]
	v_cvt_pk_bf16_f32 v36, v40, v41
	v_cvt_pk_bf16_f32 v37, v42, v43
	v_cvt_pk_bf16_f32 v38, v38, v39
	v_cvt_pk_bf16_f32 v39, v44, v45
	global_store_dwordx4 v[70:71], v[36:39], off offset:256 sc1
	v_lshlrev_b32_e32 v40, 16, v36
	v_lshlrev_b32_e32 v41, 16, v37
	v_and_b32_e32 v36, 0xffff0000, v36
	v_and_b32_e32 v37, 0xffff0000, v37
	v_mul_f32_e32 v36, v36, v36
	v_mul_f32_e32 v37, v37, v37
	v_lshlrev_b32_e32 v42, 16, v38
	v_and_b32_e32 v38, 0xffff0000, v38
	v_lshlrev_b32_e32 v43, 16, v39
	v_and_b32_e32 v39, 0xffff0000, v39
	v_fmac_f32_e32 v36, v40, v40
	v_fmac_f32_e32 v37, v41, v41
	v_add_f32_e32 v36, v36, v37
	v_mul_f32_e32 v37, v38, v38
	v_mul_f32_e32 v38, v39, v39
	v_fmac_f32_e32 v37, v42, v42
	v_fmac_f32_e32 v38, v43, v43
	v_fmac_f32_e32 v73, v49, v49
	v_add_f32_e32 v37, v37, v38
	v_fmac_f32_e32 v72, v48, v48
	v_add_f32_e32 v36, v37, v36
	v_add_f32_e32 v37, v72, v73
	v_add_f32_e32 v37, v46, v37
	v_add_f32_e32 v50, v37, v36
	v_add_u32_e32 v36, 0xb0, v146
	v_ashrrev_i32_e32 v37, 31, v36
	v_lshlrev_b64 v[46:47], 11, v[36:37]
	v_lshl_add_u64 v[36:37], s[50:51], 0, v[46:47]
	v_lshl_add_u64 v[70:71], v[36:37], 0, v[150:151]
	global_load_dwordx4 v[36:39], v[70:71], off
	v_lshl_add_u64 v[52:53], s[50:51], 0, v[58:59]
	v_lshl_add_u64 v[64:65], v[52:53], 0, v[150:151]
	global_load_dwordx4 v[60:63], v[64:65], off
	global_load_dwordx4 v[86:89], v[64:65], off offset:256
	v_lshl_add_u64 v[58:59], v[148:149], 0, v[58:59]
	s_waitcnt vmcnt(2)
	v_lshlrev_b32_e32 v42, 16, v36
	v_and_b32_e32 v43, 0xffff0000, v36
	v_lshlrev_b32_e32 v48, 16, v37
	v_and_b32_e32 v49, 0xffff0000, v37
	v_lshlrev_b32_e32 v40, 16, v38
	v_and_b32_e32 v41, 0xffff0000, v38
	v_lshlrev_b32_e32 v44, 16, v39
	v_and_b32_e32 v45, 0xffff0000, v39
	global_load_dwordx4 v[36:39], v[70:71], off offset:256
	s_waitcnt vmcnt(2)
	v_lshlrev_b32_e32 v54, 16, v60
	v_and_b32_e32 v55, 0xffff0000, v60
	v_lshlrev_b32_e32 v60, 16, v61
	v_and_b32_e32 v61, 0xffff0000, v61
	v_lshlrev_b32_e32 v52, 16, v62
	v_and_b32_e32 v53, 0xffff0000, v62
	v_lshlrev_b32_e32 v56, 16, v63
	v_and_b32_e32 v57, 0xffff0000, v63
	s_waitcnt vmcnt(1)
	v_lshlrev_b32_e32 v64, 16, v86
	v_and_b32_e32 v65, 0xffff0000, v86
	v_pk_add_f32 v[32:33], v[32:33], v[54:55]
	v_lshlrev_b32_e32 v68, 16, v87
	v_and_b32_e32 v69, 0xffff0000, v87
	v_lshlrev_b32_e32 v62, 16, v88
	v_and_b32_e32 v63, 0xffff0000, v88
	v_lshlrev_b32_e32 v66, 16, v89
	v_and_b32_e32 v67, 0xffff0000, v89
	v_pk_add_f32 v[34:35], v[34:35], v[60:61]
	v_pk_add_f32 v[54:55], v[30:31], v[56:57]
	v_pk_add_f32 v[30:31], v[28:29], v[52:53]
	v_cvt_pk_bf16_f32 v28, v32, v33
	v_pk_add_f32 v[24:25], v[24:25], v[64:65]
	v_cvt_pk_bf16_f32 v29, v34, v35
	v_pk_add_f32 v[26:27], v[26:27], v[68:69]
	v_pk_add_f32 v[32:33], v[22:23], v[66:67]
	v_pk_add_f32 v[22:23], v[20:21], v[62:63]
	v_cvt_pk_bf16_f32 v20, v24, v25
	v_and_b32_e32 v25, 0xffff0000, v28
	v_cvt_pk_bf16_f32 v21, v26, v27
	v_lshlrev_b32_e32 v24, 16, v28
	v_mul_f32_e32 v25, v25, v25
	v_and_b32_e32 v26, 0xffff0000, v29
	v_fmac_f32_e32 v25, v24, v24
	v_lshlrev_b32_e32 v24, 16, v29
	v_mul_f32_e32 v26, v26, v26
	v_cvt_pk_bf16_f32 v30, v30, v31
	v_fmac_f32_e32 v26, v24, v24
	v_cvt_pk_bf16_f32 v31, v54, v55
	v_add_f32_e32 v24, v25, v26
	v_and_b32_e32 v26, 0xffff0000, v30
	v_lshlrev_b32_e32 v25, 16, v30
	v_mul_f32_e32 v26, v26, v26
	v_and_b32_e32 v27, 0xffff0000, v31
	v_fmac_f32_e32 v26, v25, v25
	v_lshlrev_b32_e32 v25, 16, v31
	v_mul_f32_e32 v27, v27, v27
	v_fmac_f32_e32 v27, v25, v25
	v_cvt_pk_bf16_f32 v22, v22, v23
	v_cvt_pk_bf16_f32 v23, v32, v33
	v_add_f32_e32 v25, v26, v27
	global_store_dwordx4 v[58:59], v[20:23], off offset:256 sc1
	v_add_f32_e32 v24, v25, v24
	v_lshlrev_b32_e32 v25, 16, v20
	v_and_b32_e32 v20, 0xffff0000, v20
	v_mul_f32_e32 v20, v20, v20
	v_fmac_f32_e32 v20, v25, v25
	v_lshlrev_b32_e32 v25, 16, v21
	v_and_b32_e32 v21, 0xffff0000, v21
	v_mul_f32_e32 v21, v21, v21
	v_fmac_f32_e32 v21, v25, v25
	v_add_f32_e32 v20, v20, v21
	v_lshlrev_b32_e32 v21, 16, v22
	v_and_b32_e32 v22, 0xffff0000, v22
	v_mul_f32_e32 v22, v22, v22
	v_fmac_f32_e32 v22, v21, v21
	v_lshlrev_b32_e32 v21, 16, v23
	v_and_b32_e32 v23, 0xffff0000, v23
	v_mul_f32_e32 v23, v23, v23
	v_fmac_f32_e32 v23, v21, v21
	v_add_f32_e32 v21, v22, v23
	v_add_f32_e32 v20, v21, v20
	v_pk_add_f32 v[18:19], v[18:19], v[48:49]
	v_pk_add_f32 v[16:17], v[16:17], v[42:43]
	v_pk_add_f32 v[22:23], v[14:15], v[44:45]
	v_pk_add_f32 v[14:15], v[12:13], v[40:41]
	v_add_f32_e32 v24, v24, v20
	v_lshl_add_u64 v[20:21], v[148:149], 0, v[46:47]
	v_cvt_pk_bf16_f32 v12, v16, v17
	v_cvt_pk_bf16_f32 v13, v18, v19
	v_cvt_pk_bf16_f32 v14, v14, v15
	v_cvt_pk_bf16_f32 v15, v22, v23
	global_store_dwordx4 v[20:21], v[12:15], off sc1
	v_lshlrev_b32_e32 v16, 16, v12
	v_lshlrev_b32_e32 v17, 16, v13
	v_and_b32_e32 v12, 0xffff0000, v12
	v_and_b32_e32 v13, 0xffff0000, v13
	v_lshlrev_b32_e32 v18, 16, v14
	v_and_b32_e32 v14, 0xffff0000, v14
	v_lshlrev_b32_e32 v19, 16, v15
	v_and_b32_e32 v15, 0xffff0000, v15
	v_mul_f32_e32 v22, v12, v12
	v_mul_f32_e32 v23, v13, v13
	v_mul_f32_e32 v12, v14, v14
	v_mul_f32_e32 v13, v15, v15
	s_waitcnt vmcnt(2)
; __device__ __forceinline__ unsigned pk2(float lo, float hi) { f32x2 v = {lo, hi}; bf16x2_t b = __builtin_convertvector(v, bf16x2_t); return __builtin_bit_cast(unsigned, b); }
; __device__ __forceinline__ float bflo(unsigned w) { return __uint_as_float(w << 16); }
; __device__ __forceinline__ float bfhi(unsigned w) { return __uint_as_float(w & 0xffff0000u); }
; __device__ __forceinline__ float xsum16(float x) { auto r = __builtin_amdgcn_permlane16_swap(__float_as_uint(x), __float_as_uint(x), false, false); return __uint_as_float(r[0]) + __uint_as_float(r[1]); }
; __device__ __forceinline__ float xsum32(float x) { auto r = __builtin_amdgcn_permlane32_swap(__float_as_uint(x), __float_as_uint(x), false, false); return __uint_as_float(r[0]) + __uint_as_float(r[1]); }
;     __device__ __forceinline__ void operator()(const f32x4 (&acc)[2][2][4][2], const Unit& u, int wr, int wc, int fr, int fq) const {
;     ...
;             for (int bj = 0; bj < 2; ++bj) {
;                 const f32x4 o0 = rv[bj][0] + acc[ai][bj][m][0] * scale, o1 = rv[bj][1] + acc[ai][bj][m][1] * scale;
;                 u32x4 w; w.x = ::pk2(o0[0], o0[1]); w.y = ::pk2(o0[2], o0[3]); w.z = ::pk2(o1[0], o1[1]); w.w = ::pk2(o1[2], o1[3]);
;                 *(u32x4*)(X + off + bj * HALF) = w;
;                 const float q0 = ::bflo(w.x), q1 = ::bfhi(w.x), q2 = ::bflo(w.y), q3 = ::bfhi(w.y), q4 = ::bflo(w.z), q5 = ::bfhi(w.z), q6 = ::bflo(w.w), q7 = ::bfhi(w.w);
;                 ss += ((q0 * q0 + q1 * q1) + (q2 * q2 + q3 * q3)) + ((q4 * q4 + q5 * q5) + (q6 * q6 + q7 * q7));
;             }
;             ssv[b] = ss;
; #pragma unroll
;             for (int bj = 0; bj < 2; ++bj)
; #pragma unroll
;                 for (int n = 0; n < 2; ++n) rv[bj][n] = rn[bj][n];
;         }
; #pragma unroll
;         for (int b = 0; b < 8; ++b) ssv[b] = ::xsum16(ssv[b]);
; #pragma unroll
;         for (int b = 0; b < 8; ++b) ssv[b] = ::xsum32(ssv[b]);
;         if (fq == 0) {
; #pragma unroll
;             for (int b = 0; b < 8; ++b) atomicAdd(RS + row0 + (b >> 2) * HALF + (b & 3) * 16, (unsigned)(ssv[b] * 1024.f + 0.5f));
	v_lshlrev_b32_e32 v70, 16, v36
	v_and_b32_e32 v71, 0xffff0000, v36
	v_lshlrev_b32_e32 v36, 16, v37
	v_and_b32_e32 v37, 0xffff0000, v37
	v_lshlrev_b32_e32 v72, 16, v38
	v_and_b32_e32 v73, 0xffff0000, v38
	v_lshlrev_b32_e32 v38, 16, v39
	v_and_b32_e32 v39, 0xffff0000, v39
	v_fmac_f32_e32 v12, v18, v18
	v_fmac_f32_e32 v13, v19, v19
	v_add_f32_e32 v14, v12, v13
	v_pk_add_f32 v[10:11], v[10:11], v[36:37]
	v_pk_add_f32 v[8:9], v[8:9], v[70:71]
	v_pk_add_f32 v[12:13], v[6:7], v[38:39]
	v_pk_add_f32 v[6:7], v[4:5], v[72:73]
	v_cvt_pk_bf16_f32 v4, v8, v9
	v_cvt_pk_bf16_f32 v5, v10, v11
	v_cvt_pk_bf16_f32 v6, v6, v7
	v_cvt_pk_bf16_f32 v7, v12, v13
	global_store_dwordx4 v[20:21], v[4:7], off offset:256 sc1
	v_lshlrev_b32_e32 v8, 16, v4
	v_lshlrev_b32_e32 v9, 16, v5
	v_and_b32_e32 v4, 0xffff0000, v4
	v_and_b32_e32 v5, 0xffff0000, v5
	v_mul_f32_e32 v4, v4, v4
	v_mul_f32_e32 v5, v5, v5
	v_lshlrev_b32_e32 v10, 16, v6
	v_and_b32_e32 v6, 0xffff0000, v6
	v_lshlrev_b32_e32 v11, 16, v7
	v_and_b32_e32 v7, 0xffff0000, v7
	v_fmac_f32_e32 v4, v8, v8
	v_fmac_f32_e32 v5, v9, v9
	v_add_f32_e32 v4, v4, v5
	v_mul_f32_e32 v5, v6, v6
	v_mul_f32_e32 v6, v7, v7
	v_fmac_f32_e32 v5, v10, v10
	v_fmac_f32_e32 v6, v11, v11
	v_fmac_f32_e32 v23, v17, v17
	v_add_f32_e32 v5, v5, v6
	v_fmac_f32_e32 v22, v16, v16
	v_add_f32_e32 v4, v5, v4
	v_add_f32_e32 v5, v22, v23
	v_add_f32_e32 v5, v14, v5
	v_add_f32_e32 v10, v5, v4
	v_mov_b32_e32 v4, v191
	v_mov_b32_e32 v5, v158
	v_mov_b32_e32 v6, v122
	v_mov_b32_e32 v7, v100
	v_mov_b32_e32 v8, v84
	v_mov_b32_e32 v9, v50
	v_mov_b32_e32 v11, v24
	v_mov_b32_e32 v12, v10
	v_permlane16_swap_b32_e32 v191, v4
	v_permlane16_swap_b32_e32 v158, v5
	v_permlane16_swap_b32_e32 v122, v6
	v_permlane16_swap_b32_e32 v100, v7
	v_permlane16_swap_b32_e32 v84, v8
	v_permlane16_swap_b32_e32 v50, v9
	v_permlane16_swap_b32_e32 v24, v11
	v_permlane16_swap_b32_e32 v10, v12
	v_add_f32_e32 v4, v191, v4
	v_add_f32_e32 v5, v158, v5
	v_add_f32_e32 v6, v122, v6
	v_add_f32_e32 v7, v100, v7
	v_add_f32_e32 v8, v84, v8
	v_add_f32_e32 v9, v50, v9
	v_add_f32_e32 v11, v24, v11
	v_add_f32_e32 v13, v10, v12
	v_mov_b32_e32 v10, v4
	v_mov_b32_e32 v12, v5
	v_mov_b32_e32 v14, v6
	v_mov_b32_e32 v15, v7
	v_mov_b32_e32 v16, v8
	v_mov_b32_e32 v17, v9
	v_mov_b32_e32 v18, v11
	v_mov_b32_e32 v19, v13
	v_permlane32_swap_b32_e32 v4, v10
	v_permlane32_swap_b32_e32 v5, v12
	v_permlane32_swap_b32_e32 v6, v14
	v_permlane32_swap_b32_e32 v7, v15
	v_permlane32_swap_b32_e32 v8, v16
	v_permlane32_swap_b32_e32 v9, v17
	v_permlane32_swap_b32_e32 v11, v18
	v_permlane32_swap_b32_e32 v13, v19
	global_store_dwordx4 v[58:59], v[28:31], off sc1
	s_and_saveexec_b64 s[82:83], s[40:41]
	s_cbranch_execz .LBB0_107
	v_add_f32_e32 v10, v4, v10
	v_add_f32_e32 v12, v5, v12
	v_fma_f32 v10, v10, s3, 0.5
	v_add_f32_e32 v6, v6, v14
	v_cvt_u32_f32_e32 v10, v10
	v_fma_f32 v12, v12, s3, 0.5
	v_add_f32_e32 v7, v7, v15
	v_cvt_u32_f32_e32 v12, v12
	v_fma_f32 v6, v6, s3, 0.5
	v_cvt_u32_f32_e32 v6, v6
	v_fma_f32 v7, v7, s3, 0.5
	v_add_f32_e32 v8, v8, v16
	v_lshl_add_u64 v[4:5], v[146:147], 2, s[52:53]
	v_cvt_u32_f32_e32 v7, v7
	v_add_f32_e32 v9, v9, v17
	global_atomic_add v[4:5], v10, off
	global_atomic_add v[4:5], v12, off offset:64
	global_atomic_add v[4:5], v6, off offset:128
	global_atomic_add v[4:5], v7, off offset:192
	v_fma_f32 v6, v8, s3, 0.5
	v_add_f32_e32 v11, v11, v18
	v_cvt_u32_f32_e32 v6, v6
	v_fma_f32 v7, v9, s3, 0.5
	v_add_f32_e32 v13, v13, v19
	v_cvt_u32_f32_e32 v7, v7
	v_fma_f32 v8, v11, s3, 0.5
	v_cvt_u32_f32_e32 v8, v8
	v_fma_f32 v9, v13, s3, 0.5
	v_cvt_u32_f32_e32 v9, v9
	global_atomic_add v[4:5], v6, off offset:512
	global_atomic_add v[4:5], v7, off offset:576
	global_atomic_add v[4:5], v8, off offset:640
	global_atomic_add v[4:5], v9, off offset:704

; __device__ __forceinline__ unsigned pk2(float lo, float hi) { f32x2 v = {lo, hi}; bf16x2_t b = __builtin_convertvector(v, bf16x2_t); return __builtin_bit_cast(unsigned, b); }
;     static __device__ __forceinline__ void unpack8(u32x4 w, f32x4& a, f32x4& b) { a = (f32x4){::bflo(w.x), ::bfhi(w.x), ::bflo(w.y), ::bfhi(w.y)}; b = (f32x4){::bflo(w.z), ::bfhi(w.z), ::bflo(w.w), ::bfhi(w.w)}; }
;     __device__ __forceinline__ void operator()(const f32x4 (&acc)[2][2][4][2], const Unit& u, int wr, int wc, int fr, int fq) const {
;         const int row0 = u.pm * BM + wr * 64 + fr, col0 = u.pn * BM + wc * 32 + 8 * fq;
; #pragma unroll
;         for (int ai = 0; ai < 2; ++ai)
; #pragma unroll
;             for (int m = 0; m < 4; ++m) {
;                 const size_t r = (size_t)(row0 + ai * HALF + m * 16);
;                 u32x4 gv[2];
; #pragma unroll
;                 for (int bj = 0; bj < 2; ++bj) gv[bj] = *(const u32x4*)(G + r * 3072 + 2048 + col0 + bj * HALF);
; #pragma unroll
;                 for (int bj = 0; bj < 2; ++bj) {
;                     f32x4 g0, g1; unpack8(gv[bj], g0, g1);
;                     f32x4 v0 = acc[ai][bj][m][0], v1 = acc[ai][bj][m][1];
; #pragma unroll
;                     for (int j = 0; j < 4; ++j) { v0[j] *= fmaxf(g0[j], 1e-30f); v1[j] *= fmaxf(g1[j], 1e-30f); }
;                     u32x4 w; w.x = ::pk2(v0[0], v0[1]); w.y = ::pk2(v0[2], v0[3]); w.z = ::pk2(v1[0], v1[1]); w.w = ::pk2(v1[2], v1[3]);
;                     *(u32x4*)(Bo + r * 1024 + col0 + bj * HALF) = w;
;                 }
;             }
;     }
.LBB0_146:
	v_mov_b64_e32 v[148:149], s[72:73]
	v_mad_i64_i32 v[140:141], s[14:15], v144, s4, v[148:149]
	v_lshlrev_b64 v[0:1], 1, v[146:147]
	v_lshl_add_u64 v[140:141], v[140:141], 0, v[0:1]
	v_add_co_u32_e32 v146, vcc, s2, v140
	s_mov_b64 s[54:55], 0x1000
	s_nop 0
	v_addc_co_u32_e32 v147, vcc, 0, v141, vcc
	global_load_dwordx4 v[150:153], v[146:147], off
	v_lshl_add_u64 v[140:141], v[140:141], 0, s[54:55]
	global_load_dwordx4 v[154:157], v[140:141], off offset:256
	v_ashrrev_i32_e32 v145, 31, v144
	v_lshlrev_b64 v[140:141], 11, v[144:145]
	v_or_b32_e32 v146, 16, v144
	v_mad_i64_i32 v[158:159], s[14:15], v146, s4, v[148:149]
	v_lshl_add_u64 v[140:141], s[46:47], 0, v[140:141]
	v_lshl_add_u64 v[158:159], v[158:159], 0, v[0:1]
	v_lshl_add_u64 v[140:141], v[140:141], 0, v[0:1]
	v_lshl_add_u64 v[160:161], v[158:159], 0, s[54:55]
	v_add_co_u32_e32 v158, vcc, s2, v158
	v_mov_b64_e32 v[238:239], v[142:143]
	s_nop 0
	v_addc_co_u32_e32 v159, vcc, 0, v159, vcc
	s_waitcnt vmcnt(0)
	v_lshlrev_b32_e32 v3, 16, v150
	v_and_b32_e32 v145, 0xffff0000, v150
	v_lshlrev_b32_e32 v147, 16, v151
	v_and_b32_e32 v150, 0xffff0000, v151
	v_lshlrev_b32_e32 v151, 16, v152
	v_and_b32_e32 v152, 0xffff0000, v152
	v_lshlrev_b32_e32 v162, 16, v153
	v_and_b32_e32 v153, 0xffff0000, v153
	v_lshlrev_b32_e32 v163, 16, v154
	v_and_b32_e32 v154, 0xffff0000, v154
	v_lshlrev_b32_e32 v172, 16, v155
	v_and_b32_e32 v155, 0xffff0000, v155
	v_lshlrev_b32_e32 v173, 16, v156
	v_and_b32_e32 v156, 0xffff0000, v156
	v_lshlrev_b32_e32 v184, 16, v157
	v_and_b32_e32 v157, 0xffff0000, v157
	v_max_f32_e32 v3, v3, v3
	v_max_f32_e32 v151, v151, v151
	v_max_f32_e32 v145, v145, v145
	v_max_f32_e32 v185, v152, v152
	v_max_f32_e32 v147, v147, v147
	v_max_f32_e32 v162, v162, v162
	v_max_f32_e32 v188, v150, v150
	v_max_f32_e32 v189, v153, v153
	v_max_f32_e32 v163, v163, v163
	v_max_f32_e32 v173, v173, v173
	v_max_f32_e32 v190, v154, v154
	v_max_f32_e32 v191, v156, v156
	v_max_f32_e32 v192, v172, v172
	v_max_f32_e32 v193, v184, v184
	v_max_f32_e32 v194, v155, v155
	v_max_f32_e32 v195, v157, v157
	v_max_f32_e32 v150, 0xda24260, v3
	v_max_f32_e32 v152, 0xda24260, v151
	v_max_f32_e32 v151, 0xda24260, v145
	v_max_f32_e32 v153, 0xda24260, v185
	v_max_f32_e32 v154, 0xda24260, v147
	v_max_f32_e32 v156, 0xda24260, v162
	v_max_f32_e32 v155, 0xda24260, v188
	v_max_f32_e32 v157, 0xda24260, v189
	v_max_f32_e32 v162, 0xda24260, v163
	v_max_f32_e32 v172, 0xda24260, v173
	v_max_f32_e32 v163, 0xda24260, v190
	v_max_f32_e32 v173, 0xda24260, v191
	v_max_f32_e32 v184, 0xda24260, v192
	v_max_f32_e32 v188, 0xda24260, v193
	v_max_f32_e32 v185, 0xda24260, v194
	v_max_f32_e32 v189, 0xda24260, v195
	v_pk_mul_f32 v[128:129], v[128:129], v[150:151]
	v_pk_mul_f32 v[150:151], v[124:125], v[152:153]
	v_pk_mul_f32 v[130:131], v[130:131], v[154:155]
	v_pk_mul_f32 v[152:153], v[126:127], v[156:157]
	v_pk_mul_f32 v[120:121], v[120:121], v[162:163]
	v_pk_mul_f32 v[154:155], v[116:117], v[172:173]
	v_cvt_pk_bf16_f32 v124, v128, v129
	v_cvt_pk_bf16_f32 v125, v130, v131
	v_cvt_pk_bf16_f32 v126, v150, v151
	v_cvt_pk_bf16_f32 v127, v152, v153
	v_pk_mul_f32 v[122:123], v[122:123], v[184:185]
	v_pk_mul_f32 v[128:129], v[118:119], v[188:189]
	global_store_dwordx4 v[140:141], v[124:127], off sc1
	v_cvt_pk_bf16_f32 v116, v120, v121
	v_cvt_pk_bf16_f32 v117, v122, v123
	v_cvt_pk_bf16_f32 v118, v154, v155
	v_cvt_pk_bf16_f32 v119, v128, v129
	global_load_dwordx4 v[124:127], v[158:159], off
	v_ashrrev_i32_e32 v147, 31, v146
	global_store_dwordx4 v[140:141], v[116:119], off offset:256 sc1
	global_load_dwordx4 v[118:121], v[160:161], off offset:256
	v_lshlrev_b64 v[128:129], 11, v[146:147]
	v_or_b32_e32 v116, 32, v144
	v_mad_i64_i32 v[122:123], s[14:15], v116, s4, v[148:149]
	v_lshl_add_u64 v[122:123], v[122:123], 0, v[0:1]
	v_lshl_add_u64 v[128:129], s[46:47], 0, v[128:129]
	v_lshl_add_u64 v[130:131], v[122:123], 0, s[54:55]
	v_add_co_u32_e32 v122, vcc, s2, v122
	v_lshl_add_u64 v[128:129], v[128:129], 0, v[0:1]
	s_nop 0
	v_addc_co_u32_e32 v123, vcc, 0, v123, vcc
	s_waitcnt vmcnt(2)
	v_lshlrev_b32_e32 v3, 16, v124
	v_and_b32_e32 v117, 0xffff0000, v124
	v_lshlrev_b32_e32 v124, 16, v125
	v_and_b32_e32 v125, 0xffff0000, v125
	v_lshlrev_b32_e32 v140, 16, v126
	v_and_b32_e32 v126, 0xffff0000, v126
	v_lshlrev_b32_e32 v141, 16, v127
	v_and_b32_e32 v127, 0xffff0000, v127
	s_waitcnt vmcnt(0)
; __device__ __forceinline__ unsigned pk2(float lo, float hi) { f32x2 v = {lo, hi}; bf16x2_t b = __builtin_convertvector(v, bf16x2_t); return __builtin_bit_cast(unsigned, b); }
;     static __device__ __forceinline__ void unpack8(u32x4 w, f32x4& a, f32x4& b) { a = (f32x4){::bflo(w.x), ::bfhi(w.x), ::bflo(w.y), ::bfhi(w.y)}; b = (f32x4){::bflo(w.z), ::bfhi(w.z), ::bflo(w.w), ::bfhi(w.w)}; }
;     __device__ __forceinline__ void operator()(const f32x4 (&acc)[2][2][4][2], const Unit& u, int wr, int wc, int fr, int fq) const {
;         const int row0 = u.pm * BM + wr * 64 + fr, col0 = u.pn * BM + wc * 32 + 8 * fq;
; #pragma unroll
;         for (int ai = 0; ai < 2; ++ai)
; #pragma unroll
;             for (int m = 0; m < 4; ++m) {
;                 const size_t r = (size_t)(row0 + ai * HALF + m * 16);
;                 u32x4 gv[2];
; #pragma unroll
;                 for (int bj = 0; bj < 2; ++bj) gv[bj] = *(const u32x4*)(G + r * 3072 + 2048 + col0 + bj * HALF);
; #pragma unroll
;                 for (int bj = 0; bj < 2; ++bj) {
;                     f32x4 g0, g1; unpack8(gv[bj], g0, g1);
;                     f32x4 v0 = acc[ai][bj][m][0], v1 = acc[ai][bj][m][1];
; #pragma unroll
;                     for (int j = 0; j < 4; ++j) { v0[j] *= fmaxf(g0[j], 1e-30f); v1[j] *= fmaxf(g1[j], 1e-30f); }
;                     u32x4 w; w.x = ::pk2(v0[0], v0[1]); w.y = ::pk2(v0[2], v0[3]); w.z = ::pk2(v1[0], v1[1]); w.w = ::pk2(v1[2], v1[3]);
;                     *(u32x4*)(Bo + r * 1024 + col0 + bj * HALF) = w;
;                 }
;             }
;     }
	v_lshlrev_b32_e32 v145, 16, v118
	v_and_b32_e32 v118, 0xffff0000, v118
	v_lshlrev_b32_e32 v146, 16, v119
	v_and_b32_e32 v119, 0xffff0000, v119
	v_lshlrev_b32_e32 v147, 16, v120
	v_and_b32_e32 v120, 0xffff0000, v120
	v_lshlrev_b32_e32 v150, 16, v121
	v_and_b32_e32 v121, 0xffff0000, v121
	v_max_f32_e32 v3, v3, v3
	v_max_f32_e32 v140, v140, v140
	v_max_f32_e32 v117, v117, v117
	v_max_f32_e32 v126, v126, v126
	v_max_f32_e32 v124, v124, v124
	v_max_f32_e32 v141, v141, v141
	v_max_f32_e32 v125, v125, v125
	v_max_f32_e32 v127, v127, v127
	v_max_f32_e32 v145, v145, v145
	v_max_f32_e32 v147, v147, v147
	v_max_f32_e32 v151, v118, v118
	v_max_f32_e32 v152, v120, v120
	v_max_f32_e32 v153, v146, v146
	v_max_f32_e32 v154, v150, v150
	v_max_f32_e32 v155, v119, v119
	v_max_f32_e32 v156, v121, v121
	v_max_f32_e32 v118, 0xda24260, v3
	v_max_f32_e32 v120, 0xda24260, v140
	v_max_f32_e32 v119, 0xda24260, v117
	v_max_f32_e32 v121, 0xda24260, v126
	v_max_f32_e32 v124, 0xda24260, v124
	v_max_f32_e32 v126, 0xda24260, v141
	v_max_f32_e32 v125, 0xda24260, v125
	v_max_f32_e32 v127, 0xda24260, v127
	v_max_f32_e32 v140, 0xda24260, v145
	v_max_f32_e32 v146, 0xda24260, v147
	v_max_f32_e32 v141, 0xda24260, v151
	v_max_f32_e32 v147, 0xda24260, v152
	v_max_f32_e32 v150, 0xda24260, v153
	v_max_f32_e32 v152, 0xda24260, v154
	v_max_f32_e32 v151, 0xda24260, v155
	v_max_f32_e32 v153, 0xda24260, v156
	v_pk_mul_f32 v[112:113], v[112:113], v[118:119]
	v_pk_mul_f32 v[118:119], v[108:109], v[120:121]
	v_pk_mul_f32 v[114:115], v[114:115], v[124:125]
	v_pk_mul_f32 v[120:121], v[110:111], v[126:127]
	v_pk_mul_f32 v[104:105], v[104:105], v[140:141]
	v_pk_mul_f32 v[124:125], v[100:101], v[146:147]
	v_cvt_pk_bf16_f32 v108, v112, v113
	v_cvt_pk_bf16_f32 v109, v114, v115
	v_cvt_pk_bf16_f32 v110, v118, v119
	v_cvt_pk_bf16_f32 v111, v120, v121
	v_pk_mul_f32 v[106:107], v[106:107], v[150:151]
	v_pk_mul_f32 v[112:113], v[102:103], v[152:153]
	global_store_dwordx4 v[128:129], v[108:111], off sc1
	v_cvt_pk_bf16_f32 v100, v104, v105
	v_cvt_pk_bf16_f32 v101, v106, v107
	v_cvt_pk_bf16_f32 v102, v124, v125
	v_cvt_pk_bf16_f32 v103, v112, v113
	global_load_dwordx4 v[108:111], v[122:123], off
	v_ashrrev_i32_e32 v117, 31, v116
	global_store_dwordx4 v[128:129], v[100:103], off offset:256 sc1
	global_load_dwordx4 v[102:105], v[130:131], off offset:256
	v_lshlrev_b64 v[112:113], 11, v[116:117]
	v_or_b32_e32 v100, 48, v144
	v_mad_i64_i32 v[106:107], s[14:15], v100, s4, v[148:149]
	v_lshl_add_u64 v[106:107], v[106:107], 0, v[0:1]
	v_lshl_add_u64 v[112:113], s[46:47], 0, v[112:113]
	v_lshl_add_u64 v[114:115], v[106:107], 0, s[54:55]
	v_add_co_u32_e32 v106, vcc, s2, v106
	v_lshl_add_u64 v[112:113], v[112:113], 0, v[0:1]
	s_nop 0
	v_addc_co_u32_e32 v107, vcc, 0, v107, vcc
	s_waitcnt vmcnt(2)
	v_lshlrev_b32_e32 v3, 16, v108
	v_and_b32_e32 v101, 0xffff0000, v108
	v_lshlrev_b32_e32 v108, 16, v109
	v_and_b32_e32 v109, 0xffff0000, v109
	v_lshlrev_b32_e32 v116, 16, v110
	v_and_b32_e32 v110, 0xffff0000, v110
	v_lshlrev_b32_e32 v117, 16, v111
	v_and_b32_e32 v111, 0xffff0000, v111
	s_waitcnt vmcnt(0)
	v_lshlrev_b32_e32 v118, 16, v102
	v_and_b32_e32 v102, 0xffff0000, v102
	v_lshlrev_b32_e32 v119, 16, v103
	v_and_b32_e32 v103, 0xffff0000, v103
	v_lshlrev_b32_e32 v120, 16, v104
	v_and_b32_e32 v104, 0xffff0000, v104
	v_lshlrev_b32_e32 v121, 16, v105
	v_and_b32_e32 v105, 0xffff0000, v105
	v_max_f32_e32 v3, v3, v3
	v_max_f32_e32 v116, v116, v116
	v_max_f32_e32 v101, v101, v101
	v_max_f32_e32 v110, v110, v110
	v_max_f32_e32 v108, v108, v108
	v_max_f32_e32 v117, v117, v117
	v_max_f32_e32 v109, v109, v109
	v_max_f32_e32 v111, v111, v111
	v_max_f32_e32 v118, v118, v118
	v_max_f32_e32 v120, v120, v120
	v_max_f32_e32 v122, v102, v102
	v_max_f32_e32 v123, v104, v104
	v_max_f32_e32 v124, v119, v119
	v_max_f32_e32 v121, v121, v121
	v_max_f32_e32 v125, v103, v103
	v_max_f32_e32 v126, v105, v105
	v_max_f32_e32 v102, 0xda24260, v3
	v_max_f32_e32 v104, 0xda24260, v116
	v_max_f32_e32 v103, 0xda24260, v101
	v_max_f32_e32 v105, 0xda24260, v110
	v_max_f32_e32 v108, 0xda24260, v108
	v_max_f32_e32 v110, 0xda24260, v117
	v_max_f32_e32 v109, 0xda24260, v109
	v_max_f32_e32 v111, 0xda24260, v111
	v_max_f32_e32 v116, 0xda24260, v118
	v_max_f32_e32 v118, 0xda24260, v120
	v_max_f32_e32 v117, 0xda24260, v122
	v_max_f32_e32 v119, 0xda24260, v123
	v_max_f32_e32 v120, 0xda24260, v124
	v_max_f32_e32 v122, 0xda24260, v121
	v_max_f32_e32 v121, 0xda24260, v125
	v_max_f32_e32 v123, 0xda24260, v126
	v_pk_mul_f32 v[96:97], v[96:97], v[102:103]
	v_pk_mul_f32 v[102:103], v[92:93], v[104:105]
	v_pk_mul_f32 v[98:99], v[98:99], v[108:109]
	v_pk_mul_f32 v[104:105], v[94:95], v[110:111]
	v_pk_mul_f32 v[88:89], v[88:89], v[116:117]
	v_pk_mul_f32 v[108:109], v[84:85], v[118:119]
	v_cvt_pk_bf16_f32 v92, v96, v97
	v_cvt_pk_bf16_f32 v93, v98, v99
	v_cvt_pk_bf16_f32 v94, v102, v103
	v_cvt_pk_bf16_f32 v95, v104, v105
	v_pk_mul_f32 v[90:91], v[90:91], v[120:121]
	v_pk_mul_f32 v[96:97], v[86:87], v[122:123]
	global_store_dwordx4 v[112:113], v[92:95], off sc1
	v_cvt_pk_bf16_f32 v84, v88, v89
	v_cvt_pk_bf16_f32 v85, v90, v91
	v_cvt_pk_bf16_f32 v86, v108, v109
	v_cvt_pk_bf16_f32 v87, v96, v97
	global_load_dwordx4 v[92:95], v[106:107], off
	v_ashrrev_i32_e32 v101, 31, v100
	global_store_dwordx4 v[112:113], v[84:87], off offset:256 sc1
	global_load_dwordx4 v[86:89], v[114:115], off offset:256
	v_lshlrev_b64 v[96:97], 11, v[100:101]
	v_add_u32_e32 v84, 0x80, v144
	v_mad_i64_i32 v[90:91], s[14:15], v84, s4, v[148:149]
	v_lshl_add_u64 v[90:91], v[90:91], 0, v[0:1]
	v_lshl_add_u64 v[96:97], s[46:47], 0, v[96:97]
	v_lshl_add_u64 v[98:99], v[90:91], 0, s[54:55]
	v_add_co_u32_e32 v90, vcc, s2, v90
	v_lshl_add_u64 v[96:97], v[96:97], 0, v[0:1]
	s_nop 0
	v_addc_co_u32_e32 v91, vcc, 0, v91, vcc
	s_waitcnt vmcnt(2)
; __device__ __forceinline__ unsigned pk2(float lo, float hi) { f32x2 v = {lo, hi}; bf16x2_t b = __builtin_convertvector(v, bf16x2_t); return __builtin_bit_cast(unsigned, b); }
;     static __device__ __forceinline__ void unpack8(u32x4 w, f32x4& a, f32x4& b) { a = (f32x4){::bflo(w.x), ::bfhi(w.x), ::bflo(w.y), ::bfhi(w.y)}; b = (f32x4){::bflo(w.z), ::bfhi(w.z), ::bflo(w.w), ::bfhi(w.w)}; }
;     __device__ __forceinline__ void operator()(const f32x4 (&acc)[2][2][4][2], const Unit& u, int wr, int wc, int fr, int fq) const {
;         const int row0 = u.pm * BM + wr * 64 + fr, col0 = u.pn * BM + wc * 32 + 8 * fq;
; #pragma unroll
;         for (int ai = 0; ai < 2; ++ai)
; #pragma unroll
;             for (int m = 0; m < 4; ++m) {
;                 const size_t r = (size_t)(row0 + ai * HALF + m * 16);
;                 u32x4 gv[2];
; #pragma unroll
;                 for (int bj = 0; bj < 2; ++bj) gv[bj] = *(const u32x4*)(G + r * 3072 + 2048 + col0 + bj * HALF);
; #pragma unroll
;                 for (int bj = 0; bj < 2; ++bj) {
;                     f32x4 g0, g1; unpack8(gv[bj], g0, g1);
;                     f32x4 v0 = acc[ai][bj][m][0], v1 = acc[ai][bj][m][1];
; #pragma unroll
;                     for (int j = 0; j < 4; ++j) { v0[j] *= fmaxf(g0[j], 1e-30f); v1[j] *= fmaxf(g1[j], 1e-30f); }
;                     u32x4 w; w.x = ::pk2(v0[0], v0[1]); w.y = ::pk2(v0[2], v0[3]); w.z = ::pk2(v1[0], v1[1]); w.w = ::pk2(v1[2], v1[3]);
;                     *(u32x4*)(Bo + r * 1024 + col0 + bj * HALF) = w;
;                 }
;             }
;     }
	v_lshlrev_b32_e32 v3, 16, v92
	v_and_b32_e32 v85, 0xffff0000, v92
	v_lshlrev_b32_e32 v92, 16, v93
	v_and_b32_e32 v93, 0xffff0000, v93
	v_lshlrev_b32_e32 v100, 16, v94
	v_and_b32_e32 v94, 0xffff0000, v94
	v_lshlrev_b32_e32 v101, 16, v95
	v_and_b32_e32 v95, 0xffff0000, v95
	s_waitcnt vmcnt(0)
	v_lshlrev_b32_e32 v102, 16, v86
	v_and_b32_e32 v86, 0xffff0000, v86
	v_lshlrev_b32_e32 v103, 16, v87
	v_and_b32_e32 v87, 0xffff0000, v87
	v_lshlrev_b32_e32 v104, 16, v88
	v_and_b32_e32 v88, 0xffff0000, v88
	v_lshlrev_b32_e32 v105, 16, v89
	v_and_b32_e32 v89, 0xffff0000, v89
	v_max_f32_e32 v3, v3, v3
	v_max_f32_e32 v100, v100, v100
	v_max_f32_e32 v85, v85, v85
	v_max_f32_e32 v94, v94, v94
	v_max_f32_e32 v92, v92, v92
	v_max_f32_e32 v101, v101, v101
	v_max_f32_e32 v93, v93, v93
	v_max_f32_e32 v95, v95, v95
	v_max_f32_e32 v102, v102, v102
	v_max_f32_e32 v104, v104, v104
	v_max_f32_e32 v106, v86, v86
	v_max_f32_e32 v107, v88, v88
	v_max_f32_e32 v108, v103, v103
	v_max_f32_e32 v105, v105, v105
	v_max_f32_e32 v109, v87, v87
	v_max_f32_e32 v110, v89, v89
	v_max_f32_e32 v86, 0xda24260, v3
	v_max_f32_e32 v88, 0xda24260, v100
	v_max_f32_e32 v87, 0xda24260, v85
	v_max_f32_e32 v89, 0xda24260, v94
	v_max_f32_e32 v92, 0xda24260, v92
	v_max_f32_e32 v94, 0xda24260, v101
	v_max_f32_e32 v93, 0xda24260, v93
	v_max_f32_e32 v95, 0xda24260, v95
	v_max_f32_e32 v100, 0xda24260, v102
	v_max_f32_e32 v102, 0xda24260, v104
	v_max_f32_e32 v101, 0xda24260, v106
	v_max_f32_e32 v103, 0xda24260, v107
	v_max_f32_e32 v104, 0xda24260, v108
	v_max_f32_e32 v106, 0xda24260, v105
	v_max_f32_e32 v105, 0xda24260, v109
	v_max_f32_e32 v107, 0xda24260, v110
	v_pk_mul_f32 v[80:81], v[80:81], v[86:87]
	v_pk_mul_f32 v[86:87], v[76:77], v[88:89]
	v_pk_mul_f32 v[82:83], v[82:83], v[92:93]
	v_pk_mul_f32 v[88:89], v[78:79], v[94:95]
	v_pk_mul_f32 v[72:73], v[72:73], v[100:101]
	v_pk_mul_f32 v[92:93], v[68:69], v[102:103]
	v_cvt_pk_bf16_f32 v76, v80, v81
	v_cvt_pk_bf16_f32 v77, v82, v83
	v_cvt_pk_bf16_f32 v78, v86, v87
	v_cvt_pk_bf16_f32 v79, v88, v89
	v_pk_mul_f32 v[74:75], v[74:75], v[104:105]
	v_pk_mul_f32 v[80:81], v[70:71], v[106:107]
	global_store_dwordx4 v[96:97], v[76:79], off sc1
	v_cvt_pk_bf16_f32 v68, v72, v73
	v_cvt_pk_bf16_f32 v69, v74, v75
	v_cvt_pk_bf16_f32 v70, v92, v93
	v_cvt_pk_bf16_f32 v71, v80, v81
	global_load_dwordx4 v[76:79], v[90:91], off
	v_ashrrev_i32_e32 v85, 31, v84
	global_store_dwordx4 v[96:97], v[68:71], off offset:256 sc1
	global_load_dwordx4 v[70:73], v[98:99], off offset:256
	v_lshlrev_b64 v[80:81], 11, v[84:85]
	v_add_u32_e32 v68, 0x90, v144
	v_mad_i64_i32 v[74:75], s[14:15], v68, s4, v[148:149]
	v_lshl_add_u64 v[74:75], v[74:75], 0, v[0:1]
	v_lshl_add_u64 v[80:81], s[46:47], 0, v[80:81]
	v_lshl_add_u64 v[82:83], v[74:75], 0, s[54:55]
	v_add_co_u32_e32 v74, vcc, s2, v74
	v_lshl_add_u64 v[80:81], v[80:81], 0, v[0:1]
	s_nop 0
	v_addc_co_u32_e32 v75, vcc, 0, v75, vcc
	s_waitcnt vmcnt(2)
	v_lshlrev_b32_e32 v3, 16, v76
	v_and_b32_e32 v69, 0xffff0000, v76
	v_lshlrev_b32_e32 v76, 16, v77
	v_and_b32_e32 v77, 0xffff0000, v77
	v_lshlrev_b32_e32 v84, 16, v78
	v_and_b32_e32 v78, 0xffff0000, v78
	v_lshlrev_b32_e32 v85, 16, v79
	v_and_b32_e32 v79, 0xffff0000, v79
	s_waitcnt vmcnt(0)
	v_lshlrev_b32_e32 v86, 16, v70
	v_and_b32_e32 v70, 0xffff0000, v70
	v_lshlrev_b32_e32 v87, 16, v71
	v_and_b32_e32 v71, 0xffff0000, v71
	v_lshlrev_b32_e32 v88, 16, v72
	v_and_b32_e32 v72, 0xffff0000, v72
	v_lshlrev_b32_e32 v89, 16, v73
	v_and_b32_e32 v73, 0xffff0000, v73
	v_max_f32_e32 v3, v3, v3
	v_max_f32_e32 v84, v84, v84
	v_max_f32_e32 v69, v69, v69
	v_max_f32_e32 v78, v78, v78
	v_max_f32_e32 v76, v76, v76
	v_max_f32_e32 v85, v85, v85
	v_max_f32_e32 v77, v77, v77
	v_max_f32_e32 v79, v79, v79
	v_max_f32_e32 v86, v86, v86
	v_max_f32_e32 v88, v88, v88
	v_max_f32_e32 v90, v70, v70
	v_max_f32_e32 v91, v72, v72
	v_max_f32_e32 v92, v87, v87
	v_max_f32_e32 v89, v89, v89
	v_max_f32_e32 v93, v71, v71
	v_max_f32_e32 v94, v73, v73
	v_max_f32_e32 v70, 0xda24260, v3
	v_max_f32_e32 v72, 0xda24260, v84
	v_max_f32_e32 v71, 0xda24260, v69
	v_max_f32_e32 v73, 0xda24260, v78
	v_max_f32_e32 v76, 0xda24260, v76
	v_max_f32_e32 v78, 0xda24260, v85
	v_max_f32_e32 v77, 0xda24260, v77
	v_max_f32_e32 v79, 0xda24260, v79
	v_max_f32_e32 v84, 0xda24260, v86
	v_max_f32_e32 v86, 0xda24260, v88
	v_max_f32_e32 v85, 0xda24260, v90
	v_max_f32_e32 v87, 0xda24260, v91
	v_max_f32_e32 v88, 0xda24260, v92
	v_max_f32_e32 v90, 0xda24260, v89
	v_max_f32_e32 v89, 0xda24260, v93
	v_max_f32_e32 v91, 0xda24260, v94
	v_pk_mul_f32 v[64:65], v[64:65], v[70:71]
	v_pk_mul_f32 v[70:71], v[60:61], v[72:73]
	v_pk_mul_f32 v[66:67], v[66:67], v[76:77]
	v_pk_mul_f32 v[72:73], v[62:63], v[78:79]
	v_pk_mul_f32 v[56:57], v[56:57], v[84:85]
	v_pk_mul_f32 v[76:77], v[52:53], v[86:87]
	v_cvt_pk_bf16_f32 v60, v64, v65
	v_cvt_pk_bf16_f32 v61, v66, v67
	v_cvt_pk_bf16_f32 v62, v70, v71
	v_cvt_pk_bf16_f32 v63, v72, v73
	v_pk_mul_f32 v[58:59], v[58:59], v[88:89]
	v_pk_mul_f32 v[64:65], v[54:55], v[90:91]
	global_store_dwordx4 v[80:81], v[60:63], off sc1
	v_cvt_pk_bf16_f32 v52, v56, v57
	v_cvt_pk_bf16_f32 v53, v58, v59
	v_cvt_pk_bf16_f32 v54, v76, v77
	v_cvt_pk_bf16_f32 v55, v64, v65
	global_load_dwordx4 v[60:63], v[74:75], off
	v_ashrrev_i32_e32 v69, 31, v68
	global_store_dwordx4 v[80:81], v[52:55], off offset:256 sc1
	global_load_dwordx4 v[54:57], v[82:83], off offset:256
	v_lshlrev_b64 v[64:65], 11, v[68:69]
	v_add_u32_e32 v52, 0xa0, v144
	v_mad_i64_i32 v[58:59], s[14:15], v52, s4, v[148:149]
	v_lshl_add_u64 v[58:59], v[58:59], 0, v[0:1]
	v_lshl_add_u64 v[64:65], s[46:47], 0, v[64:65]
	v_lshl_add_u64 v[66:67], v[58:59], 0, s[54:55]
	v_add_co_u32_e32 v58, vcc, s2, v58
	v_lshl_add_u64 v[64:65], v[64:65], 0, v[0:1]
	s_nop 0
	v_addc_co_u32_e32 v59, vcc, 0, v59, vcc
	s_waitcnt vmcnt(2)
; __device__ __forceinline__ unsigned pk2(float lo, float hi) { f32x2 v = {lo, hi}; bf16x2_t b = __builtin_convertvector(v, bf16x2_t); return __builtin_bit_cast(unsigned, b); }
;     static __device__ __forceinline__ void unpack8(u32x4 w, f32x4& a, f32x4& b) { a = (f32x4){::bflo(w.x), ::bfhi(w.x), ::bflo(w.y), ::bfhi(w.y)}; b = (f32x4){::bflo(w.z), ::bfhi(w.z), ::bflo(w.w), ::bfhi(w.w)}; }
; #define PG8_BAR __builtin_amdgcn_s_barrier()
;     __device__ __forceinline__ void operator()(const f32x4 (&acc)[2][2][4][2], const Unit& u, int wr, int wc, int fr, int fq) const {
;         const int row0 = u.pm * BM + wr * 64 + fr, col0 = u.pn * BM + wc * 32 + 8 * fq;
; #pragma unroll
;         for (int ai = 0; ai < 2; ++ai)
; #pragma unroll
;             for (int m = 0; m < 4; ++m) {
;                 const size_t r = (size_t)(row0 + ai * HALF + m * 16);
;                 u32x4 gv[2];
; #pragma unroll
;                 for (int bj = 0; bj < 2; ++bj) gv[bj] = *(const u32x4*)(G + r * 3072 + 2048 + col0 + bj * HALF);
; #pragma unroll
;                 for (int bj = 0; bj < 2; ++bj) {
;                     f32x4 g0, g1; unpack8(gv[bj], g0, g1);
;                     f32x4 v0 = acc[ai][bj][m][0], v1 = acc[ai][bj][m][1];
; #pragma unroll
;                     for (int j = 0; j < 4; ++j) { v0[j] *= fmaxf(g0[j], 1e-30f); v1[j] *= fmaxf(g1[j], 1e-30f); }
;                     u32x4 w; w.x = ::pk2(v0[0], v0[1]); w.y = ::pk2(v0[2], v0[3]); w.z = ::pk2(v1[0], v1[1]); w.w = ::pk2(v1[2], v1[3]);
;                     *(u32x4*)(Bo + r * 1024 + col0 + bj * HALF) = w;
;                 }
;             }
;     }
; template <class Epi, class Sched, bool ALIGN_EPI = false, bool SP2 = false>
; __device__ __forceinline__ void gemm_phase(PG8_LAS unsigned char* lds, const Gemm g, const Sched& S, const Epi& E) {
;     ...
;         if (!has_next) break;
; #pragma unroll
;         for (int a = 0; a < 2; ++a)
; #pragma unroll
;             for (int b = 0; b < 2; ++b)
; #pragma unroll
;                 for (int m = 0; m < 4; ++m)
; #pragma unroll
;                     for (int n = 0; n < 2; ++n) acc[a][b][m][n] = (f32x4){0.f, 0.f, 0.f, 0.f};
;         cur = nxt; cA = nA; cB = nB; ++ui;
;         if constexpr (ALIGN_EPI) { if (wr == 1) PG8_BAR; }
	v_lshlrev_b32_e32 v3, 16, v60
	v_and_b32_e32 v53, 0xffff0000, v60
	v_lshlrev_b32_e32 v60, 16, v61
	v_and_b32_e32 v61, 0xffff0000, v61
	v_lshlrev_b32_e32 v68, 16, v62
	v_and_b32_e32 v62, 0xffff0000, v62
	v_lshlrev_b32_e32 v69, 16, v63
	v_and_b32_e32 v63, 0xffff0000, v63
	s_waitcnt vmcnt(0)
	v_lshlrev_b32_e32 v70, 16, v54
	v_and_b32_e32 v54, 0xffff0000, v54
	v_lshlrev_b32_e32 v71, 16, v55
	v_and_b32_e32 v55, 0xffff0000, v55
	v_lshlrev_b32_e32 v72, 16, v56
	v_and_b32_e32 v56, 0xffff0000, v56
	v_lshlrev_b32_e32 v73, 16, v57
	v_and_b32_e32 v57, 0xffff0000, v57
	v_max_f32_e32 v3, v3, v3
	v_max_f32_e32 v68, v68, v68
	v_max_f32_e32 v53, v53, v53
	v_max_f32_e32 v62, v62, v62
	v_max_f32_e32 v60, v60, v60
	v_max_f32_e32 v69, v69, v69
	v_max_f32_e32 v61, v61, v61
	v_max_f32_e32 v63, v63, v63
	v_max_f32_e32 v70, v70, v70
	v_max_f32_e32 v72, v72, v72
	v_max_f32_e32 v74, v54, v54
	v_max_f32_e32 v75, v56, v56
	v_max_f32_e32 v76, v71, v71
	v_max_f32_e32 v73, v73, v73
	v_max_f32_e32 v77, v55, v55
	v_max_f32_e32 v78, v57, v57
	v_max_f32_e32 v54, 0xda24260, v3
	v_max_f32_e32 v56, 0xda24260, v68
	v_max_f32_e32 v55, 0xda24260, v53
	v_max_f32_e32 v57, 0xda24260, v62
	v_max_f32_e32 v60, 0xda24260, v60
	v_max_f32_e32 v62, 0xda24260, v69
	v_max_f32_e32 v61, 0xda24260, v61
	v_max_f32_e32 v63, 0xda24260, v63
	v_max_f32_e32 v68, 0xda24260, v70
	v_max_f32_e32 v70, 0xda24260, v72
	v_max_f32_e32 v69, 0xda24260, v74
	v_max_f32_e32 v71, 0xda24260, v75
	v_max_f32_e32 v72, 0xda24260, v76
	v_max_f32_e32 v74, 0xda24260, v73
	v_max_f32_e32 v73, 0xda24260, v77
	v_max_f32_e32 v75, 0xda24260, v78
	v_pk_mul_f32 v[48:49], v[48:49], v[54:55]
	v_pk_mul_f32 v[54:55], v[44:45], v[56:57]
	v_pk_mul_f32 v[50:51], v[50:51], v[60:61]
	v_pk_mul_f32 v[56:57], v[46:47], v[62:63]
	v_pk_mul_f32 v[40:41], v[40:41], v[68:69]
	v_pk_mul_f32 v[60:61], v[36:37], v[70:71]
	v_cvt_pk_bf16_f32 v44, v48, v49
	v_cvt_pk_bf16_f32 v45, v50, v51
	v_cvt_pk_bf16_f32 v46, v54, v55
	v_cvt_pk_bf16_f32 v47, v56, v57
	v_pk_mul_f32 v[42:43], v[42:43], v[72:73]
	v_pk_mul_f32 v[48:49], v[38:39], v[74:75]
	global_store_dwordx4 v[64:65], v[44:47], off sc1
	v_cvt_pk_bf16_f32 v36, v40, v41
	v_cvt_pk_bf16_f32 v37, v42, v43
	v_cvt_pk_bf16_f32 v38, v60, v61
	v_cvt_pk_bf16_f32 v39, v48, v49
	global_load_dwordx4 v[44:47], v[58:59], off
	v_ashrrev_i32_e32 v53, 31, v52
	global_store_dwordx4 v[64:65], v[36:39], off offset:256 sc1
	global_load_dwordx4 v[38:41], v[66:67], off offset:256
	v_lshlrev_b64 v[48:49], 11, v[52:53]
	v_add_u32_e32 v36, 0xb0, v144
	v_mad_i64_i32 v[42:43], s[14:15], v36, s4, v[148:149]
	v_lshl_add_u64 v[42:43], v[42:43], 0, v[0:1]
	v_lshl_add_u64 v[48:49], s[46:47], 0, v[48:49]
	v_lshl_add_u64 v[50:51], v[42:43], 0, s[54:55]
	v_add_co_u32_e32 v42, vcc, s2, v42
	v_lshl_add_u64 v[48:49], v[48:49], 0, v[0:1]
	s_nop 0
	v_addc_co_u32_e32 v43, vcc, 0, v43, vcc
	s_and_b64 vcc, exec, s[40:41]
	s_mov_b64 s[40:41], -1
	s_waitcnt vmcnt(2)
	v_lshlrev_b32_e32 v3, 16, v44
	v_and_b32_e32 v37, 0xffff0000, v44
	v_lshlrev_b32_e32 v44, 16, v45
	v_and_b32_e32 v45, 0xffff0000, v45
	v_lshlrev_b32_e32 v52, 16, v46
	v_and_b32_e32 v46, 0xffff0000, v46
	v_lshlrev_b32_e32 v53, 16, v47
	v_and_b32_e32 v47, 0xffff0000, v47
	s_waitcnt vmcnt(0)
; __device__ __forceinline__ unsigned pk2(float lo, float hi) { f32x2 v = {lo, hi}; bf16x2_t b = __builtin_convertvector(v, bf16x2_t); return __builtin_bit_cast(unsigned, b); }
;     static __device__ __forceinline__ void unpack8(u32x4 w, f32x4& a, f32x4& b) { a = (f32x4){::bflo(w.x), ::bfhi(w.x), ::bflo(w.y), ::bfhi(w.y)}; b = (f32x4){::bflo(w.z), ::bfhi(w.z), ::bflo(w.w), ::bfhi(w.w)}; }
; #define PG8_BAR __builtin_amdgcn_s_barrier()
;     __device__ __forceinline__ void operator()(const f32x4 (&acc)[2][2][4][2], const Unit& u, int wr, int wc, int fr, int fq) const {
;         const int row0 = u.pm * BM + wr * 64 + fr, col0 = u.pn * BM + wc * 32 + 8 * fq;
; #pragma unroll
;         for (int ai = 0; ai < 2; ++ai)
; #pragma unroll
;             for (int m = 0; m < 4; ++m) {
;                 const size_t r = (size_t)(row0 + ai * HALF + m * 16);
;                 u32x4 gv[2];
; #pragma unroll
;                 for (int bj = 0; bj < 2; ++bj) gv[bj] = *(const u32x4*)(G + r * 3072 + 2048 + col0 + bj * HALF);
; #pragma unroll
;                 for (int bj = 0; bj < 2; ++bj) {
;                     f32x4 g0, g1; unpack8(gv[bj], g0, g1);
;                     f32x4 v0 = acc[ai][bj][m][0], v1 = acc[ai][bj][m][1];
; #pragma unroll
;                     for (int j = 0; j < 4; ++j) { v0[j] *= fmaxf(g0[j], 1e-30f); v1[j] *= fmaxf(g1[j], 1e-30f); }
;                     u32x4 w; w.x = ::pk2(v0[0], v0[1]); w.y = ::pk2(v0[2], v0[3]); w.z = ::pk2(v1[0], v1[1]); w.w = ::pk2(v1[2], v1[3]);
;                     *(u32x4*)(Bo + r * 1024 + col0 + bj * HALF) = w;
;                 }
;             }
;     }
; template <class Epi, class Sched, bool ALIGN_EPI = false, bool SP2 = false>
; __device__ __forceinline__ void gemm_phase(PG8_LAS unsigned char* lds, const Gemm g, const Sched& S, const Epi& E) {
;     ...
;         if (!has_next) break;
; #pragma unroll
;         for (int a = 0; a < 2; ++a)
; #pragma unroll
;             for (int b = 0; b < 2; ++b)
; #pragma unroll
;                 for (int m = 0; m < 4; ++m)
; #pragma unroll
;                     for (int n = 0; n < 2; ++n) acc[a][b][m][n] = (f32x4){0.f, 0.f, 0.f, 0.f};
;         cur = nxt; cA = nA; cB = nB; ++ui;
;         if constexpr (ALIGN_EPI) { if (wr == 1) PG8_BAR; }
	v_lshlrev_b32_e32 v54, 16, v38
	v_and_b32_e32 v38, 0xffff0000, v38
	v_lshlrev_b32_e32 v55, 16, v39
	v_and_b32_e32 v39, 0xffff0000, v39
	v_lshlrev_b32_e32 v56, 16, v40
	v_and_b32_e32 v40, 0xffff0000, v40
	v_lshlrev_b32_e32 v57, 16, v41
	v_and_b32_e32 v41, 0xffff0000, v41
	v_max_f32_e32 v3, v3, v3
	v_max_f32_e32 v52, v52, v52
	v_max_f32_e32 v37, v37, v37
	v_max_f32_e32 v46, v46, v46
	v_max_f32_e32 v44, v44, v44
	v_max_f32_e32 v53, v53, v53
	v_max_f32_e32 v45, v45, v45
	v_max_f32_e32 v47, v47, v47
	v_max_f32_e32 v54, v54, v54
	v_max_f32_e32 v56, v56, v56
	v_max_f32_e32 v58, v38, v38
	v_max_f32_e32 v59, v40, v40
	v_max_f32_e32 v60, v55, v55
	v_max_f32_e32 v57, v57, v57
	v_max_f32_e32 v61, v39, v39
	v_max_f32_e32 v62, v41, v41
	v_max_f32_e32 v38, 0xda24260, v3
	v_max_f32_e32 v40, 0xda24260, v52
	v_max_f32_e32 v39, 0xda24260, v37
	v_max_f32_e32 v41, 0xda24260, v46
	v_max_f32_e32 v44, 0xda24260, v44
	v_max_f32_e32 v46, 0xda24260, v53
	v_max_f32_e32 v45, 0xda24260, v45
	v_max_f32_e32 v47, 0xda24260, v47
	v_max_f32_e32 v52, 0xda24260, v54
	v_max_f32_e32 v54, 0xda24260, v56
	v_max_f32_e32 v53, 0xda24260, v58
	v_max_f32_e32 v55, 0xda24260, v59
	v_max_f32_e32 v56, 0xda24260, v60
	v_max_f32_e32 v58, 0xda24260, v57
	v_max_f32_e32 v57, 0xda24260, v61
	v_max_f32_e32 v59, 0xda24260, v62
	v_pk_mul_f32 v[32:33], v[32:33], v[38:39]
	v_pk_mul_f32 v[38:39], v[28:29], v[40:41]
	v_pk_mul_f32 v[34:35], v[34:35], v[44:45]
	v_pk_mul_f32 v[40:41], v[30:31], v[46:47]
	v_pk_mul_f32 v[24:25], v[24:25], v[52:53]
	v_pk_mul_f32 v[44:45], v[20:21], v[54:55]
	v_cvt_pk_bf16_f32 v28, v32, v33
	v_cvt_pk_bf16_f32 v29, v34, v35
	v_cvt_pk_bf16_f32 v30, v38, v39
	v_cvt_pk_bf16_f32 v31, v40, v41
	v_pk_mul_f32 v[26:27], v[26:27], v[56:57]
	v_pk_mul_f32 v[32:33], v[22:23], v[58:59]
	global_store_dwordx4 v[48:49], v[28:31], off sc1
	v_cvt_pk_bf16_f32 v20, v24, v25
	v_cvt_pk_bf16_f32 v21, v26, v27
	v_cvt_pk_bf16_f32 v22, v44, v45
	v_cvt_pk_bf16_f32 v23, v32, v33
	global_load_dwordx4 v[28:31], v[42:43], off
	v_ashrrev_i32_e32 v37, 31, v36
	global_store_dwordx4 v[48:49], v[20:23], off offset:256 sc1
	global_load_dwordx4 v[20:23], v[50:51], off offset:256
	v_lshlrev_b64 v[24:25], 11, v[36:37]
	v_lshl_add_u64 v[24:25], s[46:47], 0, v[24:25]
	v_lshl_add_u64 v[0:1], v[24:25], 0, v[0:1]
	s_waitcnt vmcnt(2)
	v_lshlrev_b32_e32 v3, 16, v28
	v_and_b32_e32 v24, 0xffff0000, v28
	v_lshlrev_b32_e32 v25, 16, v29
	v_and_b32_e32 v26, 0xffff0000, v29
	v_lshlrev_b32_e32 v27, 16, v30
	v_and_b32_e32 v28, 0xffff0000, v30
	v_lshlrev_b32_e32 v29, 16, v31
	v_and_b32_e32 v30, 0xffff0000, v31
	s_waitcnt vmcnt(0)
	v_lshlrev_b32_e32 v31, 16, v20
	v_and_b32_e32 v20, 0xffff0000, v20
	v_lshlrev_b32_e32 v32, 16, v21
	v_and_b32_e32 v21, 0xffff0000, v21
	v_lshlrev_b32_e32 v33, 16, v22
	v_and_b32_e32 v22, 0xffff0000, v22
	v_lshlrev_b32_e32 v34, 16, v23
	v_and_b32_e32 v23, 0xffff0000, v23
	v_max_f32_e32 v3, v3, v3
	v_max_f32_e32 v27, v27, v27
	v_max_f32_e32 v24, v24, v24
	v_max_f32_e32 v28, v28, v28
	v_max_f32_e32 v25, v25, v25
	v_max_f32_e32 v29, v29, v29
	v_max_f32_e32 v35, v26, v26
	v_max_f32_e32 v30, v30, v30
	v_max_f32_e32 v31, v31, v31
	v_max_f32_e32 v33, v33, v33
	v_max_f32_e32 v36, v20, v20
	v_max_f32_e32 v37, v22, v22
	v_max_f32_e32 v32, v32, v32
	v_max_f32_e32 v34, v34, v34
	v_max_f32_e32 v38, v21, v21
	v_max_f32_e32 v39, v23, v23
	v_max_f32_e32 v20, 0xda24260, v3
	v_max_f32_e32 v22, 0xda24260, v27
	v_max_f32_e32 v21, 0xda24260, v24
	v_max_f32_e32 v23, 0xda24260, v28
	v_max_f32_e32 v24, 0xda24260, v25
	v_max_f32_e32 v26, 0xda24260, v29
	v_max_f32_e32 v25, 0xda24260, v35
	v_max_f32_e32 v27, 0xda24260, v30
	v_max_f32_e32 v28, 0xda24260, v31
	v_max_f32_e32 v30, 0xda24260, v33
	v_max_f32_e32 v29, 0xda24260, v36
	v_max_f32_e32 v31, 0xda24260, v37
	v_max_f32_e32 v32, 0xda24260, v32
	v_max_f32_e32 v34, 0xda24260, v34
	v_max_f32_e32 v33, 0xda24260, v38
	v_max_f32_e32 v35, 0xda24260, v39
	v_pk_mul_f32 v[16:17], v[16:17], v[20:21]
	v_pk_mul_f32 v[12:13], v[12:13], v[22:23]
	v_pk_mul_f32 v[18:19], v[18:19], v[24:25]
	v_pk_mul_f32 v[14:15], v[14:15], v[26:27]
	v_pk_mul_f32 v[8:9], v[8:9], v[28:29]
	v_pk_mul_f32 v[20:21], v[4:5], v[30:31]
	v_pk_mul_f32 v[10:11], v[10:11], v[32:33]
	v_pk_mul_f32 v[22:23], v[6:7], v[34:35]
	v_cvt_pk_bf16_f32 v4, v16, v17
	v_cvt_pk_bf16_f32 v5, v18, v19
	v_cvt_pk_bf16_f32 v6, v12, v13
	v_cvt_pk_bf16_f32 v7, v14, v15
	v_cvt_pk_bf16_f32 v8, v8, v9
	v_cvt_pk_bf16_f32 v9, v10, v11
	v_cvt_pk_bf16_f32 v10, v20, v21
	v_cvt_pk_bf16_f32 v11, v22, v23
	global_store_dwordx4 v[0:1], v[4:7], off sc1
	global_store_dwordx4 v[0:1], v[8:11], off offset:256 sc1
	s_cbranch_vccnz .LBB0_122
	s_andn2_b64 vcc, exec, s[48:49]
	s_cbranch_vccnz .LBB0_121
	s_barrier
	s_branch .LBB0_121

; #define LAS __attribute__((address_space(3)))
; __device__ __forceinline__ f32x4 mfma16(bf16x8 a, bf16x8 b, f32x4 c) { return __builtin_amdgcn_mfma_f32_16x16x32_bf16(a, b, c, 0, 0, 0); }
; template <int DVT, int NKB> ...
;     ...
; #pragma unroll
;     for (int nb = 0; nb < NKB; ++nb)
; #pragma unroll
;         for (int t = 0; t < 2; ++t) {
;             const LAS unsigned char* kp = kbase + (nb * 32 + t * 16 + fr) * kstr + quad * 16;
;             const bf16x8 k0 = *(const LAS bf16x8*)kp, k1 = *(const LAS bf16x8*)(kp + 64), k2 = *(const LAS bf16x8*)(kp + 128), k3 = *(const LAS bf16x8*)(kp + 192);
;             f32x4 b4;
; #pragma unroll
;             for (int j = 0; j < 4; ++j) b4[j] = nslope * __builtin_fabsf(relq - (float)(nb * 32 + t * 16 + j));
;             f32x4 aa = mfma16(k0, qa0, b4), ab = mfma16(k2, qb0, b4);
;             aa = mfma16(k1, qa1, aa); ab = mfma16(k3, qb1, ab);
; #pragma unroll
;             for (int j = 0; j < 4; ++j) { mxa = fmaxf(mxa, aa[j]); mxb = fmaxf(mxb, ab[j]); }
;             sa[nb][t] = aa; sb[nb][t] = ab;
;         }
;     if (!__any((mxa - ma > -140.f) || (mxb - mb > -140.f))) return;
; __device__ __forceinline__ void diff_unit(LAS unsigned char* lds, const bf16_t* zA, bf16_t* ya, int bl, int h, int qt, float slope, float lam, float oml, const float* subln, int tid) {
;     ...
;             for (int j = 0; j < 2; ++j) { pk_[j] = *(const u32x4*)(kg + (size_t)(knext * 64 + j * 32) * 1536); pv_[j] = *(const u32x4*)(vg + (size_t)(knext * 64 + j * 32) * 1536); }
;         }
;         const float relq = (float)(qpos - ktile * 64 - quad * 4);
.LBB0_210:
	v_lshl_or_b32 v140, s55, 6, v139
	v_sub_u32_e32 v140, v138, v140
	v_cvt_f32_i32_e32 v148, v140
	s_bitcmp1_b32 s54, 0
	s_cselect_b32 s42, 0x8c00, 0
	s_add_i32 s56, s42, 0
	v_add3_u32 v140, s56, v146, v3
	ds_read_b128 v[188:191], v140
	ds_read_b128 v[192:195], v140 offset:64
	ds_read_b128 v[196:199], v140 offset:128
	ds_read_b128 v[200:203], v140 offset:192
	ds_read_b128 v[204:207], v140 offset:4352
	ds_read_b128 v[208:211], v140 offset:4416
	ds_read_b128 v[212:215], v140 offset:4480
	ds_read_b128 v[216:219], v140 offset:4544
	ds_read_b128 v[220:223], v140 offset:8704
	ds_read_b128 v[224:227], v140 offset:8768
	ds_read_b128 v[228:231], v140 offset:8832
	ds_read_b128 v[232:235], v140 offset:8896
	s_lshl_b32 s55, s53, 6
	v_mad_i64_i32 v[172:173], s[42:43], s55, v182, v[144:145]
	v_add_f32_e32 v161, -1.0, v148
	v_add_f32_e32 v162, s16, v148
	s_or_b32 s42, s55, 32
	v_add_f32_e32 v163, s17, v148
	global_load_dwordx4 v[88:91], v[172:173], off offset:1024
	v_mul_f32_e64 v160, v0, |v148|
	global_load_dwordx4 v[84:87], v[172:173], off offset:2048
	v_mad_i64_i32 v[236:237], s[42:43], s42, v182, v[144:145]
	v_mul_f32_e64 v161, v0, |v161|
	v_mul_f32_e64 v162, v0, |v162|
	v_mul_f32_e64 v163, v0, |v163|
	global_load_dwordx4 v[92:95], v[236:237], off offset:1024
	global_load_dwordx4 v[96:99], v[236:237], off offset:2048
	s_waitcnt lgkmcnt(11)
	v_mfma_f32_16x16x32_bf16 v[116:119], v[188:191], v[16:19], v[160:163]
	v_add_f32_e32 v164, s20, v148
	v_add_f32_e32 v165, s21, v148
	s_waitcnt lgkmcnt(9)
	v_mfma_f32_16x16x32_bf16 v[120:123], v[196:199], v[12:15], v[160:163]
	v_add_f32_e32 v166, s18, v148
	v_add_f32_e32 v167, s19, v148
	v_mfma_f32_16x16x32_bf16 v[116:119], v[192:195], v[8:11], v[116:119]
	v_mul_f32_e64 v164, v0, |v164|
	v_mul_f32_e64 v165, v0, |v165|
	s_waitcnt lgkmcnt(8)
	v_mfma_f32_16x16x32_bf16 v[120:123], v[200:203], v[4:7], v[120:123]
	v_mul_f32_e64 v166, v0, |v166|
	v_mul_f32_e64 v167, v0, |v167|
	ds_read_b128 v[188:191], v140 offset:13056
	ds_read_b128 v[192:195], v140 offset:13120
	ds_read_b128 v[196:199], v140 offset:13184
	ds_read_b128 v[200:203], v140 offset:13248
	s_waitcnt lgkmcnt(11)
	v_mfma_f32_16x16x32_bf16 v[124:127], v[204:207], v[16:19], v[164:167]
	v_add_f32_e32 v240, s24, v148
	v_add_f32_e32 v241, s25, v148
	s_waitcnt lgkmcnt(9)
	v_mfma_f32_16x16x32_bf16 v[128:131], v[212:215], v[12:15], v[164:167]
	v_add_f32_e32 v242, s22, v148
	v_add_f32_e32 v243, s23, v148
	v_mfma_f32_16x16x32_bf16 v[124:127], v[208:211], v[8:11], v[124:127]
	v_mul_f32_e64 v240, v0, |v240|
	v_mul_f32_e64 v241, v0, |v241|
	s_waitcnt lgkmcnt(8)
	v_mfma_f32_16x16x32_bf16 v[128:131], v[216:219], v[4:7], v[128:131]
	v_mul_f32_e64 v242, v0, |v242|
	v_mul_f32_e64 v243, v0, |v243|
	v_max3_f32 v172, v116, s96, v117
	v_max3_f32 v173, v120, s96, v121
	v_max3_f32 v172, v172, v118, v119
	v_max3_f32 v173, v173, v122, v123
	s_waitcnt lgkmcnt(7)
	v_mfma_f32_16x16x32_bf16 v[100:103], v[220:223], v[16:19], v[240:243]
	v_add_f32_e32 v244, s28, v148
	v_add_f32_e32 v245, s29, v148
	s_waitcnt lgkmcnt(5)
	v_mfma_f32_16x16x32_bf16 v[104:107], v[228:231], v[12:15], v[240:243]
	v_add_f32_e32 v246, s26, v148
	v_add_f32_e32 v247, s27, v148
	v_mfma_f32_16x16x32_bf16 v[100:103], v[224:227], v[8:11], v[100:103]
	v_mul_f32_e64 v244, v0, |v244|
	v_mul_f32_e64 v245, v0, |v245|
	s_waitcnt lgkmcnt(4)
	v_mfma_f32_16x16x32_bf16 v[104:107], v[232:235], v[4:7], v[104:107]
	v_mul_f32_e64 v246, v0, |v246|
	v_mul_f32_e64 v247, v0, |v247|
	v_max3_f32 v172, v172, v124, v125
	v_max3_f32 v173, v173, v128, v129
	v_max3_f32 v172, v172, v126, v127
	v_max3_f32 v173, v173, v130, v131
	s_waitcnt lgkmcnt(3)
	v_mfma_f32_16x16x32_bf16 v[108:111], v[188:191], v[16:19], v[244:247]
	s_waitcnt lgkmcnt(1)
	v_mfma_f32_16x16x32_bf16 v[112:115], v[196:199], v[12:15], v[244:247]
	v_mfma_f32_16x16x32_bf16 v[108:111], v[192:195], v[8:11], v[108:111]
	s_waitcnt lgkmcnt(0)
	v_mfma_f32_16x16x32_bf16 v[112:115], v[200:203], v[4:7], v[112:115]
	v_max3_f32 v172, v172, v100, v101
	v_max3_f32 v173, v173, v104, v105
	v_max3_f32 v172, v172, v102, v103
	v_max3_f32 v173, v173, v106, v107
	s_nop 4
	v_max3_f32 v172, v172, v108, v109
	v_max3_f32 v173, v173, v112, v113
	v_max3_f32 v148, v172, v110, v111
	v_max3_f32 v137, v173, v114, v115
	v_sub_f32_e32 v140, v148, v159
	v_sub_f32_e32 v141, v137, v154
	v_max_f32_e32 v140, v140, v141
	v_cmp_lt_f32_e32 vcc, s37, v140
	s_cbranch_vccz .LBB0_215
; #define LAS __attribute__((address_space(3)))
; __device__ __forceinline__ float fexp2(float x) { return __builtin_amdgcn_exp2f(x); }
; __device__ __forceinline__ s16x4 ldtr(const LAS unsigned char* p) { return __builtin_bit_cast(s16x4, __builtin_amdgcn_ds_read_tr16_b64_v4i16((LAS v4i16_t*)p)); }
; __device__ __forceinline__ float xmax16(float x) { auto r = __builtin_amdgcn_permlane16_swap(__float_as_uint(x), __float_as_uint(x), false, false); return fmaxf(__uint_as_float(r[0]), __uint_as_float(r[1])); }
; __device__ __forceinline__ float xmax32(float x) { auto r = __builtin_amdgcn_permlane32_swap(__float_as_uint(x), __float_as_uint(x), false, false); return fmaxf(__uint_as_float(r[0]), __uint_as_float(r[1])); }
; template <int DVT, int NKB> ...
;     ...
;     if (!__any((mxa - ma > -140.f) || (mxb - mb > -140.f))) return;
;     mxa = xmax16(mxa); mxb = xmax16(mxb);
;     mxa = xmax32(mxa); mxb = xmax32(mxb);
;     const float mna = fmaxf(ma, mxa), mnb = fmaxf(mb, mxb);
;     if (__any((mna > ma) || (mnb > mb))) {
;         const float ala = fexp2(ma - mna), alb = fexp2(mb - mnb);
;         la *= ala; lb *= alb;
; #pragma unroll
;         for (int d = 0; d < DVT; ++d) { oa[d] = oa[d] * ala; ob[d] = ob[d] * alb; }
;         ma = mna; mb = mnb;
;     }
;     ...
;         const LAS unsigned char* vp = vbase + (nb * 32 + quad * 4 + (fr >> 2)) * vstr + (fr & 3) * 8;
;         __builtin_amdgcn_s_setprio(1);
; #pragma unroll
;         for (int d = 0; d < DVT; ++d) {
;             const bf16x8 vf = cat8(ldtr(vp + d * 32), ldtr(vp + 16 * vstr + d * 32));
	v_add3_u32 v252, s56, v147, v153
	ds_read_b64_tr_b16 v[188:189], v252 offset:17408
	ds_read_b64_tr_b16 v[190:191], v252 offset:22016
	ds_read_b64_tr_b16 v[192:193], v252 offset:17440
	ds_read_b64_tr_b16 v[194:195], v252 offset:22048
	ds_read_b64_tr_b16 v[196:197], v252 offset:17472
	ds_read_b64_tr_b16 v[198:199], v252 offset:22080
	ds_read_b64_tr_b16 v[200:201], v252 offset:17504
	ds_read_b64_tr_b16 v[202:203], v252 offset:22112
	ds_read_b64_tr_b16 v[204:205], v252 offset:17536
	ds_read_b64_tr_b16 v[206:207], v252 offset:22144
	ds_read_b64_tr_b16 v[208:209], v252 offset:17568
	ds_read_b64_tr_b16 v[210:211], v252 offset:22176
	ds_read_b64_tr_b16 v[212:213], v252 offset:17600
	ds_read_b64_tr_b16 v[214:215], v252 offset:22208
	ds_read_b64_tr_b16 v[216:217], v252 offset:17632
	ds_read_b64_tr_b16 v[218:219], v252 offset:22240
	v_cmp_lt_f32_e32 vcc, 0, v140
	s_cbranch_vccz .LBB0_213
	v_mov_b32_e32 v140, v148
	s_nop 1
	v_permlane16_swap_b32_e32 v148, v140
	v_max_f32_e32 v140, v140, v140
	v_max_f32_e32 v141, v148, v148
	v_max_f32_e32 v140, v141, v140
	v_mov_b32_e32 v141, v137
	s_nop 1
	v_permlane16_swap_b32_e32 v137, v141
	v_max_f32_e32 v141, v141, v141
	v_max_f32_e32 v137, v137, v137
	v_max_f32_e32 v141, v137, v141
	v_mov_b32_e32 v137, v140
	v_mov_b32_e32 v148, v141
	s_nop 0
	v_permlane32_swap_b32_e32 v140, v137
	v_permlane32_swap_b32_e32 v141, v148
	v_max3_f32 v137, v159, v140, v137
	v_max3_f32 v148, v154, v141, v148
	v_cmp_gt_f32_e32 vcc, v137, v159
	v_cmp_gt_f32_e64 s[42:43], v148, v154
	s_or_b64 vcc, vcc, s[42:43]
	s_cbranch_vccz .LBB0_213
	v_sub_f32_e32 v140, v159, v137
	v_exp_f32_e32 v160, v140
	v_sub_f32_e32 v140, v154, v148
	v_exp_f32_e32 v161, v140
	v_mov_b32_e32 v159, v137
	v_mov_b32_e32 v154, v161
	v_pk_mul_f32 v[134:135], v[134:135], v[160:161]
	v_pk_mul_f32 v[70:71], v[70:71], v[154:155] op_sel_hi:[1,0]
	v_pk_mul_f32 v[68:69], v[68:69], v[154:155] op_sel_hi:[1,0]
	v_pk_mul_f32 v[66:67], v[66:67], v[154:155] op_sel_hi:[1,0]
	v_pk_mul_f32 v[64:65], v[64:65], v[154:155] op_sel_hi:[1,0]
	v_pk_mul_f32 v[50:51], v[50:51], v[154:155] op_sel_hi:[1,0]
	v_pk_mul_f32 v[48:49], v[48:49], v[154:155] op_sel_hi:[1,0]
	v_pk_mul_f32 v[62:63], v[62:63], v[154:155] op_sel_hi:[1,0]
	v_pk_mul_f32 v[60:61], v[60:61], v[154:155] op_sel_hi:[1,0]
	v_pk_mul_f32 v[54:55], v[54:55], v[154:155] op_sel_hi:[1,0]
	v_pk_mul_f32 v[52:53], v[52:53], v[154:155] op_sel_hi:[1,0]
	v_pk_mul_f32 v[58:59], v[58:59], v[154:155] op_sel_hi:[1,0]
	v_pk_mul_f32 v[56:57], v[56:57], v[154:155] op_sel_hi:[1,0]
	v_pk_mul_f32 v[82:83], v[82:83], v[154:155] op_sel_hi:[1,0]
	v_pk_mul_f32 v[80:81], v[80:81], v[154:155] op_sel_hi:[1,0]
	v_pk_mul_f32 v[74:75], v[74:75], v[160:161] op_sel_hi:[1,0]
	v_pk_mul_f32 v[72:73], v[72:73], v[160:161] op_sel_hi:[1,0]
	v_pk_mul_f32 v[46:47], v[46:47], v[160:161] op_sel_hi:[1,0]
	v_pk_mul_f32 v[44:45], v[44:45], v[160:161] op_sel_hi:[1,0]
	v_pk_mul_f32 v[26:27], v[26:27], v[160:161] op_sel_hi:[1,0]
	v_pk_mul_f32 v[24:25], v[24:25], v[160:161] op_sel_hi:[1,0]
	v_pk_mul_f32 v[30:31], v[30:31], v[160:161] op_sel_hi:[1,0]
	v_pk_mul_f32 v[28:29], v[28:29], v[160:161] op_sel_hi:[1,0]
	v_pk_mul_f32 v[42:43], v[42:43], v[160:161] op_sel_hi:[1,0]
	v_pk_mul_f32 v[40:41], v[40:41], v[160:161] op_sel_hi:[1,0]
	v_pk_mul_f32 v[22:23], v[22:23], v[160:161] op_sel_hi:[1,0]
	v_pk_mul_f32 v[20:21], v[20:21], v[160:161] op_sel_hi:[1,0]
	v_pk_mul_f32 v[34:35], v[34:35], v[160:161] op_sel_hi:[1,0]
	v_pk_mul_f32 v[32:33], v[32:33], v[160:161] op_sel_hi:[1,0]
	v_pk_mul_f32 v[38:39], v[38:39], v[160:161] op_sel_hi:[1,0]
	v_pk_mul_f32 v[36:37], v[36:37], v[160:161] op_sel_hi:[1,0]
	v_pk_mul_f32 v[78:79], v[78:79], v[154:155] op_sel_hi:[1,0]
	v_pk_mul_f32 v[76:77], v[76:77], v[154:155] op_sel_hi:[1,0]
	v_mov_b32_e32 v154, v148
	s_branch .LBB0_214

; __device__ __forceinline__ unsigned pk2(float lo, float hi) { f32x2 v = {lo, hi}; bf16x2_t b = __builtin_convertvector(v, bf16x2_t); return __builtin_bit_cast(unsigned, b); }
; __device__ __forceinline__ float fexp2(float x) { return __builtin_amdgcn_exp2f(x); }
; __device__ __forceinline__ float frcp(float x) { return __builtin_amdgcn_rcpf(x); }
;     __device__ __forceinline__ void operator()(const f32x4 (&acc)[2][2][4][2], const Unit& u, int wr, int wc, int fr, int fq) const {
;     ...
;         for (int ai = 0; ai < 2; ++ai)
; #pragma unroll
;             for (int m = 0; m < 4; ++m) {
;                 bf16_t* rowp = base + (size_t)(row0 + ai * HALF + m * 16) * ld + col0;
;                 const float rs = __builtin_amdgcn_rsqf(rsv[ai][m] * (1.f / 1024.f) + 1e-6f);
; #pragma unroll
;                 for (int bj = 0; bj < 2; ++bj) {
;                     f32x4 v0 = acc[ai][bj][m][0] * rs, v1 = acc[ai][bj][m][1] * rs;
;                     if (sig) {
;                         float e[8];
;                         __builtin_amdgcn_sched_barrier(0);
; #pragma unroll
;                         for (int j = 0; j < 4; ++j) { e[j] = ::fexp2(-LOG2E * v0[j]); e[4 + j] = ::fexp2(-LOG2E * v1[j]); }
;                         __builtin_amdgcn_sched_barrier(0);
; #pragma unroll
;                         for (int j = 0; j < 8; ++j) e[j] = ::frcp(1.f + e[j]);
;                         __builtin_amdgcn_sched_barrier(0);
; #pragma unroll
;                         for (int j = 0; j < 4; ++j) { v0[j] = e[j]; v1[j] = e[4 + j]; }
;                     } else { v0 = v0 * sc; v1 = v1 * sc; }
;                     u32x4 w; w.x = ::pk2(v0[0], v0[1]); w.y = ::pk2(v0[2], v0[3]); w.z = ::pk2(v1[0], v1[1]); w.w = ::pk2(v1[2], v1[3]);
;                     *(u32x4*)(rowp + bj * HALF) = w;
;                 }
.LBB0_255:
	v_lshl_or_b32 v124, s53, 8, v161
	v_ashrrev_i32_e32 v125, 31, v124
	v_mul_lo_u32 v128, s75, v156
	v_mul_lo_u32 v129, s74, v157
	v_mad_u64_u32 v[126:127], s[42:43], s74, v156, 0
	v_lshl_add_u64 v[124:125], v[124:125], 1, s[82:83]
	v_add3_u32 v127, v127, v129, v128
	v_mov_b32_e32 v159, v158
	v_lshl_add_u64 v[126:127], v[126:127], 1, v[124:125]
	v_cvt_pk_bf16_f32 v128, v132, v133
	v_cvt_pk_bf16_f32 v129, v134, v135
	v_cvt_pk_bf16_f32 v130, v136, v137
	v_cvt_pk_bf16_f32 v131, v138, v139
	global_store_dwordx4 v[126:127], v[128:131], off sc1
	v_pk_mul_f32 v[134:135], v[116:117], v[158:159]
	v_cndmask_b32_e64 v116, 0, 1, s[76:77]
	v_mov_b32_e32 v130, v158
	v_mov_b32_e32 v131, v158
	v_pk_mul_f32 v[128:129], v[122:123], v[130:131]
	v_pk_mul_f32 v[132:133], v[120:121], v[158:159]
	v_pk_mul_f32 v[130:131], v[118:119], v[130:131]
	v_cmp_ne_u32_e64 s[42:43], 1, v116
	s_andn2_b64 vcc, exec, s[76:77]
	s_mov_b64 s[76:77], -1
	s_cbranch_vccnz .LBB0_257
	v_mov_b32_e32 v120, v154
	v_mov_b32_e32 v121, v154
	v_pk_mul_f32 v[118:119], v[120:121], v[128:129]
	v_pk_mul_f32 v[116:117], v[154:155], v[132:133]
	v_pk_mul_f32 v[122:123], v[120:121], v[130:131]
	v_pk_mul_f32 v[120:121], v[154:155], v[134:135]
	s_mov_b64 s[76:77], 0

; __device__ __forceinline__ unsigned pk2(float lo, float hi) { f32x2 v = {lo, hi}; bf16x2_t b = __builtin_convertvector(v, bf16x2_t); return __builtin_bit_cast(unsigned, b); }
; __device__ __forceinline__ float fexp2(float x) { return __builtin_amdgcn_exp2f(x); }
; __device__ __forceinline__ float frcp(float x) { return __builtin_amdgcn_rcpf(x); }
;     __device__ __forceinline__ void operator()(const f32x4 (&acc)[2][2][4][2], const Unit& u, int wr, int wc, int fr, int fq) const {
;     ...
;             for (int m = 0; m < 4; ++m) rsv[ai][m] = (float)RS[row0 + ai * HALF + m * 16] * (1.f / 1024.f);
; #pragma unroll
;         for (int ai = 0; ai < 2; ++ai)
; #pragma unroll
;             for (int m = 0; m < 4; ++m) {
;                 bf16_t* rowp = base + (size_t)(row0 + ai * HALF + m * 16) * ld + col0;
;                 const float rs = __builtin_amdgcn_rsqf(rsv[ai][m] * (1.f / 1024.f) + 1e-6f);
; #pragma unroll
;                 for (int bj = 0; bj < 2; ++bj) {
;                     f32x4 v0 = acc[ai][bj][m][0] * rs, v1 = acc[ai][bj][m][1] * rs;
;                     if (sig) {
;                         float e[8];
;                         __builtin_amdgcn_sched_barrier(0);
; #pragma unroll
;                         for (int j = 0; j < 4; ++j) { e[j] = ::fexp2(-LOG2E * v0[j]); e[4 + j] = ::fexp2(-LOG2E * v1[j]); }
;                         __builtin_amdgcn_sched_barrier(0);
; #pragma unroll
;                         for (int j = 0; j < 8; ++j) e[j] = ::frcp(1.f + e[j]);
;                         __builtin_amdgcn_sched_barrier(0);
; #pragma unroll
;                         for (int j = 0; j < 4; ++j) { v0[j] = e[j]; v1[j] = e[4 + j]; }
;                     } else { v0 = v0 * sc; v1 = v1 * sc; }
;                     u32x4 w; w.x = ::pk2(v0[0], v0[1]); w.y = ::pk2(v0[2], v0[3]); w.z = ::pk2(v1[0], v1[1]); w.w = ::pk2(v1[2], v1[3]);
;                     *(u32x4*)(rowp + bj * HALF) = w;
;                 }
.LBB0_259:
	v_cvt_f32_u32_e32 v130, v169
	v_cvt_pk_bf16_f32 v128, v116, v117
	v_cvt_pk_bf16_f32 v129, v118, v119
	v_cvt_pk_bf16_f32 v131, v122, v123
	v_mul_f32_e32 v116, 0x3a800000, v130
	v_fmamk_f32 v116, v116, 0x3a800000, v175
	v_rsq_f32_e32 v116, v116
	v_cvt_pk_bf16_f32 v130, v120, v121
	global_store_dwordx4 v[126:127], v[128:131], off offset:256 sc1
	s_and_b64 vcc, exec, s[42:43]
	v_pk_mul_f32 v[118:119], v[114:115], v[116:117] op_sel_hi:[1,0]
	v_pk_mul_f32 v[122:123], v[112:113], v[116:117] op_sel_hi:[1,0]
	v_pk_mul_f32 v[120:121], v[110:111], v[116:117] op_sel_hi:[1,0]
	v_pk_mul_f32 v[126:127], v[108:109], v[116:117] op_sel_hi:[1,0]
	s_mov_b64 s[76:77], -1
	s_cbranch_vccnz .LBB0_261
	v_mov_b32_e32 v112, v154
	v_mov_b32_e32 v113, v154
	v_pk_mul_f32 v[110:111], v[112:113], v[118:119]
	v_pk_mul_f32 v[108:109], v[154:155], v[122:123]
	v_pk_mul_f32 v[114:115], v[112:113], v[120:121]
	v_pk_mul_f32 v[112:113], v[154:155], v[126:127]
	s_mov_b64 s[76:77], 0

; __device__ __forceinline__ unsigned pk2(float lo, float hi) { f32x2 v = {lo, hi}; bf16x2_t b = __builtin_convertvector(v, bf16x2_t); return __builtin_bit_cast(unsigned, b); }
; __device__ __forceinline__ float fexp2(float x) { return __builtin_amdgcn_exp2f(x); }
; __device__ __forceinline__ float frcp(float x) { return __builtin_amdgcn_rcpf(x); }
;     __device__ __forceinline__ void operator()(const f32x4 (&acc)[2][2][4][2], const Unit& u, int wr, int wc, int fr, int fq) const {
;     ...
;         for (int ai = 0; ai < 2; ++ai)
; #pragma unroll
;             for (int m = 0; m < 4; ++m) {
;                 bf16_t* rowp = base + (size_t)(row0 + ai * HALF + m * 16) * ld + col0;
;                 const float rs = __builtin_amdgcn_rsqf(rsv[ai][m] * (1.f / 1024.f) + 1e-6f);
; #pragma unroll
;                 for (int bj = 0; bj < 2; ++bj) {
;                     f32x4 v0 = acc[ai][bj][m][0] * rs, v1 = acc[ai][bj][m][1] * rs;
;                     if (sig) {
;                         float e[8];
;                         __builtin_amdgcn_sched_barrier(0);
; #pragma unroll
;                         for (int j = 0; j < 4; ++j) { e[j] = ::fexp2(-LOG2E * v0[j]); e[4 + j] = ::fexp2(-LOG2E * v1[j]); }
;                         __builtin_amdgcn_sched_barrier(0);
; #pragma unroll
;                         for (int j = 0; j < 8; ++j) e[j] = ::frcp(1.f + e[j]);
;                         __builtin_amdgcn_sched_barrier(0);
; #pragma unroll
;                         for (int j = 0; j < 4; ++j) { v0[j] = e[j]; v1[j] = e[4 + j]; }
;                     } else { v0 = v0 * sc; v1 = v1 * sc; }
;                     u32x4 w; w.x = ::pk2(v0[0], v0[1]); w.y = ::pk2(v0[2], v0[3]); w.z = ::pk2(v1[0], v1[1]); w.w = ::pk2(v1[2], v1[3]);
;                     *(u32x4*)(rowp + bj * HALF) = w;
;                 }
.LBB0_263:
	v_or_b32_e32 v118, 16, v156
	v_mul_lo_u32 v121, s75, v118
	v_mul_lo_u32 v120, s74, v157
	v_mad_u64_u32 v[118:119], s[64:65], s74, v118, 0
	v_add3_u32 v119, v119, v120, v121
	v_lshl_add_u64 v[118:119], v[118:119], 1, v[124:125]
	v_cvt_pk_bf16_f32 v108, v108, v109
	v_cvt_pk_bf16_f32 v109, v110, v111
	v_cvt_pk_bf16_f32 v110, v112, v113
	v_cvt_pk_bf16_f32 v111, v114, v115
	v_mov_b32_e32 v117, v116
	global_store_dwordx4 v[118:119], v[108:111], off sc1
	v_pk_mul_f32 v[112:113], v[104:105], v[116:117]
	v_pk_mul_f32 v[114:115], v[100:101], v[116:117]
	v_mov_b32_e32 v110, v116
	v_mov_b32_e32 v111, v116
	v_pk_mul_f32 v[108:109], v[106:107], v[110:111]
	v_pk_mul_f32 v[110:111], v[102:103], v[110:111]
	s_and_b64 vcc, exec, s[42:43]
	s_mov_b64 s[76:77], -1
	s_cbranch_vccnz .LBB0_265
	v_mov_b32_e32 v104, v154
	v_mov_b32_e32 v105, v154
	v_pk_mul_f32 v[102:103], v[104:105], v[108:109]
	v_pk_mul_f32 v[100:101], v[154:155], v[112:113]
	v_pk_mul_f32 v[106:107], v[104:105], v[110:111]
	v_pk_mul_f32 v[104:105], v[154:155], v[114:115]
	s_mov_b64 s[76:77], 0

; __device__ __forceinline__ unsigned pk2(float lo, float hi) { f32x2 v = {lo, hi}; bf16x2_t b = __builtin_convertvector(v, bf16x2_t); return __builtin_bit_cast(unsigned, b); }
; __device__ __forceinline__ float fexp2(float x) { return __builtin_amdgcn_exp2f(x); }
; __device__ __forceinline__ float frcp(float x) { return __builtin_amdgcn_rcpf(x); }
;     __device__ __forceinline__ void operator()(const f32x4 (&acc)[2][2][4][2], const Unit& u, int wr, int wc, int fr, int fq) const {
;     ...
;             for (int m = 0; m < 4; ++m) rsv[ai][m] = (float)RS[row0 + ai * HALF + m * 16] * (1.f / 1024.f);
; #pragma unroll
;         for (int ai = 0; ai < 2; ++ai)
; #pragma unroll
;             for (int m = 0; m < 4; ++m) {
;                 bf16_t* rowp = base + (size_t)(row0 + ai * HALF + m * 16) * ld + col0;
;                 const float rs = __builtin_amdgcn_rsqf(rsv[ai][m] * (1.f / 1024.f) + 1e-6f);
; #pragma unroll
;                 for (int bj = 0; bj < 2; ++bj) {
;                     f32x4 v0 = acc[ai][bj][m][0] * rs, v1 = acc[ai][bj][m][1] * rs;
;                     if (sig) {
;                         float e[8];
;                         __builtin_amdgcn_sched_barrier(0);
; #pragma unroll
;                         for (int j = 0; j < 4; ++j) { e[j] = ::fexp2(-LOG2E * v0[j]); e[4 + j] = ::fexp2(-LOG2E * v1[j]); }
;                         __builtin_amdgcn_sched_barrier(0);
; #pragma unroll
;                         for (int j = 0; j < 8; ++j) e[j] = ::frcp(1.f + e[j]);
;                         __builtin_amdgcn_sched_barrier(0);
; #pragma unroll
;                         for (int j = 0; j < 4; ++j) { v0[j] = e[j]; v1[j] = e[4 + j]; }
;                     } else { v0 = v0 * sc; v1 = v1 * sc; }
;                     u32x4 w; w.x = ::pk2(v0[0], v0[1]); w.y = ::pk2(v0[2], v0[3]); w.z = ::pk2(v1[0], v1[1]); w.w = ::pk2(v1[2], v1[3]);
;                     *(u32x4*)(rowp + bj * HALF) = w;
;                 }
.LBB0_267:
	v_cvt_f32_u32_e32 v110, v168
	v_cvt_pk_bf16_f32 v108, v100, v101
	v_cvt_pk_bf16_f32 v109, v102, v103
	v_cvt_pk_bf16_f32 v111, v106, v107
	v_mul_f32_e32 v100, 0x3a800000, v110
	v_fmamk_f32 v100, v100, 0x3a800000, v175
	v_rsq_f32_e32 v100, v100
	v_cvt_pk_bf16_f32 v110, v104, v105
	global_store_dwordx4 v[118:119], v[108:111], off offset:256 sc1
	s_and_b64 vcc, exec, s[42:43]
	v_pk_mul_f32 v[102:103], v[98:99], v[100:101] op_sel_hi:[1,0]
	v_pk_mul_f32 v[106:107], v[96:97], v[100:101] op_sel_hi:[1,0]
	v_pk_mul_f32 v[104:105], v[94:95], v[100:101] op_sel_hi:[1,0]
	v_pk_mul_f32 v[108:109], v[92:93], v[100:101] op_sel_hi:[1,0]
	s_mov_b64 s[76:77], -1
	s_cbranch_vccnz .LBB0_269
	v_mov_b32_e32 v96, v154
	v_mov_b32_e32 v97, v154
	v_pk_mul_f32 v[94:95], v[96:97], v[102:103]
	v_pk_mul_f32 v[92:93], v[154:155], v[106:107]
	v_pk_mul_f32 v[98:99], v[96:97], v[104:105]
	v_pk_mul_f32 v[96:97], v[154:155], v[108:109]
	s_mov_b64 s[76:77], 0

; __device__ __forceinline__ unsigned pk2(float lo, float hi) { f32x2 v = {lo, hi}; bf16x2_t b = __builtin_convertvector(v, bf16x2_t); return __builtin_bit_cast(unsigned, b); }
; __device__ __forceinline__ float fexp2(float x) { return __builtin_amdgcn_exp2f(x); }
; __device__ __forceinline__ float frcp(float x) { return __builtin_amdgcn_rcpf(x); }
;     __device__ __forceinline__ void operator()(const f32x4 (&acc)[2][2][4][2], const Unit& u, int wr, int wc, int fr, int fq) const {
;     ...
;         for (int ai = 0; ai < 2; ++ai)
; #pragma unroll
;             for (int m = 0; m < 4; ++m) {
;                 bf16_t* rowp = base + (size_t)(row0 + ai * HALF + m * 16) * ld + col0;
;                 const float rs = __builtin_amdgcn_rsqf(rsv[ai][m] * (1.f / 1024.f) + 1e-6f);
; #pragma unroll
;                 for (int bj = 0; bj < 2; ++bj) {
;                     f32x4 v0 = acc[ai][bj][m][0] * rs, v1 = acc[ai][bj][m][1] * rs;
;                     if (sig) {
;                         float e[8];
;                         __builtin_amdgcn_sched_barrier(0);
; #pragma unroll
;                         for (int j = 0; j < 4; ++j) { e[j] = ::fexp2(-LOG2E * v0[j]); e[4 + j] = ::fexp2(-LOG2E * v1[j]); }
;                         __builtin_amdgcn_sched_barrier(0);
; #pragma unroll
;                         for (int j = 0; j < 8; ++j) e[j] = ::frcp(1.f + e[j]);
;                         __builtin_amdgcn_sched_barrier(0);
; #pragma unroll
;                         for (int j = 0; j < 4; ++j) { v0[j] = e[j]; v1[j] = e[4 + j]; }
;                     } else { v0 = v0 * sc; v1 = v1 * sc; }
;                     u32x4 w; w.x = ::pk2(v0[0], v0[1]); w.y = ::pk2(v0[2], v0[3]); w.z = ::pk2(v1[0], v1[1]); w.w = ::pk2(v1[2], v1[3]);
;                     *(u32x4*)(rowp + bj * HALF) = w;
;                 }
.LBB0_271:
	v_or_b32_e32 v102, 32, v156
	v_mul_lo_u32 v104, s75, v102
	v_mad_u64_u32 v[102:103], s[64:65], s74, v102, 0
	v_add3_u32 v103, v103, v120, v104
	v_lshl_add_u64 v[102:103], v[102:103], 1, v[124:125]
	v_cvt_pk_bf16_f32 v92, v92, v93
	v_cvt_pk_bf16_f32 v93, v94, v95
	v_cvt_pk_bf16_f32 v94, v96, v97
	v_cvt_pk_bf16_f32 v95, v98, v99
	v_mov_b32_e32 v101, v100
	global_store_dwordx4 v[102:103], v[92:95], off sc1
	v_pk_mul_f32 v[96:97], v[88:89], v[100:101]
	v_pk_mul_f32 v[98:99], v[84:85], v[100:101]
	v_mov_b32_e32 v94, v100
	v_mov_b32_e32 v95, v100
	v_pk_mul_f32 v[92:93], v[90:91], v[94:95]
	v_pk_mul_f32 v[94:95], v[86:87], v[94:95]
	s_and_b64 vcc, exec, s[42:43]
	s_mov_b64 s[76:77], -1
	s_cbranch_vccnz .LBB0_273
	v_mov_b32_e32 v88, v154
	v_mov_b32_e32 v89, v154
	v_pk_mul_f32 v[86:87], v[88:89], v[92:93]
	v_pk_mul_f32 v[84:85], v[154:155], v[96:97]
	v_pk_mul_f32 v[90:91], v[88:89], v[94:95]
	v_pk_mul_f32 v[88:89], v[154:155], v[98:99]
	s_mov_b64 s[76:77], 0

; __device__ __forceinline__ unsigned pk2(float lo, float hi) { f32x2 v = {lo, hi}; bf16x2_t b = __builtin_convertvector(v, bf16x2_t); return __builtin_bit_cast(unsigned, b); }
; __device__ __forceinline__ float fexp2(float x) { return __builtin_amdgcn_exp2f(x); }
; __device__ __forceinline__ float frcp(float x) { return __builtin_amdgcn_rcpf(x); }
;     __device__ __forceinline__ void operator()(const f32x4 (&acc)[2][2][4][2], const Unit& u, int wr, int wc, int fr, int fq) const {
;     ...
;             for (int m = 0; m < 4; ++m) rsv[ai][m] = (float)RS[row0 + ai * HALF + m * 16] * (1.f / 1024.f);
; #pragma unroll
;         for (int ai = 0; ai < 2; ++ai)
; #pragma unroll
;             for (int m = 0; m < 4; ++m) {
;                 bf16_t* rowp = base + (size_t)(row0 + ai * HALF + m * 16) * ld + col0;
;                 const float rs = __builtin_amdgcn_rsqf(rsv[ai][m] * (1.f / 1024.f) + 1e-6f);
; #pragma unroll
;                 for (int bj = 0; bj < 2; ++bj) {
;                     f32x4 v0 = acc[ai][bj][m][0] * rs, v1 = acc[ai][bj][m][1] * rs;
;                     if (sig) {
;                         float e[8];
;                         __builtin_amdgcn_sched_barrier(0);
; #pragma unroll
;                         for (int j = 0; j < 4; ++j) { e[j] = ::fexp2(-LOG2E * v0[j]); e[4 + j] = ::fexp2(-LOG2E * v1[j]); }
;                         __builtin_amdgcn_sched_barrier(0);
; #pragma unroll
;                         for (int j = 0; j < 8; ++j) e[j] = ::frcp(1.f + e[j]);
;                         __builtin_amdgcn_sched_barrier(0);
; #pragma unroll
;                         for (int j = 0; j < 4; ++j) { v0[j] = e[j]; v1[j] = e[4 + j]; }
;                     } else { v0 = v0 * sc; v1 = v1 * sc; }
;                     u32x4 w; w.x = ::pk2(v0[0], v0[1]); w.y = ::pk2(v0[2], v0[3]); w.z = ::pk2(v1[0], v1[1]); w.w = ::pk2(v1[2], v1[3]);
;                     *(u32x4*)(rowp + bj * HALF) = w;
;                 }
.LBB0_275:
	v_cvt_f32_u32_e32 v94, v167
	v_cvt_pk_bf16_f32 v92, v84, v85
	v_cvt_pk_bf16_f32 v93, v86, v87
	v_cvt_pk_bf16_f32 v95, v90, v91
	v_mul_f32_e32 v84, 0x3a800000, v94
	v_fmamk_f32 v84, v84, 0x3a800000, v175
	v_rsq_f32_e32 v84, v84
	v_cvt_pk_bf16_f32 v94, v88, v89
	global_store_dwordx4 v[102:103], v[92:95], off offset:256 sc1
	s_and_b64 vcc, exec, s[42:43]
	v_pk_mul_f32 v[86:87], v[82:83], v[84:85] op_sel_hi:[1,0]
	v_pk_mul_f32 v[90:91], v[80:81], v[84:85] op_sel_hi:[1,0]
	v_pk_mul_f32 v[88:89], v[78:79], v[84:85] op_sel_hi:[1,0]
	v_pk_mul_f32 v[92:93], v[76:77], v[84:85] op_sel_hi:[1,0]
	s_mov_b64 s[76:77], -1
	s_cbranch_vccnz .LBB0_277
	v_mov_b32_e32 v80, v154
	v_mov_b32_e32 v81, v154
	v_pk_mul_f32 v[78:79], v[80:81], v[86:87]
	v_pk_mul_f32 v[76:77], v[154:155], v[90:91]
	v_pk_mul_f32 v[82:83], v[80:81], v[88:89]
	v_pk_mul_f32 v[80:81], v[154:155], v[92:93]
	s_mov_b64 s[76:77], 0

; __device__ __forceinline__ unsigned pk2(float lo, float hi) { f32x2 v = {lo, hi}; bf16x2_t b = __builtin_convertvector(v, bf16x2_t); return __builtin_bit_cast(unsigned, b); }
; __device__ __forceinline__ float fexp2(float x) { return __builtin_amdgcn_exp2f(x); }
; __device__ __forceinline__ float frcp(float x) { return __builtin_amdgcn_rcpf(x); }
;     __device__ __forceinline__ void operator()(const f32x4 (&acc)[2][2][4][2], const Unit& u, int wr, int wc, int fr, int fq) const {
;     ...
;         for (int ai = 0; ai < 2; ++ai)
; #pragma unroll
;             for (int m = 0; m < 4; ++m) {
;                 bf16_t* rowp = base + (size_t)(row0 + ai * HALF + m * 16) * ld + col0;
;                 const float rs = __builtin_amdgcn_rsqf(rsv[ai][m] * (1.f / 1024.f) + 1e-6f);
; #pragma unroll
;                 for (int bj = 0; bj < 2; ++bj) {
;                     f32x4 v0 = acc[ai][bj][m][0] * rs, v1 = acc[ai][bj][m][1] * rs;
;                     if (sig) {
;                         float e[8];
;                         __builtin_amdgcn_sched_barrier(0);
; #pragma unroll
;                         for (int j = 0; j < 4; ++j) { e[j] = ::fexp2(-LOG2E * v0[j]); e[4 + j] = ::fexp2(-LOG2E * v1[j]); }
;                         __builtin_amdgcn_sched_barrier(0);
; #pragma unroll
;                         for (int j = 0; j < 8; ++j) e[j] = ::frcp(1.f + e[j]);
;                         __builtin_amdgcn_sched_barrier(0);
; #pragma unroll
;                         for (int j = 0; j < 4; ++j) { v0[j] = e[j]; v1[j] = e[4 + j]; }
;                     } else { v0 = v0 * sc; v1 = v1 * sc; }
;                     u32x4 w; w.x = ::pk2(v0[0], v0[1]); w.y = ::pk2(v0[2], v0[3]); w.z = ::pk2(v1[0], v1[1]); w.w = ::pk2(v1[2], v1[3]);
;                     *(u32x4*)(rowp + bj * HALF) = w;
;                 }
.LBB0_279:
	v_or_b32_e32 v86, 48, v156
	v_mul_lo_u32 v88, s75, v86
	v_mad_u64_u32 v[86:87], s[64:65], s74, v86, 0
	v_add3_u32 v87, v87, v120, v88
	v_lshl_add_u64 v[86:87], v[86:87], 1, v[124:125]
	v_cvt_pk_bf16_f32 v76, v76, v77
	v_cvt_pk_bf16_f32 v77, v78, v79
	v_cvt_pk_bf16_f32 v78, v80, v81
	v_cvt_pk_bf16_f32 v79, v82, v83
	v_mov_b32_e32 v85, v84
	global_store_dwordx4 v[86:87], v[76:79], off sc1
	v_pk_mul_f32 v[80:81], v[72:73], v[84:85]
	v_pk_mul_f32 v[82:83], v[68:69], v[84:85]
	v_mov_b32_e32 v78, v84
	v_mov_b32_e32 v79, v84
	v_pk_mul_f32 v[76:77], v[74:75], v[78:79]
	v_pk_mul_f32 v[78:79], v[70:71], v[78:79]
	s_and_b64 vcc, exec, s[42:43]
	s_mov_b64 s[76:77], -1
	s_cbranch_vccnz .LBB0_281
	v_mov_b32_e32 v72, v154
	v_mov_b32_e32 v73, v154
	v_pk_mul_f32 v[70:71], v[72:73], v[76:77]
	v_pk_mul_f32 v[68:69], v[154:155], v[80:81]
	v_pk_mul_f32 v[74:75], v[72:73], v[78:79]
	v_pk_mul_f32 v[72:73], v[154:155], v[82:83]
	s_mov_b64 s[76:77], 0

; __device__ __forceinline__ unsigned pk2(float lo, float hi) { f32x2 v = {lo, hi}; bf16x2_t b = __builtin_convertvector(v, bf16x2_t); return __builtin_bit_cast(unsigned, b); }
; __device__ __forceinline__ float fexp2(float x) { return __builtin_amdgcn_exp2f(x); }
; __device__ __forceinline__ float frcp(float x) { return __builtin_amdgcn_rcpf(x); }
;     __device__ __forceinline__ void operator()(const f32x4 (&acc)[2][2][4][2], const Unit& u, int wr, int wc, int fr, int fq) const {
;     ...
;             for (int m = 0; m < 4; ++m) rsv[ai][m] = (float)RS[row0 + ai * HALF + m * 16] * (1.f / 1024.f);
; #pragma unroll
;         for (int ai = 0; ai < 2; ++ai)
; #pragma unroll
;             for (int m = 0; m < 4; ++m) {
;                 bf16_t* rowp = base + (size_t)(row0 + ai * HALF + m * 16) * ld + col0;
;                 const float rs = __builtin_amdgcn_rsqf(rsv[ai][m] * (1.f / 1024.f) + 1e-6f);
; #pragma unroll
;                 for (int bj = 0; bj < 2; ++bj) {
;                     f32x4 v0 = acc[ai][bj][m][0] * rs, v1 = acc[ai][bj][m][1] * rs;
;                     if (sig) {
;                         float e[8];
;                         __builtin_amdgcn_sched_barrier(0);
; #pragma unroll
;                         for (int j = 0; j < 4; ++j) { e[j] = ::fexp2(-LOG2E * v0[j]); e[4 + j] = ::fexp2(-LOG2E * v1[j]); }
;                         __builtin_amdgcn_sched_barrier(0);
; #pragma unroll
;                         for (int j = 0; j < 8; ++j) e[j] = ::frcp(1.f + e[j]);
;                         __builtin_amdgcn_sched_barrier(0);
; #pragma unroll
;                         for (int j = 0; j < 4; ++j) { v0[j] = e[j]; v1[j] = e[4 + j]; }
;                     } else { v0 = v0 * sc; v1 = v1 * sc; }
;                     u32x4 w; w.x = ::pk2(v0[0], v0[1]); w.y = ::pk2(v0[2], v0[3]); w.z = ::pk2(v1[0], v1[1]); w.w = ::pk2(v1[2], v1[3]);
;                     *(u32x4*)(rowp + bj * HALF) = w;
;                 }
.LBB0_283:
	v_cvt_f32_u32_e32 v78, v166
	v_cvt_pk_bf16_f32 v76, v68, v69
	v_cvt_pk_bf16_f32 v77, v70, v71
	v_cvt_pk_bf16_f32 v79, v74, v75
	v_mul_f32_e32 v68, 0x3a800000, v78
	v_fmamk_f32 v68, v68, 0x3a800000, v175
	v_rsq_f32_e32 v68, v68
	v_cvt_pk_bf16_f32 v78, v72, v73
	global_store_dwordx4 v[86:87], v[76:79], off offset:256 sc1
	s_and_b64 vcc, exec, s[42:43]
	v_pk_mul_f32 v[70:71], v[66:67], v[68:69] op_sel_hi:[1,0]
	v_pk_mul_f32 v[74:75], v[64:65], v[68:69] op_sel_hi:[1,0]
	v_pk_mul_f32 v[72:73], v[62:63], v[68:69] op_sel_hi:[1,0]
	v_pk_mul_f32 v[76:77], v[60:61], v[68:69] op_sel_hi:[1,0]
	s_mov_b64 s[76:77], -1
	s_cbranch_vccnz .LBB0_285
	v_mov_b32_e32 v64, v154
	v_mov_b32_e32 v65, v154
	v_pk_mul_f32 v[62:63], v[64:65], v[70:71]
	v_pk_mul_f32 v[60:61], v[154:155], v[74:75]
	v_pk_mul_f32 v[66:67], v[64:65], v[72:73]
	v_pk_mul_f32 v[64:65], v[154:155], v[76:77]
	s_mov_b64 s[76:77], 0

; __device__ __forceinline__ unsigned pk2(float lo, float hi) { f32x2 v = {lo, hi}; bf16x2_t b = __builtin_convertvector(v, bf16x2_t); return __builtin_bit_cast(unsigned, b); }
; __device__ __forceinline__ float fexp2(float x) { return __builtin_amdgcn_exp2f(x); }
; __device__ __forceinline__ float frcp(float x) { return __builtin_amdgcn_rcpf(x); }
;     __device__ __forceinline__ void operator()(const f32x4 (&acc)[2][2][4][2], const Unit& u, int wr, int wc, int fr, int fq) const {
;     ...
;         for (int ai = 0; ai < 2; ++ai)
; #pragma unroll
;             for (int m = 0; m < 4; ++m) {
;                 bf16_t* rowp = base + (size_t)(row0 + ai * HALF + m * 16) * ld + col0;
;                 const float rs = __builtin_amdgcn_rsqf(rsv[ai][m] * (1.f / 1024.f) + 1e-6f);
; #pragma unroll
;                 for (int bj = 0; bj < 2; ++bj) {
;                     f32x4 v0 = acc[ai][bj][m][0] * rs, v1 = acc[ai][bj][m][1] * rs;
;                     if (sig) {
;                         float e[8];
;                         __builtin_amdgcn_sched_barrier(0);
; #pragma unroll
;                         for (int j = 0; j < 4; ++j) { e[j] = ::fexp2(-LOG2E * v0[j]); e[4 + j] = ::fexp2(-LOG2E * v1[j]); }
;                         __builtin_amdgcn_sched_barrier(0);
; #pragma unroll
;                         for (int j = 0; j < 8; ++j) e[j] = ::frcp(1.f + e[j]);
;                         __builtin_amdgcn_sched_barrier(0);
; #pragma unroll
;                         for (int j = 0; j < 4; ++j) { v0[j] = e[j]; v1[j] = e[4 + j]; }
;                     } else { v0 = v0 * sc; v1 = v1 * sc; }
;                     u32x4 w; w.x = ::pk2(v0[0], v0[1]); w.y = ::pk2(v0[2], v0[3]); w.z = ::pk2(v1[0], v1[1]); w.w = ::pk2(v1[2], v1[3]);
;                     *(u32x4*)(rowp + bj * HALF) = w;
;                 }
.LBB0_287:
	v_add_u32_e32 v70, 0x80, v156
	v_ashrrev_i32_e32 v71, 31, v70
	v_mul_lo_u32 v72, s74, v71
	v_mul_lo_u32 v73, s75, v70
	v_mad_u64_u32 v[70:71], s[64:65], s74, v70, 0
	v_add3_u32 v71, v71, v72, v73
	v_lshl_add_u64 v[70:71], v[70:71], 1, v[124:125]
	v_cvt_pk_bf16_f32 v60, v60, v61
	v_cvt_pk_bf16_f32 v61, v62, v63
	v_cvt_pk_bf16_f32 v62, v64, v65
	v_cvt_pk_bf16_f32 v63, v66, v67
	v_mov_b32_e32 v69, v68
	global_store_dwordx4 v[70:71], v[60:63], off sc1
	v_pk_mul_f32 v[64:65], v[56:57], v[68:69]
	v_pk_mul_f32 v[66:67], v[52:53], v[68:69]
	v_mov_b32_e32 v62, v68
	v_mov_b32_e32 v63, v68
	v_pk_mul_f32 v[60:61], v[58:59], v[62:63]
	v_pk_mul_f32 v[62:63], v[54:55], v[62:63]
	s_and_b64 vcc, exec, s[42:43]
	s_mov_b64 s[76:77], -1
	s_cbranch_vccnz .LBB0_289
	v_mov_b32_e32 v56, v154
	v_mov_b32_e32 v57, v154
	v_pk_mul_f32 v[54:55], v[56:57], v[60:61]
	v_pk_mul_f32 v[52:53], v[154:155], v[64:65]
	v_pk_mul_f32 v[58:59], v[56:57], v[62:63]
	v_pk_mul_f32 v[56:57], v[154:155], v[66:67]
	s_mov_b64 s[76:77], 0

; __device__ __forceinline__ unsigned pk2(float lo, float hi) { f32x2 v = {lo, hi}; bf16x2_t b = __builtin_convertvector(v, bf16x2_t); return __builtin_bit_cast(unsigned, b); }
; __device__ __forceinline__ float fexp2(float x) { return __builtin_amdgcn_exp2f(x); }
; __device__ __forceinline__ float frcp(float x) { return __builtin_amdgcn_rcpf(x); }
;     __device__ __forceinline__ void operator()(const f32x4 (&acc)[2][2][4][2], const Unit& u, int wr, int wc, int fr, int fq) const {
;     ...
;             for (int m = 0; m < 4; ++m) rsv[ai][m] = (float)RS[row0 + ai * HALF + m * 16] * (1.f / 1024.f);
; #pragma unroll
;         for (int ai = 0; ai < 2; ++ai)
; #pragma unroll
;             for (int m = 0; m < 4; ++m) {
;                 bf16_t* rowp = base + (size_t)(row0 + ai * HALF + m * 16) * ld + col0;
;                 const float rs = __builtin_amdgcn_rsqf(rsv[ai][m] * (1.f / 1024.f) + 1e-6f);
; #pragma unroll
;                 for (int bj = 0; bj < 2; ++bj) {
;                     f32x4 v0 = acc[ai][bj][m][0] * rs, v1 = acc[ai][bj][m][1] * rs;
;                     if (sig) {
;                         float e[8];
;                         __builtin_amdgcn_sched_barrier(0);
; #pragma unroll
;                         for (int j = 0; j < 4; ++j) { e[j] = ::fexp2(-LOG2E * v0[j]); e[4 + j] = ::fexp2(-LOG2E * v1[j]); }
;                         __builtin_amdgcn_sched_barrier(0);
; #pragma unroll
;                         for (int j = 0; j < 8; ++j) e[j] = ::frcp(1.f + e[j]);
;                         __builtin_amdgcn_sched_barrier(0);
; #pragma unroll
;                         for (int j = 0; j < 4; ++j) { v0[j] = e[j]; v1[j] = e[4 + j]; }
;                     } else { v0 = v0 * sc; v1 = v1 * sc; }
;                     u32x4 w; w.x = ::pk2(v0[0], v0[1]); w.y = ::pk2(v0[2], v0[3]); w.z = ::pk2(v1[0], v1[1]); w.w = ::pk2(v1[2], v1[3]);
;                     *(u32x4*)(rowp + bj * HALF) = w;
;                 }
.LBB0_291:
	v_cvt_f32_u32_e32 v62, v165
	v_cvt_pk_bf16_f32 v60, v52, v53
	v_cvt_pk_bf16_f32 v61, v54, v55
	v_cvt_pk_bf16_f32 v63, v58, v59
	v_mul_f32_e32 v52, 0x3a800000, v62
	v_fmamk_f32 v52, v52, 0x3a800000, v175
	v_rsq_f32_e32 v52, v52
	v_cvt_pk_bf16_f32 v62, v56, v57
	global_store_dwordx4 v[70:71], v[60:63], off offset:256 sc1
	s_and_b64 vcc, exec, s[42:43]
	v_pk_mul_f32 v[54:55], v[50:51], v[52:53] op_sel_hi:[1,0]
	v_pk_mul_f32 v[58:59], v[48:49], v[52:53] op_sel_hi:[1,0]
	v_pk_mul_f32 v[56:57], v[46:47], v[52:53] op_sel_hi:[1,0]
	v_pk_mul_f32 v[60:61], v[44:45], v[52:53] op_sel_hi:[1,0]
	s_mov_b64 s[76:77], -1
	s_cbranch_vccnz .LBB0_293
	v_mov_b32_e32 v48, v154
	v_mov_b32_e32 v49, v154
	v_pk_mul_f32 v[46:47], v[48:49], v[54:55]
	v_pk_mul_f32 v[44:45], v[154:155], v[58:59]
	v_pk_mul_f32 v[50:51], v[48:49], v[56:57]
	v_pk_mul_f32 v[48:49], v[154:155], v[60:61]
	s_mov_b64 s[76:77], 0

; __device__ __forceinline__ unsigned pk2(float lo, float hi) { f32x2 v = {lo, hi}; bf16x2_t b = __builtin_convertvector(v, bf16x2_t); return __builtin_bit_cast(unsigned, b); }
; __device__ __forceinline__ float fexp2(float x) { return __builtin_amdgcn_exp2f(x); }
; __device__ __forceinline__ float frcp(float x) { return __builtin_amdgcn_rcpf(x); }
;     __device__ __forceinline__ void operator()(const f32x4 (&acc)[2][2][4][2], const Unit& u, int wr, int wc, int fr, int fq) const {
;     ...
;         for (int ai = 0; ai < 2; ++ai)
; #pragma unroll
;             for (int m = 0; m < 4; ++m) {
;                 bf16_t* rowp = base + (size_t)(row0 + ai * HALF + m * 16) * ld + col0;
;                 const float rs = __builtin_amdgcn_rsqf(rsv[ai][m] * (1.f / 1024.f) + 1e-6f);
; #pragma unroll
;                 for (int bj = 0; bj < 2; ++bj) {
;                     f32x4 v0 = acc[ai][bj][m][0] * rs, v1 = acc[ai][bj][m][1] * rs;
;                     if (sig) {
;                         float e[8];
;                         __builtin_amdgcn_sched_barrier(0);
; #pragma unroll
;                         for (int j = 0; j < 4; ++j) { e[j] = ::fexp2(-LOG2E * v0[j]); e[4 + j] = ::fexp2(-LOG2E * v1[j]); }
;                         __builtin_amdgcn_sched_barrier(0);
; #pragma unroll
;                         for (int j = 0; j < 8; ++j) e[j] = ::frcp(1.f + e[j]);
;                         __builtin_amdgcn_sched_barrier(0);
; #pragma unroll
;                         for (int j = 0; j < 4; ++j) { v0[j] = e[j]; v1[j] = e[4 + j]; }
;                     } else { v0 = v0 * sc; v1 = v1 * sc; }
;                     u32x4 w; w.x = ::pk2(v0[0], v0[1]); w.y = ::pk2(v0[2], v0[3]); w.z = ::pk2(v1[0], v1[1]); w.w = ::pk2(v1[2], v1[3]);
;                     *(u32x4*)(rowp + bj * HALF) = w;
;                 }
.LBB0_295:
	v_add_u32_e32 v54, 0x90, v156
	v_ashrrev_i32_e32 v55, 31, v54
	v_mul_lo_u32 v56, s74, v55
	v_mul_lo_u32 v57, s75, v54
	v_mad_u64_u32 v[54:55], s[64:65], s74, v54, 0
	v_add3_u32 v55, v55, v56, v57
	v_lshl_add_u64 v[54:55], v[54:55], 1, v[124:125]
	v_cvt_pk_bf16_f32 v44, v44, v45
	v_cvt_pk_bf16_f32 v45, v46, v47
	v_cvt_pk_bf16_f32 v46, v48, v49
	v_cvt_pk_bf16_f32 v47, v50, v51
	v_mov_b32_e32 v53, v52
	global_store_dwordx4 v[54:55], v[44:47], off sc1
	v_pk_mul_f32 v[48:49], v[40:41], v[52:53]
	v_pk_mul_f32 v[50:51], v[36:37], v[52:53]
	v_mov_b32_e32 v46, v52
	v_mov_b32_e32 v47, v52
	v_pk_mul_f32 v[44:45], v[42:43], v[46:47]
	v_pk_mul_f32 v[46:47], v[38:39], v[46:47]
	s_and_b64 vcc, exec, s[42:43]
	s_mov_b64 s[76:77], -1
	s_cbranch_vccnz .LBB0_297
	v_mov_b32_e32 v40, v154
	v_mov_b32_e32 v41, v154
	v_pk_mul_f32 v[38:39], v[40:41], v[44:45]
	v_pk_mul_f32 v[36:37], v[154:155], v[48:49]
	v_pk_mul_f32 v[42:43], v[40:41], v[46:47]
	v_pk_mul_f32 v[40:41], v[154:155], v[50:51]
	s_mov_b64 s[76:77], 0

; __device__ __forceinline__ unsigned pk2(float lo, float hi) { f32x2 v = {lo, hi}; bf16x2_t b = __builtin_convertvector(v, bf16x2_t); return __builtin_bit_cast(unsigned, b); }
; __device__ __forceinline__ float fexp2(float x) { return __builtin_amdgcn_exp2f(x); }
; __device__ __forceinline__ float frcp(float x) { return __builtin_amdgcn_rcpf(x); }
;     __device__ __forceinline__ void operator()(const f32x4 (&acc)[2][2][4][2], const Unit& u, int wr, int wc, int fr, int fq) const {
;     ...
;             for (int m = 0; m < 4; ++m) rsv[ai][m] = (float)RS[row0 + ai * HALF + m * 16] * (1.f / 1024.f);
; #pragma unroll
;         for (int ai = 0; ai < 2; ++ai)
; #pragma unroll
;             for (int m = 0; m < 4; ++m) {
;                 bf16_t* rowp = base + (size_t)(row0 + ai * HALF + m * 16) * ld + col0;
;                 const float rs = __builtin_amdgcn_rsqf(rsv[ai][m] * (1.f / 1024.f) + 1e-6f);
; #pragma unroll
;                 for (int bj = 0; bj < 2; ++bj) {
;                     f32x4 v0 = acc[ai][bj][m][0] * rs, v1 = acc[ai][bj][m][1] * rs;
;                     if (sig) {
;                         float e[8];
;                         __builtin_amdgcn_sched_barrier(0);
; #pragma unroll
;                         for (int j = 0; j < 4; ++j) { e[j] = ::fexp2(-LOG2E * v0[j]); e[4 + j] = ::fexp2(-LOG2E * v1[j]); }
;                         __builtin_amdgcn_sched_barrier(0);
; #pragma unroll
;                         for (int j = 0; j < 8; ++j) e[j] = ::frcp(1.f + e[j]);
;                         __builtin_amdgcn_sched_barrier(0);
; #pragma unroll
;                         for (int j = 0; j < 4; ++j) { v0[j] = e[j]; v1[j] = e[4 + j]; }
;                     } else { v0 = v0 * sc; v1 = v1 * sc; }
;                     u32x4 w; w.x = ::pk2(v0[0], v0[1]); w.y = ::pk2(v0[2], v0[3]); w.z = ::pk2(v1[0], v1[1]); w.w = ::pk2(v1[2], v1[3]);
;                     *(u32x4*)(rowp + bj * HALF) = w;
;                 }
.LBB0_299:
	v_cvt_f32_u32_e32 v46, v164
	v_cvt_pk_bf16_f32 v44, v36, v37
	v_cvt_pk_bf16_f32 v45, v38, v39
	v_cvt_pk_bf16_f32 v47, v42, v43
	v_mul_f32_e32 v36, 0x3a800000, v46
	v_fmamk_f32 v36, v36, 0x3a800000, v175
	v_rsq_f32_e32 v36, v36
	v_cvt_pk_bf16_f32 v46, v40, v41
	global_store_dwordx4 v[54:55], v[44:47], off offset:256 sc1
	s_and_b64 vcc, exec, s[42:43]
	v_pk_mul_f32 v[38:39], v[34:35], v[36:37] op_sel_hi:[1,0]
	v_pk_mul_f32 v[42:43], v[32:33], v[36:37] op_sel_hi:[1,0]
	v_pk_mul_f32 v[40:41], v[30:31], v[36:37] op_sel_hi:[1,0]
	v_pk_mul_f32 v[44:45], v[28:29], v[36:37] op_sel_hi:[1,0]
	s_mov_b64 s[76:77], -1
	s_cbranch_vccnz .LBB0_301
	v_mov_b32_e32 v32, v154
	v_mov_b32_e32 v33, v154
	v_pk_mul_f32 v[30:31], v[32:33], v[38:39]
	v_pk_mul_f32 v[28:29], v[154:155], v[42:43]
	v_pk_mul_f32 v[34:35], v[32:33], v[40:41]
	v_pk_mul_f32 v[32:33], v[154:155], v[44:45]
	s_mov_b64 s[76:77], 0

; __device__ __forceinline__ unsigned pk2(float lo, float hi) { f32x2 v = {lo, hi}; bf16x2_t b = __builtin_convertvector(v, bf16x2_t); return __builtin_bit_cast(unsigned, b); }
; __device__ __forceinline__ float fexp2(float x) { return __builtin_amdgcn_exp2f(x); }
; __device__ __forceinline__ float frcp(float x) { return __builtin_amdgcn_rcpf(x); }
;     __device__ __forceinline__ void operator()(const f32x4 (&acc)[2][2][4][2], const Unit& u, int wr, int wc, int fr, int fq) const {
;     ...
;         for (int ai = 0; ai < 2; ++ai)
; #pragma unroll
;             for (int m = 0; m < 4; ++m) {
;                 bf16_t* rowp = base + (size_t)(row0 + ai * HALF + m * 16) * ld + col0;
;                 const float rs = __builtin_amdgcn_rsqf(rsv[ai][m] * (1.f / 1024.f) + 1e-6f);
; #pragma unroll
;                 for (int bj = 0; bj < 2; ++bj) {
;                     f32x4 v0 = acc[ai][bj][m][0] * rs, v1 = acc[ai][bj][m][1] * rs;
;                     if (sig) {
;                         float e[8];
;                         __builtin_amdgcn_sched_barrier(0);
; #pragma unroll
;                         for (int j = 0; j < 4; ++j) { e[j] = ::fexp2(-LOG2E * v0[j]); e[4 + j] = ::fexp2(-LOG2E * v1[j]); }
;                         __builtin_amdgcn_sched_barrier(0);
; #pragma unroll
;                         for (int j = 0; j < 8; ++j) e[j] = ::frcp(1.f + e[j]);
;                         __builtin_amdgcn_sched_barrier(0);
; #pragma unroll
;                         for (int j = 0; j < 4; ++j) { v0[j] = e[j]; v1[j] = e[4 + j]; }
;                     } else { v0 = v0 * sc; v1 = v1 * sc; }
;                     u32x4 w; w.x = ::pk2(v0[0], v0[1]); w.y = ::pk2(v0[2], v0[3]); w.z = ::pk2(v1[0], v1[1]); w.w = ::pk2(v1[2], v1[3]);
;                     *(u32x4*)(rowp + bj * HALF) = w;
;                 }
.LBB0_303:
	v_add_u32_e32 v38, 0xa0, v156
	v_ashrrev_i32_e32 v39, 31, v38
	v_mul_lo_u32 v40, s74, v39
	v_mul_lo_u32 v41, s75, v38
	v_mad_u64_u32 v[38:39], s[64:65], s74, v38, 0
	v_add3_u32 v39, v39, v40, v41
	v_lshl_add_u64 v[38:39], v[38:39], 1, v[124:125]
	v_cvt_pk_bf16_f32 v28, v28, v29
	v_cvt_pk_bf16_f32 v29, v30, v31
	v_cvt_pk_bf16_f32 v30, v32, v33
	v_cvt_pk_bf16_f32 v31, v34, v35
	v_mov_b32_e32 v37, v36
	global_store_dwordx4 v[38:39], v[28:31], off sc1
	v_pk_mul_f32 v[32:33], v[24:25], v[36:37]
	v_pk_mul_f32 v[34:35], v[20:21], v[36:37]
	v_mov_b32_e32 v30, v36
	v_mov_b32_e32 v31, v36
	v_pk_mul_f32 v[28:29], v[26:27], v[30:31]
	v_pk_mul_f32 v[30:31], v[22:23], v[30:31]
	s_and_b64 vcc, exec, s[42:43]
	s_mov_b64 s[76:77], -1
	s_cbranch_vccnz .LBB0_305
	v_mov_b32_e32 v24, v154
	v_mov_b32_e32 v25, v154
	v_pk_mul_f32 v[22:23], v[24:25], v[28:29]
	v_pk_mul_f32 v[20:21], v[154:155], v[32:33]
	v_pk_mul_f32 v[26:27], v[24:25], v[30:31]
	v_pk_mul_f32 v[24:25], v[154:155], v[34:35]
	s_mov_b64 s[76:77], 0

; __device__ __forceinline__ unsigned pk2(float lo, float hi) { f32x2 v = {lo, hi}; bf16x2_t b = __builtin_convertvector(v, bf16x2_t); return __builtin_bit_cast(unsigned, b); }
; __device__ __forceinline__ float fexp2(float x) { return __builtin_amdgcn_exp2f(x); }
; __device__ __forceinline__ float frcp(float x) { return __builtin_amdgcn_rcpf(x); }
;     __device__ __forceinline__ void operator()(const f32x4 (&acc)[2][2][4][2], const Unit& u, int wr, int wc, int fr, int fq) const {
;     ...
;             for (int m = 0; m < 4; ++m) rsv[ai][m] = (float)RS[row0 + ai * HALF + m * 16] * (1.f / 1024.f);
; #pragma unroll
;         for (int ai = 0; ai < 2; ++ai)
; #pragma unroll
;             for (int m = 0; m < 4; ++m) {
;                 bf16_t* rowp = base + (size_t)(row0 + ai * HALF + m * 16) * ld + col0;
;                 const float rs = __builtin_amdgcn_rsqf(rsv[ai][m] * (1.f / 1024.f) + 1e-6f);
; #pragma unroll
;                 for (int bj = 0; bj < 2; ++bj) {
;                     f32x4 v0 = acc[ai][bj][m][0] * rs, v1 = acc[ai][bj][m][1] * rs;
;                     if (sig) {
;                         float e[8];
;                         __builtin_amdgcn_sched_barrier(0);
; #pragma unroll
;                         for (int j = 0; j < 4; ++j) { e[j] = ::fexp2(-LOG2E * v0[j]); e[4 + j] = ::fexp2(-LOG2E * v1[j]); }
;                         __builtin_amdgcn_sched_barrier(0);
; #pragma unroll
;                         for (int j = 0; j < 8; ++j) e[j] = ::frcp(1.f + e[j]);
;                         __builtin_amdgcn_sched_barrier(0);
; #pragma unroll
;                         for (int j = 0; j < 4; ++j) { v0[j] = e[j]; v1[j] = e[4 + j]; }
;                     } else { v0 = v0 * sc; v1 = v1 * sc; }
;                     u32x4 w; w.x = ::pk2(v0[0], v0[1]); w.y = ::pk2(v0[2], v0[3]); w.z = ::pk2(v1[0], v1[1]); w.w = ::pk2(v1[2], v1[3]);
;                     *(u32x4*)(rowp + bj * HALF) = w;
;                 }
.LBB0_307:
	v_cvt_f32_u32_e32 v30, v163
	v_cvt_pk_bf16_f32 v28, v20, v21
	v_cvt_pk_bf16_f32 v29, v22, v23
	v_cvt_pk_bf16_f32 v31, v26, v27
	v_mul_f32_e32 v20, 0x3a800000, v30
	v_fmamk_f32 v20, v20, 0x3a800000, v175
	v_rsq_f32_e32 v20, v20
	v_cvt_pk_bf16_f32 v30, v24, v25
	global_store_dwordx4 v[38:39], v[28:31], off offset:256 sc1
	s_and_b64 vcc, exec, s[42:43]
	v_pk_mul_f32 v[22:23], v[18:19], v[20:21] op_sel_hi:[1,0]
	v_pk_mul_f32 v[26:27], v[16:17], v[20:21] op_sel_hi:[1,0]
	v_pk_mul_f32 v[24:25], v[14:15], v[20:21] op_sel_hi:[1,0]
	v_pk_mul_f32 v[28:29], v[12:13], v[20:21] op_sel_hi:[1,0]
	s_mov_b64 s[76:77], -1
	s_cbranch_vccnz .LBB0_309
	v_mov_b32_e32 v16, v154
	v_mov_b32_e32 v17, v154
	v_pk_mul_f32 v[14:15], v[16:17], v[22:23]
	v_pk_mul_f32 v[12:13], v[154:155], v[26:27]
	v_pk_mul_f32 v[18:19], v[16:17], v[24:25]
	v_pk_mul_f32 v[16:17], v[154:155], v[28:29]
	s_mov_b64 s[76:77], 0

; __device__ __forceinline__ unsigned pk2(float lo, float hi) { f32x2 v = {lo, hi}; bf16x2_t b = __builtin_convertvector(v, bf16x2_t); return __builtin_bit_cast(unsigned, b); }
; __device__ __forceinline__ float fexp2(float x) { return __builtin_amdgcn_exp2f(x); }
; __device__ __forceinline__ float frcp(float x) { return __builtin_amdgcn_rcpf(x); }
;     __device__ __forceinline__ void operator()(const f32x4 (&acc)[2][2][4][2], const Unit& u, int wr, int wc, int fr, int fq) const {
;     ...
;         for (int ai = 0; ai < 2; ++ai)
; #pragma unroll
;             for (int m = 0; m < 4; ++m) {
;                 bf16_t* rowp = base + (size_t)(row0 + ai * HALF + m * 16) * ld + col0;
;                 const float rs = __builtin_amdgcn_rsqf(rsv[ai][m] * (1.f / 1024.f) + 1e-6f);
; #pragma unroll
;                 for (int bj = 0; bj < 2; ++bj) {
;                     f32x4 v0 = acc[ai][bj][m][0] * rs, v1 = acc[ai][bj][m][1] * rs;
;                     if (sig) {
;                         float e[8];
;                         __builtin_amdgcn_sched_barrier(0);
; #pragma unroll
;                         for (int j = 0; j < 4; ++j) { e[j] = ::fexp2(-LOG2E * v0[j]); e[4 + j] = ::fexp2(-LOG2E * v1[j]); }
;                         __builtin_amdgcn_sched_barrier(0);
; #pragma unroll
;                         for (int j = 0; j < 8; ++j) e[j] = ::frcp(1.f + e[j]);
;                         __builtin_amdgcn_sched_barrier(0);
; #pragma unroll
;                         for (int j = 0; j < 4; ++j) { v0[j] = e[j]; v1[j] = e[4 + j]; }
;                     } else { v0 = v0 * sc; v1 = v1 * sc; }
;                     u32x4 w; w.x = ::pk2(v0[0], v0[1]); w.y = ::pk2(v0[2], v0[3]); w.z = ::pk2(v1[0], v1[1]); w.w = ::pk2(v1[2], v1[3]);
;                     *(u32x4*)(rowp + bj * HALF) = w;
;                 }
.LBB0_311:
	v_add_u32_e32 v22, 0xb0, v156
	v_ashrrev_i32_e32 v23, 31, v22
	v_mul_lo_u32 v24, s74, v23
	v_mul_lo_u32 v25, s75, v22
	v_mad_u64_u32 v[22:23], s[64:65], s74, v22, 0
	v_add3_u32 v23, v23, v24, v25
	v_lshl_add_u64 v[22:23], v[22:23], 1, v[124:125]
	v_cvt_pk_bf16_f32 v12, v12, v13
	v_cvt_pk_bf16_f32 v13, v14, v15
	v_cvt_pk_bf16_f32 v14, v16, v17
	v_cvt_pk_bf16_f32 v15, v18, v19
	v_mov_b32_e32 v21, v20
	global_store_dwordx4 v[22:23], v[12:15], off sc1
	v_pk_mul_f32 v[16:17], v[8:9], v[20:21]
	v_pk_mul_f32 v[18:19], v[4:5], v[20:21]
	v_mov_b32_e32 v14, v20
	v_mov_b32_e32 v15, v20
	v_pk_mul_f32 v[12:13], v[10:11], v[14:15]
	v_pk_mul_f32 v[14:15], v[6:7], v[14:15]
	s_and_b64 vcc, exec, s[42:43]
	s_mov_b64 s[42:43], -1
	s_cbranch_vccnz .LBB0_313
	v_mov_b32_e32 v8, v154
	v_mov_b32_e32 v9, v154
	v_pk_mul_f32 v[6:7], v[8:9], v[12:13]
	v_pk_mul_f32 v[4:5], v[154:155], v[16:17]
	v_pk_mul_f32 v[10:11], v[8:9], v[14:15]
	v_pk_mul_f32 v[8:9], v[154:155], v[18:19]
	s_mov_b64 s[42:43], 0

; __device__ __forceinline__ unsigned pk2(float lo, float hi) { f32x2 v = {lo, hi}; bf16x2_t b = __builtin_convertvector(v, bf16x2_t); return __builtin_bit_cast(unsigned, b); }
; #define PG8_BAR __builtin_amdgcn_s_barrier()
;     __device__ __forceinline__ void operator()(const f32x4 (&acc)[2][2][4][2], const Unit& u, int wr, int wc, int fr, int fq) const {
;     ...
;                     u32x4 w; w.x = ::pk2(v0[0], v0[1]); w.y = ::pk2(v0[2], v0[3]); w.z = ::pk2(v1[0], v1[1]); w.w = ::pk2(v1[2], v1[3]);
;                     *(u32x4*)(rowp + bj * HALF) = w;
;                 }
; template <class Epi, class Sched, bool ALIGN_EPI = false, bool SP2 = false>
; __device__ __forceinline__ void gemm_phase(PG8_LAS unsigned char* lds, const Gemm g, const Sched& S, const Epi& E) {
;     ...
;         if (!has_next) break;
; #pragma unroll
;         for (int a = 0; a < 2; ++a)
; #pragma unroll
;             for (int b = 0; b < 2; ++b)
; #pragma unroll
;                 for (int m = 0; m < 4; ++m)
; #pragma unroll
;                     for (int n = 0; n < 2; ++n) acc[a][b][m][n] = (f32x4){0.f, 0.f, 0.f, 0.f};
;         cur = nxt; cA = nA; cB = nB; ++ui;
;         if constexpr (ALIGN_EPI) { if (wr == 1) PG8_BAR; }
.LBB0_315:
	v_cvt_pk_bf16_f32 v4, v4, v5
	v_cvt_pk_bf16_f32 v5, v6, v7
	v_cvt_pk_bf16_f32 v6, v8, v9
	v_cvt_pk_bf16_f32 v7, v10, v11
	s_andn2_b64 vcc, exec, s[40:41]
	s_mov_b64 s[40:41], -1
	global_store_dwordx4 v[22:23], v[4:7], off offset:256 sc1
	s_cbranch_vccnz .LBB0_232
	s_andn2_b64 vcc, exec, s[44:45]
	s_cbranch_vccnz .LBB0_231
	s_barrier
	s_branch .LBB0_231
